# IEEE f32 division expansions replaced by v_rcp_f32 (+mul) in gate/silu/ratio/softmax-normalisation paths
# speedup vs baseline: 1.0416x; 1.0292x over previous
; #define MFMA16(a, b, c) __builtin_amdgcn_mfma_f32_16x16x32_bf16((a), (b), (c), 0, 0, 0)
; DI void gemm_tile(const bf16_t* __restrict__ A, int lda, const bf16_t* __restrict__ Bt, int ldb, int bvalid, int K, f32x4 (&acc)[4][4], char* lds, bool preloaded = false) {
;     ...
;   const bf16_t* ap = A + (size_t)lr * lda + ((lc ^ ((lr >> 1) & 7)) << 3);
;   const bf16_t* bp = Bt + ((lc ^ ((lr >> 1) & 7)) << 3);
;   typedef __attribute__((address_space(1))) const unsigned gptr_t;
;   typedef __attribute__((address_space(3))) unsigned lptr_t;
;   const unsigned lbase = (unsigned)(size_t)lds + (unsigned)tid * 16u;
;     ...
;   auto compute = [&](int st) {
;     const char* base = lds + st * 32768;
;     bf16x8 af[2][4], bfr[2][4];
; #pragma unroll
;     for (int s = 0; s < 2; ++s) {
;       const int ch = ((4 * s + fq) ^ fx) << 4;
; #pragma unroll
;       for (int mi = 0; mi < 4; ++mi) af[s][mi] = *(const bf16x8*)(base + (wm * 64 + mi * 16 + fr) * 128 + ch);
; #pragma unroll
;       for (int ni = 0; ni < 4; ++ni) bfr[s][ni] = *(const bf16x8*)(base + 16384 + (wn * 64 + ni * 16 + fr) * 128 + ch);
;     }
;     __builtin_amdgcn_s_setprio(1);
; #pragma unroll
;     for (int s = 0; s < 2; ++s)
; #pragma unroll
;       for (int mi = 0; mi < 4; ++mi)
; #pragma unroll
;         for (int ni = 0; ni < 4; ++ni) acc[mi][ni] = MFMA16(af[s][mi], bfr[s][ni], acc[mi][ni]);
;     __builtin_amdgcn_s_setprio(0);
;   };
;   const int nk = K >> 6;
;   if (!preloaded) { GLDS(0, 0) }
;   __syncthreads();
; DI void phaseD_tile(const P& p, int layer, int mt, int nt, char* lds) {
;     ...
;   const size_t goff = ((size_t)((mt * 2 + wm) * 16 + nt * 2 + wn) * 64 + lane) * 16;
;   const unsigned* GP = (const unsigned*)(p.ws + W_GP) + goff;
;   const unsigned* GA = (const unsigned*)(p.ws + W_GA) + goff;
;   u32x4 gpv[4], gav[4];
; #pragma unroll
;   for (int mi = 0; mi < 4; ++mi) { gpv[mi] = __builtin_nontemporal_load((const u32x4*)(GP + mi * 4)); gav[mi] = __builtin_nontemporal_load((const u32x4*)(GA + mi * 4)); }
;   gemm_tile((const bf16_t*)(p.ws + W_POOLED) + (size_t)row0 * 512, 512, (const bf16_t*)(p.ws + W_WPO) + ((size_t)layer * 1024 + col0) * 512, 512, 128, 512, acc, lds);
.LBB0_277:
	v_mov_b32_e32 v99, v158
	v_mov_b32_e32 v2, v158
	s_lshl_b32 s8, s6, 1
	v_readfirstlane_b32 s5, v2
	s_ashr_i32 s19, s5, 7
	s_bfe_u32 s20, s5, 0x10006
	s_lshl_b32 s5, s7, 5
	s_lshl_b32 s4, s7, 7
	s_lshl_b32 s7, s19, 4
	s_add_i32 s5, s8, s5
	s_add_i32 s5, s5, s7
	s_or_b32 s8, s5, s20
	s_ashr_i32 s9, s8, 31
	v_and_b32_e32 v0, 63, v99
	s_lshl_b64 s[8:9], s[8:9], 12
	v_lshl_or_b32 v2, v0, 6, s8
	v_mov_b32_e32 v3, s9
	v_readlane_b32 s8, v240, 41
	v_readlane_b32 s9, v240, 42
	s_ashr_i32 s5, s4, 31
	s_lshl_b32 s6, s6, 7
	v_lshl_add_u64 v[6:7], s[8:9], 0, v[2:3]
	v_readlane_b32 s8, v240, 43
	v_readlane_b32 s9, v240, 44
	v_mov_b32_e32 v30, v158
	v_readlane_b32 s22, v240, 35
	v_lshl_add_u64 v[10:11], s[8:9], 0, v[2:3]
	s_lshl_b64 s[8:9], s[4:5], 10
	s_add_u32 s10, s74, s8
	s_addc_u32 s11, s75, s9
	s_ashr_i32 s7, s6, 31
	s_lshl_b64 s[12:13], s[6:7], 9
	s_add_u32 s12, s12, s94
	global_load_dwordx4 v[2:5], v[6:7], off offset:48 nt
	global_load_dwordx4 v[14:17], v[6:7], off offset:32 nt
	global_load_dwordx4 v[54:57], v[6:7], off offset:16 nt
	global_load_dwordx4 v[38:41], v[6:7], off nt
	s_nop 0
	global_load_dwordx4 v[6:9], v[10:11], off offset:48 nt
	global_load_dwordx4 v[18:21], v[10:11], off offset:32 nt
	global_load_dwordx4 v[58:61], v[10:11], off offset:16 nt
	global_load_dwordx4 v[46:49], v[10:11], off nt
	s_addc_u32 s13, s13, s95
	s_lshl_b64 s[12:13], s[12:13], 1
	v_ashrrev_i32_e32 v12, 3, v30
	v_lshrrev_b32_e32 v0, 4, v30
	v_ashrrev_i32_e32 v13, 31, v12
	v_xor_b32_e32 v0, v0, v30
	v_readlane_b32 s23, v240, 36
	s_add_u32 s22, s22, s12
	v_lshlrev_b64 v[10:11], 10, v[12:13]
	v_lshlrev_b32_e32 v0, 4, v0
	s_addc_u32 s23, s23, s13
	v_lshl_add_u64 v[10:11], s[10:11], 0, v[10:11]
	v_and_b32_e32 v0, 0x70, v0
	v_lshlrev_b32_e32 v35, 9, v12
	v_lshl_add_u64 v[10:11], v[10:11], 0, v[0:1]
	v_lshl_add_u64 v[26:27], s[22:23], 0, v[0:1]
	v_and_b32_e32 v0, 0xfe00, v35
	v_lshlrev_b32_e32 v34, 4, v30
	v_lshlrev_b32_e32 v0, 1, v0
	v_add_u32_e32 v22, 0x4000, v34
	v_readfirstlane_b32 s5, v34
	v_lshl_add_u64 v[12:13], v[26:27], 0, v[0:1]
	v_add_u32_e32 v0, 0x1000, v34
	s_mov_b32 m0, s5
	v_readfirstlane_b32 s10, v22
	v_readfirstlane_b32 s11, v0
	v_add_u32_e32 v0, 0x4000, v35
	global_load_lds_dwordx4 v[10:11], off
	s_mov_b32 m0, s10
	s_mov_b64 s[40:41], 0x8000
	v_and_b32_e32 v0, 0xfe00, v0
	global_load_lds_dwordx4 v[12:13], off
	v_lshl_add_u64 v[22:23], v[10:11], 0, s[40:41]
	s_mov_b32 m0, s11
	v_lshlrev_b32_e32 v0, 1, v0
	global_load_lds_dwordx4 v[22:23], off
	v_lshl_add_u64 v[22:23], v[26:27], 0, v[0:1]
	v_add_u32_e32 v0, 0x5000, v34
	s_mov_b32 s33, 0x8000
	v_readfirstlane_b32 s21, v0
	v_add_u32_e32 v0, 0x2000, v34
	s_mov_b32 m0, s21
	s_mov_b64 s[42:43], 0x10000
	v_readfirstlane_b32 s22, v0
	v_bitop3_b32 v0, v35, s33, v167 bitop3:0x6c
	global_load_lds_dwordx4 v[22:23], off
	v_lshl_add_u64 v[24:25], v[10:11], 0, s[42:43]
	s_mov_b32 m0, s22
	v_lshlrev_b32_e32 v0, 1, v0
	global_load_lds_dwordx4 v[24:25], off
	v_lshl_add_u64 v[24:25], v[26:27], 0, v[0:1]
	v_add_u32_e32 v0, 0x6000, v34
	v_readfirstlane_b32 s26, v30
	v_readfirstlane_b32 s23, v0
	v_add_u32_e32 v0, 0x3000, v34
	s_lshl_b32 s27, s26, 7
	v_readfirstlane_b32 s24, v0
	v_add_u32_e32 v0, 0xc000, v35
	v_and_b32_e32 v0, 0xfe00, v0
	v_lshlrev_b32_e32 v0, 1, v0
	v_lshl_add_u64 v[26:27], v[26:27], 0, v[0:1]
	v_add_u32_e32 v0, 0x7000, v34
	s_lshl_b32 s26, s26, 6
	v_readfirstlane_b32 s25, v0
	v_lshlrev_b32_e32 v0, 7, v30
	v_bfe_u32 v31, v30, 4, 2
	v_bfe_u32 v33, v30, 1, 3
	s_mov_b32 m0, s23
	s_mov_b64 s[50:51], 0x18000
	s_and_b32 s27, s27, 0x2000
	v_and_b32_e32 v0, 0x780, v0
	s_and_b32 s26, s26, 0xffffe000
	v_lshrrev_b32_e32 v32, 1, v30
	global_load_lds_dwordx4 v[24:25], off
	v_lshl_add_u64 v[28:29], v[10:11], 0, s[50:51]
	s_mov_b32 m0, s24
	v_or_b32_e32 v30, s27, v0
	v_or_b32_e32 v37, s26, v0
	v_bitop3_b32 v0, v31, v33, 4 bitop3:0x36
	global_load_lds_dwordx4 v[28:29], off
	v_bitop3_b32 v28, v32, v31, 7 bitop3:0x6c
	v_lshlrev_b32_e32 v31, 4, v0
	v_add_u32_e32 v0, 0x8000, v34
	s_mov_b32 m0, s25
	s_mov_b64 s[38:39], 0x80
	v_add_u32_e32 v32, 0xc000, v34
	v_readfirstlane_b32 s29, v0
	global_load_lds_dwordx4 v[26:27], off
	v_lshlrev_b32_e32 v36, 4, v28
	v_lshl_add_u64 v[28:29], v[10:11], 0, s[38:39]
	s_mov_b32 m0, s29
	v_readfirstlane_b32 s26, v32
	v_add_u32_e32 v0, 0x9000, v34
	s_waitcnt vmcnt(0) lgkmcnt(0)
	s_barrier
; #define MFMA16(a, b, c) __builtin_amdgcn_mfma_f32_16x16x32_bf16((a), (b), (c), 0, 0, 0)
; DI void gemm_tile(const bf16_t* __restrict__ A, int lda, const bf16_t* __restrict__ Bt, int ldb, int bvalid, int K, f32x4 (&acc)[4][4], char* lds, bool preloaded = false) {
;     ...
;   auto compute = [&](int st) {
;     const char* base = lds + st * 32768;
;     bf16x8 af[2][4], bfr[2][4];
; #pragma unroll
;     for (int s = 0; s < 2; ++s) {
;       const int ch = ((4 * s + fq) ^ fx) << 4;
; #pragma unroll
;       for (int mi = 0; mi < 4; ++mi) af[s][mi] = *(const bf16x8*)(base + (wm * 64 + mi * 16 + fr) * 128 + ch);
; #pragma unroll
;       for (int ni = 0; ni < 4; ++ni) bfr[s][ni] = *(const bf16x8*)(base + 16384 + (wn * 64 + ni * 16 + fr) * 128 + ch);
;     }
;     __builtin_amdgcn_s_setprio(1);
; #pragma unroll
;     for (int s = 0; s < 2; ++s)
; #pragma unroll
;       for (int mi = 0; mi < 4; ++mi)
; #pragma unroll
;         for (int ni = 0; ni < 4; ++ni) acc[mi][ni] = MFMA16(af[s][mi], bfr[s][ni], acc[mi][ni]);
;     __builtin_amdgcn_s_setprio(0);
;   };
;   const int nk = K >> 6;
;   if (!preloaded) { GLDS(0, 0) }
;   __syncthreads();
;   for (int kt = 0; kt < nk; ++kt) {
;     if (kt + 1 < nk) { GLDS((kt + 1) & 1, (kt + 1) << 6) }
;     compute(kt & 1);
;     __syncthreads();
;   }
	global_load_lds_dwordx4 v[28:29], off
	v_lshl_add_u64 v[28:29], v[12:13], 0, s[38:39]
	s_mov_b32 m0, s26
	s_mov_b64 s[58:59], 0x8080
	v_readfirstlane_b32 s27, v0
	v_add_u32_e32 v0, 0xd000, v34
	global_load_lds_dwordx4 v[28:29], off
	v_lshl_add_u64 v[28:29], v[10:11], 0, s[58:59]
	s_mov_b32 m0, s27
	v_readfirstlane_b32 s28, v0
	v_add_u32_e32 v0, 0xa000, v34
	global_load_lds_dwordx4 v[28:29], off
	v_lshl_add_u64 v[28:29], v[22:23], 0, s[38:39]
	s_mov_b32 m0, s28
	s_mov_b64 s[62:63], 0x10080
	v_readfirstlane_b32 s30, v0
	v_add_u32_e32 v0, 0xe000, v34
	global_load_lds_dwordx4 v[28:29], off
	v_lshl_add_u64 v[28:29], v[10:11], 0, s[62:63]
	s_mov_b32 m0, s30
	v_readfirstlane_b32 s31, v0
	v_add_u32_e32 v0, 0xb000, v34
	global_load_lds_dwordx4 v[28:29], off
	v_lshl_add_u64 v[28:29], v[24:25], 0, s[38:39]
	s_mov_b32 m0, s31
	s_mov_b64 s[68:69], 0x18080
	v_readfirstlane_b32 s34, v0
	v_add_u32_e32 v0, 0xf000, v34
	global_load_lds_dwordx4 v[28:29], off
	v_lshl_add_u64 v[28:29], v[10:11], 0, s[68:69]
	s_mov_b32 m0, s34
	v_readfirstlane_b32 s35, v0
	global_load_lds_dwordx4 v[28:29], off
	v_lshl_add_u64 v[28:29], v[26:27], 0, s[38:39]
	s_mov_b32 m0, s35
	v_or_b32_e32 v0, v36, v37
	global_load_lds_dwordx4 v[28:29], off
	v_or_b32_e32 v28, v36, v30
	v_or_b32_e32 v29, v31, v37
	v_or_b32_e32 v30, v31, v30
	ds_read_b128 v[32:35], v0
	ds_read_b128 v[42:45], v0 offset:2048
	ds_read_b128 v[50:53], v0 offset:4096
	ds_read_b128 v[62:65], v0 offset:6144
	ds_read_b128 v[66:69], v28 offset:16384
	ds_read_b128 v[70:73], v28 offset:18432
	ds_read_b128 v[74:77], v28 offset:20480
	ds_read_b128 v[78:81], v28 offset:22528
	ds_read_b128 v[82:85], v29
	ds_read_b128 v[86:89], v29 offset:2048
	ds_read_b128 v[90:93], v29 offset:4096
	ds_read_b128 v[94:97], v29 offset:6144
	ds_read_b128 v[100:103], v30 offset:16384
	ds_read_b128 v[104:107], v30 offset:18432
	ds_read_b128 v[108:111], v30 offset:20480
	ds_read_b128 v[112:115], v30 offset:22528
	v_and_b32_e32 v98, 15, v99
	s_setprio 1
	s_waitcnt lgkmcnt(0)
	v_mfma_f32_16x16x32_bf16 v[116:119], v[32:35], v[66:69], 0
	v_mfma_f32_16x16x32_bf16 v[120:123], v[32:35], v[70:73], 0
	v_mfma_f32_16x16x32_bf16 v[124:127], v[32:35], v[74:77], 0
	v_mfma_f32_16x16x32_bf16 v[32:35], v[32:35], v[78:81], 0
	v_mfma_f32_16x16x32_bf16 v[128:131], v[42:45], v[66:69], 0
	v_mfma_f32_16x16x32_bf16 v[132:135], v[42:45], v[70:73], 0
	v_mfma_f32_16x16x32_bf16 v[136:139], v[42:45], v[74:77], 0
	v_mfma_f32_16x16x32_bf16 v[42:45], v[42:45], v[78:81], 0
	v_mfma_f32_16x16x32_bf16 v[140:143], v[50:53], v[66:69], 0
	v_mfma_f32_16x16x32_bf16 v[144:147], v[50:53], v[70:73], 0
	v_mfma_f32_16x16x32_bf16 v[148:151], v[50:53], v[74:77], 0
	v_mfma_f32_16x16x32_bf16 v[50:53], v[50:53], v[78:81], 0
	v_mfma_f32_16x16x32_bf16 v[66:69], v[62:65], v[66:69], 0
	v_mfma_f32_16x16x32_bf16 v[70:73], v[62:65], v[70:73], 0
	v_mfma_f32_16x16x32_bf16 v[74:77], v[62:65], v[74:77], 0
	v_mfma_f32_16x16x32_bf16 v[62:65], v[62:65], v[78:81], 0
	v_mfma_f32_16x16x32_bf16 v[78:81], v[82:85], v[100:103], v[116:119]
	v_mfma_f32_16x16x32_bf16 v[116:119], v[82:85], v[104:107], v[120:123]
	v_mfma_f32_16x16x32_bf16 v[120:123], v[82:85], v[108:111], v[124:127]
	v_mfma_f32_16x16x32_bf16 v[32:35], v[82:85], v[112:115], v[32:35]
	v_mfma_f32_16x16x32_bf16 v[82:85], v[86:89], v[100:103], v[128:131]
	v_mfma_f32_16x16x32_bf16 v[124:127], v[86:89], v[104:107], v[132:135]
	v_mfma_f32_16x16x32_bf16 v[128:131], v[86:89], v[108:111], v[136:139]
	v_mfma_f32_16x16x32_bf16 v[42:45], v[86:89], v[112:115], v[42:45]
	v_mfma_f32_16x16x32_bf16 v[86:89], v[90:93], v[100:103], v[140:143]
	v_mfma_f32_16x16x32_bf16 v[132:135], v[90:93], v[104:107], v[144:147]
	v_mfma_f32_16x16x32_bf16 v[136:139], v[90:93], v[108:111], v[148:151]
	v_mfma_f32_16x16x32_bf16 v[50:53], v[90:93], v[112:115], v[50:53]
	v_mfma_f32_16x16x32_bf16 v[66:69], v[94:97], v[100:103], v[66:69]
	v_mfma_f32_16x16x32_bf16 v[70:73], v[94:97], v[104:107], v[70:73]
	v_mfma_f32_16x16x32_bf16 v[74:77], v[94:97], v[108:111], v[74:77]
	v_mfma_f32_16x16x32_bf16 v[62:65], v[94:97], v[112:115], v[62:65]
	s_setprio 0
	s_mov_b64 s[36:37], 0x100
	s_mov_b32 m0, s5
	v_lshl_add_u64 v[36:37], v[10:11], 0, s[36:37]
	s_waitcnt vmcnt(0)
	s_barrier
	global_load_lds_dwordx4 v[36:37], off
	v_lshl_add_u64 v[36:37], v[12:13], 0, s[36:37]
	s_mov_b32 m0, s10
	s_mov_b64 s[70:71], 0x8100
	global_load_lds_dwordx4 v[36:37], off
	v_lshl_add_u64 v[36:37], v[10:11], 0, s[70:71]
	s_mov_b32 m0, s11
	s_mov_b64 s[92:93], 0x10100
	global_load_lds_dwordx4 v[36:37], off
	v_lshl_add_u64 v[36:37], v[22:23], 0, s[36:37]
	s_mov_b32 m0, s21
	s_mov_b64 s[0:1], 0x18100
	global_load_lds_dwordx4 v[36:37], off
	v_lshl_add_u64 v[36:37], v[10:11], 0, s[92:93]
	s_mov_b32 m0, s22
	s_nop 0
	global_load_lds_dwordx4 v[36:37], off
	v_lshl_add_u64 v[36:37], v[24:25], 0, s[36:37]
	s_mov_b32 m0, s23
	s_nop 0
	global_load_lds_dwordx4 v[36:37], off
	v_lshl_add_u64 v[36:37], v[10:11], 0, s[0:1]
	s_mov_b32 m0, s24
	s_nop 0
	global_load_lds_dwordx4 v[36:37], off
	v_lshl_add_u64 v[36:37], v[26:27], 0, s[36:37]
	s_mov_b32 m0, s25
	s_nop 0
	global_load_lds_dwordx4 v[36:37], off
	ds_read_b128 v[90:93], v0 offset:32768
	ds_read_b128 v[94:97], v0 offset:34816
	ds_read_b128 v[100:103], v0 offset:36864
	ds_read_b128 v[104:107], v0 offset:38912
	ds_read_b128 v[108:111], v28 offset:49152
	ds_read_b128 v[112:115], v28 offset:51200
	ds_read_b128 v[140:143], v28 offset:53248
	ds_read_b128 v[144:147], v28 offset:55296
	ds_read_b128 v[148:151], v29 offset:32768
	ds_read_b128 v[152:155], v29 offset:34816
	ds_read_b128 v[180:183], v29 offset:36864
	ds_read_b128 v[184:187], v29 offset:38912
	ds_read_b128 v[188:191], v30 offset:49152
	ds_read_b128 v[192:195], v30 offset:51200
	ds_read_b128 v[196:199], v30 offset:53248
	ds_read_b128 v[200:203], v30 offset:55296
	s_setprio 1
	s_waitcnt lgkmcnt(0)
; #define MFMA16(a, b, c) __builtin_amdgcn_mfma_f32_16x16x32_bf16((a), (b), (c), 0, 0, 0)
; DI void gemm_tile(const bf16_t* __restrict__ A, int lda, const bf16_t* __restrict__ Bt, int ldb, int bvalid, int K, f32x4 (&acc)[4][4], char* lds, bool preloaded = false) {
;     ...
;   auto compute = [&](int st) {
;     const char* base = lds + st * 32768;
;     bf16x8 af[2][4], bfr[2][4];
; #pragma unroll
;     for (int s = 0; s < 2; ++s) {
;       const int ch = ((4 * s + fq) ^ fx) << 4;
; #pragma unroll
;       for (int mi = 0; mi < 4; ++mi) af[s][mi] = *(const bf16x8*)(base + (wm * 64 + mi * 16 + fr) * 128 + ch);
; #pragma unroll
;       for (int ni = 0; ni < 4; ++ni) bfr[s][ni] = *(const bf16x8*)(base + 16384 + (wn * 64 + ni * 16 + fr) * 128 + ch);
;     }
;     __builtin_amdgcn_s_setprio(1);
; #pragma unroll
;     for (int s = 0; s < 2; ++s)
; #pragma unroll
;       for (int mi = 0; mi < 4; ++mi)
; #pragma unroll
;         for (int ni = 0; ni < 4; ++ni) acc[mi][ni] = MFMA16(af[s][mi], bfr[s][ni], acc[mi][ni]);
;     __builtin_amdgcn_s_setprio(0);
;   };
;   const int nk = K >> 6;
;   if (!preloaded) { GLDS(0, 0) }
;   __syncthreads();
;   for (int kt = 0; kt < nk; ++kt) {
;     if (kt + 1 < nk) { GLDS((kt + 1) & 1, (kt + 1) << 6) }
;     compute(kt & 1);
;     __syncthreads();
;   }
	v_mfma_f32_16x16x32_bf16 v[78:81], v[90:93], v[108:111], v[78:81]
	v_mfma_f32_16x16x32_bf16 v[116:119], v[90:93], v[112:115], v[116:119]
	v_mfma_f32_16x16x32_bf16 v[120:123], v[90:93], v[140:143], v[120:123]
	v_mfma_f32_16x16x32_bf16 v[32:35], v[90:93], v[144:147], v[32:35]
	v_mfma_f32_16x16x32_bf16 v[82:85], v[94:97], v[108:111], v[82:85]
	v_mfma_f32_16x16x32_bf16 v[90:93], v[94:97], v[112:115], v[124:127]
	v_mfma_f32_16x16x32_bf16 v[124:127], v[94:97], v[140:143], v[128:131]
	v_mfma_f32_16x16x32_bf16 v[42:45], v[94:97], v[144:147], v[42:45]
	v_mfma_f32_16x16x32_bf16 v[86:89], v[100:103], v[108:111], v[86:89]
	v_mfma_f32_16x16x32_bf16 v[94:97], v[100:103], v[112:115], v[132:135]
	v_mfma_f32_16x16x32_bf16 v[128:131], v[100:103], v[140:143], v[136:139]
	v_mfma_f32_16x16x32_bf16 v[50:53], v[100:103], v[144:147], v[50:53]
	v_mfma_f32_16x16x32_bf16 v[66:69], v[104:107], v[108:111], v[66:69]
	v_mfma_f32_16x16x32_bf16 v[70:73], v[104:107], v[112:115], v[70:73]
	v_mfma_f32_16x16x32_bf16 v[74:77], v[104:107], v[140:143], v[74:77]
	v_mfma_f32_16x16x32_bf16 v[62:65], v[104:107], v[144:147], v[62:65]
	v_mfma_f32_16x16x32_bf16 v[78:81], v[148:151], v[188:191], v[78:81]
	v_mfma_f32_16x16x32_bf16 v[100:103], v[148:151], v[192:195], v[116:119]
	v_mfma_f32_16x16x32_bf16 v[104:107], v[148:151], v[196:199], v[120:123]
	v_mfma_f32_16x16x32_bf16 v[32:35], v[148:151], v[200:203], v[32:35]
	v_mfma_f32_16x16x32_bf16 v[82:85], v[152:155], v[188:191], v[82:85]
	v_mfma_f32_16x16x32_bf16 v[90:93], v[152:155], v[192:195], v[90:93]
	v_mfma_f32_16x16x32_bf16 v[108:111], v[152:155], v[196:199], v[124:127]
	v_mfma_f32_16x16x32_bf16 v[42:45], v[152:155], v[200:203], v[42:45]
	v_mfma_f32_16x16x32_bf16 v[86:89], v[180:183], v[188:191], v[86:89]
	v_mfma_f32_16x16x32_bf16 v[94:97], v[180:183], v[192:195], v[94:97]
	v_mfma_f32_16x16x32_bf16 v[112:115], v[180:183], v[196:199], v[128:131]
	v_mfma_f32_16x16x32_bf16 v[50:53], v[180:183], v[200:203], v[50:53]
	v_mfma_f32_16x16x32_bf16 v[66:69], v[184:187], v[188:191], v[66:69]
	v_mfma_f32_16x16x32_bf16 v[70:73], v[184:187], v[192:195], v[70:73]
	v_mfma_f32_16x16x32_bf16 v[74:77], v[184:187], v[196:199], v[74:77]
	v_mfma_f32_16x16x32_bf16 v[62:65], v[184:187], v[200:203], v[62:65]
	s_setprio 0
	s_mov_b64 s[0:1], 0x180
	s_mov_b32 m0, s29
	v_lshl_add_u64 v[36:37], v[10:11], 0, s[0:1]
	s_waitcnt vmcnt(0)
	s_barrier
	global_load_lds_dwordx4 v[36:37], off
	v_lshl_add_u64 v[36:37], v[12:13], 0, s[0:1]
	s_mov_b32 m0, s26
	s_mov_b64 s[2:3], 0x8180
	global_load_lds_dwordx4 v[36:37], off
	v_lshl_add_u64 v[36:37], v[10:11], 0, s[2:3]
	s_mov_b32 m0, s27
	s_mov_b64 s[2:3], 0x10180
	global_load_lds_dwordx4 v[36:37], off
	v_lshl_add_u64 v[36:37], v[22:23], 0, s[0:1]
	s_mov_b32 m0, s28
	s_nop 0
	global_load_lds_dwordx4 v[36:37], off
	v_lshl_add_u64 v[36:37], v[10:11], 0, s[2:3]
	s_mov_b32 m0, s30
	s_mov_b64 s[2:3], 0x18180
	global_load_lds_dwordx4 v[36:37], off
	v_lshl_add_u64 v[36:37], v[24:25], 0, s[0:1]
	s_mov_b32 m0, s31
	s_nop 0
	global_load_lds_dwordx4 v[36:37], off
	v_lshl_add_u64 v[36:37], v[10:11], 0, s[2:3]
	s_mov_b32 m0, s34
	s_nop 0
	global_load_lds_dwordx4 v[36:37], off
	v_lshl_add_u64 v[36:37], v[26:27], 0, s[0:1]
	s_mov_b32 m0, s35
	s_nop 0
	global_load_lds_dwordx4 v[36:37], off
	ds_read_b128 v[116:119], v0
	ds_read_b128 v[120:123], v0 offset:2048
	ds_read_b128 v[124:127], v0 offset:4096
	ds_read_b128 v[128:131], v0 offset:6144
	ds_read_b128 v[132:135], v28 offset:16384
	ds_read_b128 v[136:139], v28 offset:18432
	ds_read_b128 v[140:143], v28 offset:20480
	ds_read_b128 v[144:147], v28 offset:22528
	ds_read_b128 v[148:151], v29
	ds_read_b128 v[152:155], v29 offset:2048
	ds_read_b128 v[180:183], v29 offset:4096
	ds_read_b128 v[184:187], v29 offset:6144
	ds_read_b128 v[188:191], v30 offset:16384
	ds_read_b128 v[192:195], v30 offset:18432
	ds_read_b128 v[196:199], v30 offset:20480
	ds_read_b128 v[200:203], v30 offset:22528
	s_setprio 1
	s_waitcnt lgkmcnt(0)
	v_mfma_f32_16x16x32_bf16 v[78:81], v[116:119], v[132:135], v[78:81]
	v_mfma_f32_16x16x32_bf16 v[100:103], v[116:119], v[136:139], v[100:103]
	v_mfma_f32_16x16x32_bf16 v[104:107], v[116:119], v[140:143], v[104:107]
	v_mfma_f32_16x16x32_bf16 v[32:35], v[116:119], v[144:147], v[32:35]
	v_mfma_f32_16x16x32_bf16 v[82:85], v[120:123], v[132:135], v[82:85]
	v_mfma_f32_16x16x32_bf16 v[90:93], v[120:123], v[136:139], v[90:93]
	v_mfma_f32_16x16x32_bf16 v[108:111], v[120:123], v[140:143], v[108:111]
	v_mfma_f32_16x16x32_bf16 v[42:45], v[120:123], v[144:147], v[42:45]
	v_mfma_f32_16x16x32_bf16 v[86:89], v[124:127], v[132:135], v[86:89]
	v_mfma_f32_16x16x32_bf16 v[94:97], v[124:127], v[136:139], v[94:97]
	v_mfma_f32_16x16x32_bf16 v[112:115], v[124:127], v[140:143], v[112:115]
	v_mfma_f32_16x16x32_bf16 v[50:53], v[124:127], v[144:147], v[50:53]
	v_mfma_f32_16x16x32_bf16 v[66:69], v[128:131], v[132:135], v[66:69]
	v_mfma_f32_16x16x32_bf16 v[70:73], v[128:131], v[136:139], v[70:73]
	v_mfma_f32_16x16x32_bf16 v[74:77], v[128:131], v[140:143], v[74:77]
	v_mfma_f32_16x16x32_bf16 v[62:65], v[128:131], v[144:147], v[62:65]
	v_mfma_f32_16x16x32_bf16 v[78:81], v[148:151], v[188:191], v[78:81]
	v_mfma_f32_16x16x32_bf16 v[100:103], v[148:151], v[192:195], v[100:103]
	v_mfma_f32_16x16x32_bf16 v[104:107], v[148:151], v[196:199], v[104:107]
	v_mfma_f32_16x16x32_bf16 v[32:35], v[148:151], v[200:203], v[32:35]
	v_mfma_f32_16x16x32_bf16 v[82:85], v[152:155], v[188:191], v[82:85]
	v_mfma_f32_16x16x32_bf16 v[90:93], v[152:155], v[192:195], v[90:93]
	v_mfma_f32_16x16x32_bf16 v[108:111], v[152:155], v[196:199], v[108:111]
	v_mfma_f32_16x16x32_bf16 v[42:45], v[152:155], v[200:203], v[42:45]
	v_mfma_f32_16x16x32_bf16 v[86:89], v[180:183], v[188:191], v[86:89]
	v_mfma_f32_16x16x32_bf16 v[94:97], v[180:183], v[192:195], v[94:97]
	v_mfma_f32_16x16x32_bf16 v[112:115], v[180:183], v[196:199], v[112:115]
	v_mfma_f32_16x16x32_bf16 v[50:53], v[180:183], v[200:203], v[50:53]
	v_mfma_f32_16x16x32_bf16 v[66:69], v[184:187], v[188:191], v[66:69]
	v_mfma_f32_16x16x32_bf16 v[70:73], v[184:187], v[192:195], v[70:73]
	v_mfma_f32_16x16x32_bf16 v[74:77], v[184:187], v[196:199], v[74:77]
	v_mfma_f32_16x16x32_bf16 v[62:65], v[184:187], v[200:203], v[62:65]
	s_setprio 0
	s_mov_b64 s[36:37], 0x200
	s_mov_b32 m0, s5
	v_lshl_add_u64 v[36:37], v[10:11], 0, s[36:37]
	s_waitcnt vmcnt(0)
	s_barrier
; #define MFMA16(a, b, c) __builtin_amdgcn_mfma_f32_16x16x32_bf16((a), (b), (c), 0, 0, 0)
; DI void gemm_tile(const bf16_t* __restrict__ A, int lda, const bf16_t* __restrict__ Bt, int ldb, int bvalid, int K, f32x4 (&acc)[4][4], char* lds, bool preloaded = false) {
;     ...
;   auto compute = [&](int st) {
;     const char* base = lds + st * 32768;
;     bf16x8 af[2][4], bfr[2][4];
; #pragma unroll
;     for (int s = 0; s < 2; ++s) {
;       const int ch = ((4 * s + fq) ^ fx) << 4;
; #pragma unroll
;       for (int mi = 0; mi < 4; ++mi) af[s][mi] = *(const bf16x8*)(base + (wm * 64 + mi * 16 + fr) * 128 + ch);
; #pragma unroll
;       for (int ni = 0; ni < 4; ++ni) bfr[s][ni] = *(const bf16x8*)(base + 16384 + (wn * 64 + ni * 16 + fr) * 128 + ch);
;     }
;     __builtin_amdgcn_s_setprio(1);
; #pragma unroll
;     for (int s = 0; s < 2; ++s)
; #pragma unroll
;       for (int mi = 0; mi < 4; ++mi)
; #pragma unroll
;         for (int ni = 0; ni < 4; ++ni) acc[mi][ni] = MFMA16(af[s][mi], bfr[s][ni], acc[mi][ni]);
;     __builtin_amdgcn_s_setprio(0);
;   };
;   const int nk = K >> 6;
;   if (!preloaded) { GLDS(0, 0) }
;   __syncthreads();
;   for (int kt = 0; kt < nk; ++kt) {
;     if (kt + 1 < nk) { GLDS((kt + 1) & 1, (kt + 1) << 6) }
;     compute(kt & 1);
;     __syncthreads();
;   }
	global_load_lds_dwordx4 v[36:37], off
	v_lshl_add_u64 v[36:37], v[12:13], 0, s[36:37]
	s_mov_b32 m0, s10
	s_mov_b64 s[2:3], 0x8200
	global_load_lds_dwordx4 v[36:37], off
	v_lshl_add_u64 v[36:37], v[10:11], 0, s[2:3]
	s_mov_b32 m0, s11
	s_mov_b64 s[2:3], 0x10200
	global_load_lds_dwordx4 v[36:37], off
	v_lshl_add_u64 v[36:37], v[22:23], 0, s[36:37]
	s_mov_b32 m0, s21
	s_nop 0
	global_load_lds_dwordx4 v[36:37], off
	v_lshl_add_u64 v[36:37], v[10:11], 0, s[2:3]
	s_mov_b32 m0, s22
	s_mov_b64 s[2:3], 0x18200
	global_load_lds_dwordx4 v[36:37], off
	v_lshl_add_u64 v[36:37], v[24:25], 0, s[36:37]
	s_mov_b32 m0, s23
	s_nop 0
	global_load_lds_dwordx4 v[36:37], off
	v_lshl_add_u64 v[36:37], v[10:11], 0, s[2:3]
	s_mov_b32 m0, s24
	s_nop 0
	global_load_lds_dwordx4 v[36:37], off
	v_lshl_add_u64 v[36:37], v[26:27], 0, s[36:37]
	s_mov_b32 m0, s25
	s_nop 0
	global_load_lds_dwordx4 v[36:37], off
	ds_read_b128 v[116:119], v0 offset:32768
	ds_read_b128 v[120:123], v0 offset:34816
	ds_read_b128 v[124:127], v0 offset:36864
	ds_read_b128 v[128:131], v0 offset:38912
	ds_read_b128 v[132:135], v28 offset:49152
	ds_read_b128 v[136:139], v28 offset:51200
	ds_read_b128 v[140:143], v28 offset:53248
	ds_read_b128 v[144:147], v28 offset:55296
	ds_read_b128 v[148:151], v29 offset:32768
	ds_read_b128 v[152:155], v29 offset:34816
	ds_read_b128 v[180:183], v29 offset:36864
	ds_read_b128 v[184:187], v29 offset:38912
	ds_read_b128 v[188:191], v30 offset:49152
	ds_read_b128 v[192:195], v30 offset:51200
	ds_read_b128 v[196:199], v30 offset:53248
	ds_read_b128 v[200:203], v30 offset:55296
	s_setprio 1
	s_waitcnt lgkmcnt(0)
	v_mfma_f32_16x16x32_bf16 v[78:81], v[116:119], v[132:135], v[78:81]
	v_mfma_f32_16x16x32_bf16 v[100:103], v[116:119], v[136:139], v[100:103]
	v_mfma_f32_16x16x32_bf16 v[104:107], v[116:119], v[140:143], v[104:107]
	v_mfma_f32_16x16x32_bf16 v[32:35], v[116:119], v[144:147], v[32:35]
	v_mfma_f32_16x16x32_bf16 v[82:85], v[120:123], v[132:135], v[82:85]
	v_mfma_f32_16x16x32_bf16 v[90:93], v[120:123], v[136:139], v[90:93]
	v_mfma_f32_16x16x32_bf16 v[108:111], v[120:123], v[140:143], v[108:111]
	v_mfma_f32_16x16x32_bf16 v[42:45], v[120:123], v[144:147], v[42:45]
	v_mfma_f32_16x16x32_bf16 v[86:89], v[124:127], v[132:135], v[86:89]
	v_mfma_f32_16x16x32_bf16 v[94:97], v[124:127], v[136:139], v[94:97]
	v_mfma_f32_16x16x32_bf16 v[112:115], v[124:127], v[140:143], v[112:115]
	v_mfma_f32_16x16x32_bf16 v[50:53], v[124:127], v[144:147], v[50:53]
	v_mfma_f32_16x16x32_bf16 v[66:69], v[128:131], v[132:135], v[66:69]
	v_mfma_f32_16x16x32_bf16 v[70:73], v[128:131], v[136:139], v[70:73]
	v_mfma_f32_16x16x32_bf16 v[74:77], v[128:131], v[140:143], v[74:77]
	v_mfma_f32_16x16x32_bf16 v[62:65], v[128:131], v[144:147], v[62:65]
	v_mfma_f32_16x16x32_bf16 v[78:81], v[148:151], v[188:191], v[78:81]
	v_mfma_f32_16x16x32_bf16 v[100:103], v[148:151], v[192:195], v[100:103]
	v_mfma_f32_16x16x32_bf16 v[104:107], v[148:151], v[196:199], v[104:107]
	v_mfma_f32_16x16x32_bf16 v[32:35], v[148:151], v[200:203], v[32:35]
	v_mfma_f32_16x16x32_bf16 v[82:85], v[152:155], v[188:191], v[82:85]
	v_mfma_f32_16x16x32_bf16 v[90:93], v[152:155], v[192:195], v[90:93]
	v_mfma_f32_16x16x32_bf16 v[108:111], v[152:155], v[196:199], v[108:111]
	v_mfma_f32_16x16x32_bf16 v[42:45], v[152:155], v[200:203], v[42:45]
	v_mfma_f32_16x16x32_bf16 v[86:89], v[180:183], v[188:191], v[86:89]
	v_mfma_f32_16x16x32_bf16 v[94:97], v[180:183], v[192:195], v[94:97]
	v_mfma_f32_16x16x32_bf16 v[112:115], v[180:183], v[196:199], v[112:115]
	v_mfma_f32_16x16x32_bf16 v[50:53], v[180:183], v[200:203], v[50:53]
	v_mfma_f32_16x16x32_bf16 v[66:69], v[184:187], v[188:191], v[66:69]
	v_mfma_f32_16x16x32_bf16 v[70:73], v[184:187], v[192:195], v[70:73]
	v_mfma_f32_16x16x32_bf16 v[74:77], v[184:187], v[196:199], v[74:77]
	v_mfma_f32_16x16x32_bf16 v[62:65], v[184:187], v[200:203], v[62:65]
	s_setprio 0
	s_mov_b64 s[2:3], 0x280
	s_mov_b32 m0, s29
	v_lshl_add_u64 v[36:37], v[10:11], 0, s[2:3]
	s_waitcnt vmcnt(0)
	s_barrier
	global_load_lds_dwordx4 v[36:37], off
	v_lshl_add_u64 v[36:37], v[12:13], 0, s[2:3]
	s_mov_b32 m0, s26
	s_mov_b64 s[14:15], 0x8280
	global_load_lds_dwordx4 v[36:37], off
	v_lshl_add_u64 v[36:37], v[10:11], 0, s[14:15]
	s_mov_b32 m0, s27
	s_mov_b64 s[14:15], 0x10280
	global_load_lds_dwordx4 v[36:37], off
	v_lshl_add_u64 v[36:37], v[22:23], 0, s[2:3]
	s_mov_b32 m0, s28
	s_nop 0
	global_load_lds_dwordx4 v[36:37], off
	v_lshl_add_u64 v[36:37], v[10:11], 0, s[14:15]
	s_mov_b32 m0, s30
	s_mov_b64 s[14:15], 0x18280
	global_load_lds_dwordx4 v[36:37], off
	v_lshl_add_u64 v[36:37], v[24:25], 0, s[2:3]
	s_mov_b32 m0, s31
	s_nop 0
	global_load_lds_dwordx4 v[36:37], off
	v_lshl_add_u64 v[36:37], v[10:11], 0, s[14:15]
	s_mov_b32 m0, s34
	s_nop 0
	global_load_lds_dwordx4 v[36:37], off
	v_lshl_add_u64 v[36:37], v[26:27], 0, s[2:3]
	s_mov_b32 m0, s35
	s_nop 0
	global_load_lds_dwordx4 v[36:37], off
	ds_read_b128 v[116:119], v0
	ds_read_b128 v[120:123], v0 offset:2048
	ds_read_b128 v[124:127], v0 offset:4096
	ds_read_b128 v[128:131], v0 offset:6144
	ds_read_b128 v[132:135], v28 offset:16384
	ds_read_b128 v[136:139], v28 offset:18432
	ds_read_b128 v[140:143], v28 offset:20480
	ds_read_b128 v[144:147], v28 offset:22528
	ds_read_b128 v[148:151], v29
	ds_read_b128 v[152:155], v29 offset:2048
	ds_read_b128 v[180:183], v29 offset:4096
	ds_read_b128 v[184:187], v29 offset:6144
	ds_read_b128 v[188:191], v30 offset:16384
	ds_read_b128 v[192:195], v30 offset:18432
	ds_read_b128 v[196:199], v30 offset:20480
	ds_read_b128 v[200:203], v30 offset:22528
	s_setprio 1
	s_waitcnt lgkmcnt(0)
; #define MFMA16(a, b, c) __builtin_amdgcn_mfma_f32_16x16x32_bf16((a), (b), (c), 0, 0, 0)
; DI void gemm_tile(const bf16_t* __restrict__ A, int lda, const bf16_t* __restrict__ Bt, int ldb, int bvalid, int K, f32x4 (&acc)[4][4], char* lds, bool preloaded = false) {
;     ...
;   auto compute = [&](int st) {
;     const char* base = lds + st * 32768;
;     bf16x8 af[2][4], bfr[2][4];
; #pragma unroll
;     for (int s = 0; s < 2; ++s) {
;       const int ch = ((4 * s + fq) ^ fx) << 4;
; #pragma unroll
;       for (int mi = 0; mi < 4; ++mi) af[s][mi] = *(const bf16x8*)(base + (wm * 64 + mi * 16 + fr) * 128 + ch);
; #pragma unroll
;       for (int ni = 0; ni < 4; ++ni) bfr[s][ni] = *(const bf16x8*)(base + 16384 + (wn * 64 + ni * 16 + fr) * 128 + ch);
;     }
;     __builtin_amdgcn_s_setprio(1);
; #pragma unroll
;     for (int s = 0; s < 2; ++s)
; #pragma unroll
;       for (int mi = 0; mi < 4; ++mi)
; #pragma unroll
;         for (int ni = 0; ni < 4; ++ni) acc[mi][ni] = MFMA16(af[s][mi], bfr[s][ni], acc[mi][ni]);
;     __builtin_amdgcn_s_setprio(0);
;   };
;   const int nk = K >> 6;
;   if (!preloaded) { GLDS(0, 0) }
;   __syncthreads();
;   for (int kt = 0; kt < nk; ++kt) {
;     if (kt + 1 < nk) { GLDS((kt + 1) & 1, (kt + 1) << 6) }
;     compute(kt & 1);
;     __syncthreads();
;   }
	v_mfma_f32_16x16x32_bf16 v[78:81], v[116:119], v[132:135], v[78:81]
	v_mfma_f32_16x16x32_bf16 v[100:103], v[116:119], v[136:139], v[100:103]
	v_mfma_f32_16x16x32_bf16 v[104:107], v[116:119], v[140:143], v[104:107]
	v_mfma_f32_16x16x32_bf16 v[32:35], v[116:119], v[144:147], v[32:35]
	v_mfma_f32_16x16x32_bf16 v[82:85], v[120:123], v[132:135], v[82:85]
	v_mfma_f32_16x16x32_bf16 v[90:93], v[120:123], v[136:139], v[90:93]
	v_mfma_f32_16x16x32_bf16 v[108:111], v[120:123], v[140:143], v[108:111]
	v_mfma_f32_16x16x32_bf16 v[42:45], v[120:123], v[144:147], v[42:45]
	v_mfma_f32_16x16x32_bf16 v[86:89], v[124:127], v[132:135], v[86:89]
	v_mfma_f32_16x16x32_bf16 v[94:97], v[124:127], v[136:139], v[94:97]
	v_mfma_f32_16x16x32_bf16 v[112:115], v[124:127], v[140:143], v[112:115]
	v_mfma_f32_16x16x32_bf16 v[50:53], v[124:127], v[144:147], v[50:53]
	v_mfma_f32_16x16x32_bf16 v[66:69], v[128:131], v[132:135], v[66:69]
	v_mfma_f32_16x16x32_bf16 v[70:73], v[128:131], v[136:139], v[70:73]
	v_mfma_f32_16x16x32_bf16 v[74:77], v[128:131], v[140:143], v[74:77]
	v_mfma_f32_16x16x32_bf16 v[62:65], v[128:131], v[144:147], v[62:65]
	v_mfma_f32_16x16x32_bf16 v[78:81], v[148:151], v[188:191], v[78:81]
	v_mfma_f32_16x16x32_bf16 v[100:103], v[148:151], v[192:195], v[100:103]
	v_mfma_f32_16x16x32_bf16 v[104:107], v[148:151], v[196:199], v[104:107]
	v_mfma_f32_16x16x32_bf16 v[32:35], v[148:151], v[200:203], v[32:35]
	v_mfma_f32_16x16x32_bf16 v[82:85], v[152:155], v[188:191], v[82:85]
	v_mfma_f32_16x16x32_bf16 v[90:93], v[152:155], v[192:195], v[90:93]
	v_mfma_f32_16x16x32_bf16 v[108:111], v[152:155], v[196:199], v[108:111]
	v_mfma_f32_16x16x32_bf16 v[42:45], v[152:155], v[200:203], v[42:45]
	v_mfma_f32_16x16x32_bf16 v[86:89], v[180:183], v[188:191], v[86:89]
	v_mfma_f32_16x16x32_bf16 v[94:97], v[180:183], v[192:195], v[94:97]
	v_mfma_f32_16x16x32_bf16 v[112:115], v[180:183], v[196:199], v[112:115]
	v_mfma_f32_16x16x32_bf16 v[50:53], v[180:183], v[200:203], v[50:53]
	v_mfma_f32_16x16x32_bf16 v[66:69], v[184:187], v[188:191], v[66:69]
	v_mfma_f32_16x16x32_bf16 v[70:73], v[184:187], v[192:195], v[70:73]
	v_mfma_f32_16x16x32_bf16 v[74:77], v[184:187], v[196:199], v[74:77]
	v_mfma_f32_16x16x32_bf16 v[62:65], v[184:187], v[200:203], v[62:65]
	s_setprio 0
	s_mov_b64 s[14:15], 0x300
	s_mov_b32 m0, s5
	v_lshl_add_u64 v[36:37], v[10:11], 0, s[14:15]
	s_waitcnt vmcnt(0)
	s_barrier
	global_load_lds_dwordx4 v[36:37], off
	v_lshl_add_u64 v[36:37], v[12:13], 0, s[14:15]
	s_mov_b32 m0, s10
	s_mov_b64 s[64:65], 0x8300
	global_load_lds_dwordx4 v[36:37], off
	v_lshl_add_u64 v[36:37], v[10:11], 0, s[64:65]
	s_mov_b32 m0, s11
	s_mov_b64 s[10:11], 0x10300
	global_load_lds_dwordx4 v[36:37], off
	v_lshl_add_u64 v[36:37], v[22:23], 0, s[14:15]
	s_mov_b32 m0, s21
	s_nop 0
	global_load_lds_dwordx4 v[36:37], off
	v_lshl_add_u64 v[36:37], v[10:11], 0, s[10:11]
	s_mov_b32 m0, s22
	s_mov_b64 s[10:11], 0x18300
	global_load_lds_dwordx4 v[36:37], off
	v_lshl_add_u64 v[36:37], v[24:25], 0, s[14:15]
	s_mov_b32 m0, s23
	s_nop 0
	global_load_lds_dwordx4 v[36:37], off
	v_lshl_add_u64 v[36:37], v[10:11], 0, s[10:11]
	s_mov_b32 m0, s24
	s_nop 0
	global_load_lds_dwordx4 v[36:37], off
	v_lshl_add_u64 v[36:37], v[26:27], 0, s[14:15]
	s_mov_b32 m0, s25
	s_nop 0
	global_load_lds_dwordx4 v[36:37], off
	ds_read_b128 v[116:119], v0 offset:32768
	ds_read_b128 v[120:123], v0 offset:34816
	ds_read_b128 v[124:127], v0 offset:36864
	ds_read_b128 v[128:131], v0 offset:38912
	ds_read_b128 v[132:135], v28 offset:49152
	ds_read_b128 v[136:139], v28 offset:51200
	ds_read_b128 v[140:143], v28 offset:53248
	ds_read_b128 v[144:147], v28 offset:55296
	ds_read_b128 v[148:151], v29 offset:32768
	ds_read_b128 v[152:155], v29 offset:34816
	ds_read_b128 v[180:183], v29 offset:36864
	ds_read_b128 v[184:187], v29 offset:38912
	ds_read_b128 v[188:191], v30 offset:49152
	ds_read_b128 v[192:195], v30 offset:51200
	ds_read_b128 v[196:199], v30 offset:53248
	ds_read_b128 v[200:203], v30 offset:55296
	s_setprio 1
	s_waitcnt lgkmcnt(0)
	v_mfma_f32_16x16x32_bf16 v[78:81], v[116:119], v[132:135], v[78:81]
	v_mfma_f32_16x16x32_bf16 v[100:103], v[116:119], v[136:139], v[100:103]
	v_mfma_f32_16x16x32_bf16 v[104:107], v[116:119], v[140:143], v[104:107]
	v_mfma_f32_16x16x32_bf16 v[32:35], v[116:119], v[144:147], v[32:35]
	v_mfma_f32_16x16x32_bf16 v[82:85], v[120:123], v[132:135], v[82:85]
	v_mfma_f32_16x16x32_bf16 v[90:93], v[120:123], v[136:139], v[90:93]
	v_mfma_f32_16x16x32_bf16 v[108:111], v[120:123], v[140:143], v[108:111]
	v_mfma_f32_16x16x32_bf16 v[42:45], v[120:123], v[144:147], v[42:45]
	v_mfma_f32_16x16x32_bf16 v[86:89], v[124:127], v[132:135], v[86:89]
	v_mfma_f32_16x16x32_bf16 v[94:97], v[124:127], v[136:139], v[94:97]
	v_mfma_f32_16x16x32_bf16 v[112:115], v[124:127], v[140:143], v[112:115]
	v_mfma_f32_16x16x32_bf16 v[50:53], v[124:127], v[144:147], v[50:53]
	v_mfma_f32_16x16x32_bf16 v[66:69], v[128:131], v[132:135], v[66:69]
	v_mfma_f32_16x16x32_bf16 v[70:73], v[128:131], v[136:139], v[70:73]
	v_mfma_f32_16x16x32_bf16 v[74:77], v[128:131], v[140:143], v[74:77]
	v_mfma_f32_16x16x32_bf16 v[62:65], v[128:131], v[144:147], v[62:65]
	v_mfma_f32_16x16x32_bf16 v[78:81], v[148:151], v[188:191], v[78:81]
	v_mfma_f32_16x16x32_bf16 v[100:103], v[148:151], v[192:195], v[100:103]
	v_mfma_f32_16x16x32_bf16 v[104:107], v[148:151], v[196:199], v[104:107]
	v_mfma_f32_16x16x32_bf16 v[32:35], v[148:151], v[200:203], v[32:35]
	v_mfma_f32_16x16x32_bf16 v[82:85], v[152:155], v[188:191], v[82:85]
	v_mfma_f32_16x16x32_bf16 v[90:93], v[152:155], v[192:195], v[90:93]
	v_mfma_f32_16x16x32_bf16 v[108:111], v[152:155], v[196:199], v[108:111]
	v_mfma_f32_16x16x32_bf16 v[42:45], v[152:155], v[200:203], v[42:45]
	v_mfma_f32_16x16x32_bf16 v[86:89], v[180:183], v[188:191], v[86:89]
	v_mfma_f32_16x16x32_bf16 v[94:97], v[180:183], v[192:195], v[94:97]
	v_mfma_f32_16x16x32_bf16 v[112:115], v[180:183], v[196:199], v[112:115]
	v_mfma_f32_16x16x32_bf16 v[50:53], v[180:183], v[200:203], v[50:53]
	v_mfma_f32_16x16x32_bf16 v[66:69], v[184:187], v[188:191], v[66:69]
	v_mfma_f32_16x16x32_bf16 v[70:73], v[184:187], v[192:195], v[70:73]
	v_mfma_f32_16x16x32_bf16 v[74:77], v[184:187], v[196:199], v[74:77]
	v_mfma_f32_16x16x32_bf16 v[62:65], v[184:187], v[200:203], v[62:65]
	s_setprio 0
	s_mov_b64 s[64:65], 0x380
	s_mov_b32 m0, s29
	v_lshl_add_u64 v[36:37], v[10:11], 0, s[64:65]
	s_waitcnt vmcnt(0)
	s_barrier
; #define MFMA16(a, b, c) __builtin_amdgcn_mfma_f32_16x16x32_bf16((a), (b), (c), 0, 0, 0)
; DI void gemm_tile(const bf16_t* __restrict__ A, int lda, const bf16_t* __restrict__ Bt, int ldb, int bvalid, int K, f32x4 (&acc)[4][4], char* lds, bool preloaded = false) {
;     ...
;   auto compute = [&](int st) {
;     const char* base = lds + st * 32768;
;     bf16x8 af[2][4], bfr[2][4];
; #pragma unroll
;     for (int s = 0; s < 2; ++s) {
;       const int ch = ((4 * s + fq) ^ fx) << 4;
; #pragma unroll
;       for (int mi = 0; mi < 4; ++mi) af[s][mi] = *(const bf16x8*)(base + (wm * 64 + mi * 16 + fr) * 128 + ch);
; #pragma unroll
;       for (int ni = 0; ni < 4; ++ni) bfr[s][ni] = *(const bf16x8*)(base + 16384 + (wn * 64 + ni * 16 + fr) * 128 + ch);
;     }
;     __builtin_amdgcn_s_setprio(1);
; #pragma unroll
;     for (int s = 0; s < 2; ++s)
; #pragma unroll
;       for (int mi = 0; mi < 4; ++mi)
; #pragma unroll
;         for (int ni = 0; ni < 4; ++ni) acc[mi][ni] = MFMA16(af[s][mi], bfr[s][ni], acc[mi][ni]);
;     __builtin_amdgcn_s_setprio(0);
;   };
;   const int nk = K >> 6;
;   if (!preloaded) { GLDS(0, 0) }
;   __syncthreads();
;   for (int kt = 0; kt < nk; ++kt) {
;     if (kt + 1 < nk) { GLDS((kt + 1) & 1, (kt + 1) << 6) }
;     compute(kt & 1);
;     __syncthreads();
;   }
	global_load_lds_dwordx4 v[36:37], off
	v_lshl_add_u64 v[12:13], v[12:13], 0, s[64:65]
	s_mov_b32 m0, s26
	s_mov_b64 s[10:11], 0x8380
	global_load_lds_dwordx4 v[12:13], off
	v_lshl_add_u64 v[12:13], v[10:11], 0, s[10:11]
	s_mov_b32 m0, s27
	s_mov_b64 s[10:11], 0x10380
	global_load_lds_dwordx4 v[12:13], off
	v_lshl_add_u64 v[12:13], v[22:23], 0, s[64:65]
	s_mov_b32 m0, s28
	s_nop 0
	global_load_lds_dwordx4 v[12:13], off
	v_lshl_add_u64 v[12:13], v[10:11], 0, s[10:11]
	s_mov_b32 m0, s30
	s_mov_b64 s[10:11], 0x18380
	global_load_lds_dwordx4 v[12:13], off
	v_lshl_add_u64 v[12:13], v[24:25], 0, s[64:65]
	s_mov_b32 m0, s31
	v_lshl_add_u64 v[10:11], v[10:11], 0, s[10:11]
	global_load_lds_dwordx4 v[12:13], off
	s_mov_b32 m0, s34
	s_nop 0
	global_load_lds_dwordx4 v[10:11], off
	v_lshl_add_u64 v[10:11], v[26:27], 0, s[64:65]
	s_mov_b32 m0, s35
	s_nop 0
	global_load_lds_dwordx4 v[10:11], off
	ds_read_b128 v[10:13], v0
	ds_read_b128 v[22:25], v0 offset:2048
	ds_read_b128 v[116:119], v0 offset:4096
	ds_read_b128 v[120:123], v0 offset:6144
	ds_read_b128 v[124:127], v28 offset:16384
	ds_read_b128 v[128:131], v28 offset:18432
	ds_read_b128 v[132:135], v28 offset:20480
	ds_read_b128 v[136:139], v28 offset:22528
	ds_read_b128 v[140:143], v29
	ds_read_b128 v[144:147], v29 offset:2048
	ds_read_b128 v[148:151], v29 offset:4096
	ds_read_b128 v[152:155], v29 offset:6144
	ds_read_b128 v[180:183], v30 offset:16384
	ds_read_b128 v[184:187], v30 offset:18432
	ds_read_b128 v[188:191], v30 offset:20480
	ds_read_b128 v[192:195], v30 offset:22528
	s_setprio 1
	s_waitcnt lgkmcnt(0)
	v_mfma_f32_16x16x32_bf16 v[78:81], v[10:13], v[124:127], v[78:81]
	v_mfma_f32_16x16x32_bf16 v[100:103], v[10:13], v[128:131], v[100:103]
	v_mfma_f32_16x16x32_bf16 v[104:107], v[10:13], v[132:135], v[104:107]
	v_mfma_f32_16x16x32_bf16 v[10:13], v[10:13], v[136:139], v[32:35]
	v_mfma_f32_16x16x32_bf16 v[32:35], v[22:25], v[124:127], v[82:85]
	v_mfma_f32_16x16x32_bf16 v[82:85], v[22:25], v[128:131], v[90:93]
	v_mfma_f32_16x16x32_bf16 v[90:93], v[22:25], v[132:135], v[108:111]
	v_mfma_f32_16x16x32_bf16 v[22:25], v[22:25], v[136:139], v[42:45]
	v_mfma_f32_16x16x32_bf16 v[42:45], v[116:119], v[124:127], v[86:89]
	v_mfma_f32_16x16x32_bf16 v[86:89], v[116:119], v[128:131], v[94:97]
	v_mfma_f32_16x16x32_bf16 v[94:97], v[116:119], v[132:135], v[112:115]
	v_mfma_f32_16x16x32_bf16 v[50:53], v[116:119], v[136:139], v[50:53]
	v_mfma_f32_16x16x32_bf16 v[66:69], v[120:123], v[124:127], v[66:69]
	v_mfma_f32_16x16x32_bf16 v[70:73], v[120:123], v[128:131], v[70:73]
	v_mfma_f32_16x16x32_bf16 v[74:77], v[120:123], v[132:135], v[74:77]
	v_mfma_f32_16x16x32_bf16 v[62:65], v[120:123], v[136:139], v[62:65]
	v_mfma_f32_16x16x32_bf16 v[78:81], v[140:143], v[180:183], v[78:81]
	v_mfma_f32_16x16x32_bf16 v[100:103], v[140:143], v[184:187], v[100:103]
	v_mfma_f32_16x16x32_bf16 v[104:107], v[140:143], v[188:191], v[104:107]
	v_mfma_f32_16x16x32_bf16 v[10:13], v[140:143], v[192:195], v[10:13]
	v_mfma_f32_16x16x32_bf16 v[32:35], v[144:147], v[180:183], v[32:35]
	v_mfma_f32_16x16x32_bf16 v[82:85], v[144:147], v[184:187], v[82:85]
	v_mfma_f32_16x16x32_bf16 v[90:93], v[144:147], v[188:191], v[90:93]
	v_mfma_f32_16x16x32_bf16 v[22:25], v[144:147], v[192:195], v[22:25]
	v_mfma_f32_16x16x32_bf16 v[42:45], v[148:151], v[180:183], v[42:45]
	v_mfma_f32_16x16x32_bf16 v[86:89], v[148:151], v[184:187], v[86:89]
	v_mfma_f32_16x16x32_bf16 v[94:97], v[148:151], v[188:191], v[94:97]
	v_mfma_f32_16x16x32_bf16 v[50:53], v[148:151], v[192:195], v[50:53]
	v_mfma_f32_16x16x32_bf16 v[66:69], v[152:155], v[180:183], v[66:69]
	v_mfma_f32_16x16x32_bf16 v[70:73], v[152:155], v[184:187], v[70:73]
	v_mfma_f32_16x16x32_bf16 v[74:77], v[152:155], v[188:191], v[74:77]
	v_mfma_f32_16x16x32_bf16 v[62:65], v[152:155], v[192:195], v[62:65]
	s_setprio 0
	s_waitcnt vmcnt(0)
	s_barrier
	ds_read_b128 v[108:111], v0 offset:32768
	ds_read_b128 v[112:115], v0 offset:34816
	ds_read_b128 v[116:119], v0 offset:36864
	ds_read_b128 v[120:123], v0 offset:38912
	ds_read_b128 v[124:127], v28 offset:49152
	ds_read_b128 v[128:131], v28 offset:51200
	ds_read_b128 v[132:135], v28 offset:53248
	ds_read_b128 v[136:139], v28 offset:55296
	ds_read_b128 v[140:143], v29 offset:32768
	ds_read_b128 v[144:147], v29 offset:34816
	ds_read_b128 v[148:151], v29 offset:36864
	ds_read_b128 v[26:29], v29 offset:38912
	ds_read_b128 v[152:155], v30 offset:49152
	ds_read_b128 v[180:183], v30 offset:51200
	ds_read_b128 v[184:187], v30 offset:53248
	ds_read_b128 v[188:191], v30 offset:55296
	s_setprio 1
	s_waitcnt lgkmcnt(11)
	v_mfma_f32_16x16x32_bf16 v[78:81], v[108:111], v[124:127], v[78:81]
	s_waitcnt lgkmcnt(10)
	v_mfma_f32_16x16x32_bf16 v[100:103], v[108:111], v[128:131], v[100:103]
	s_waitcnt lgkmcnt(9)
	v_mfma_f32_16x16x32_bf16 v[104:107], v[108:111], v[132:135], v[104:107]
	s_waitcnt lgkmcnt(8)
	v_mfma_f32_16x16x32_bf16 v[108:111], v[108:111], v[136:139], v[10:13]
	v_mfma_f32_16x16x32_bf16 v[34:37], v[112:115], v[124:127], v[32:35]
	v_mfma_f32_16x16x32_bf16 v[82:85], v[112:115], v[128:131], v[82:85]
	v_mfma_f32_16x16x32_bf16 v[192:195], v[112:115], v[132:135], v[90:93]
	v_mfma_f32_16x16x32_bf16 v[112:115], v[112:115], v[136:139], v[22:25]
	v_mfma_f32_16x16x32_bf16 v[42:45], v[116:119], v[124:127], v[42:45]
	v_mfma_f32_16x16x32_bf16 v[196:199], v[116:119], v[128:131], v[86:89]
	v_mfma_f32_16x16x32_bf16 v[200:203], v[116:119], v[132:135], v[94:97]
	v_mfma_f32_16x16x32_bf16 v[50:53], v[116:119], v[136:139], v[50:53]
	v_mfma_f32_16x16x32_bf16 v[116:119], v[120:123], v[124:127], v[66:69]
	v_mfma_f32_16x16x32_bf16 v[124:127], v[120:123], v[128:131], v[70:73]
	v_mfma_f32_16x16x32_bf16 v[128:131], v[120:123], v[132:135], v[74:77]
	v_mfma_f32_16x16x32_bf16 v[120:123], v[120:123], v[136:139], v[62:65]
	s_waitcnt lgkmcnt(3)
	v_mfma_f32_16x16x32_bf16 v[10:13], v[140:143], v[152:155], v[78:81]
	s_waitcnt lgkmcnt(2)
	v_mfma_f32_16x16x32_bf16 v[22:25], v[140:143], v[180:183], v[100:103]
	s_waitcnt lgkmcnt(1)
	v_mfma_f32_16x16x32_bf16 v[30:33], v[140:143], v[184:187], v[104:107]
	s_waitcnt lgkmcnt(0)
	v_mfma_f32_16x16x32_bf16 v[94:97], v[140:143], v[188:191], v[108:111]
	v_mfma_f32_16x16x32_bf16 v[90:93], v[144:147], v[152:155], v[34:37]
	v_mfma_f32_16x16x32_bf16 v[62:65], v[144:147], v[180:183], v[82:85]
	v_mfma_f32_16x16x32_bf16 v[70:73], v[144:147], v[184:187], v[192:195]
	v_mfma_f32_16x16x32_bf16 v[86:89], v[144:147], v[188:191], v[112:115]
	v_mfma_f32_16x16x32_bf16 v[82:85], v[148:151], v[152:155], v[42:45]
	v_mfma_f32_16x16x32_bf16 v[78:81], v[148:151], v[180:183], v[196:199]
	v_mfma_f32_16x16x32_bf16 v[74:77], v[148:151], v[184:187], v[200:203]
	v_mfma_f32_16x16x32_bf16 v[66:69], v[148:151], v[188:191], v[50:53]
	v_mfma_f32_16x16x32_bf16 v[50:53], v[26:29], v[152:155], v[116:119]
	v_mfma_f32_16x16x32_bf16 v[42:45], v[26:29], v[180:183], v[124:127]
	v_mfma_f32_16x16x32_bf16 v[34:37], v[26:29], v[184:187], v[128:131]
	v_mfma_f32_16x16x32_bf16 v[26:29], v[26:29], v[188:191], v[120:123]
	s_setprio 0
	v_mov_b32_e32 v106, v158
	s_barrier
; DI int tidx() { int t = __builtin_amdgcn_workitem_id_x(); asm volatile("" : "+v"(t)); return t; }
; DI void gemm_prefetch0(const bf16_t* __restrict__ A, int lda, const bf16_t* __restrict__ Bt, int ldb, int bvalid, char* lds) {
;   const int tid = tidx();
;   const int lr = tid >> 3, lc = tid & 7;
;   const bf16_t* ap = A + (size_t)lr * lda + ((lc ^ ((lr >> 1) & 7)) << 3);
;   const bf16_t* bp = Bt + ((lc ^ ((lr >> 1) & 7)) << 3);
;   typedef __attribute__((address_space(1))) const unsigned gptr_t;
;   typedef __attribute__((address_space(3))) unsigned lptr_t;
;   const unsigned lbase = (unsigned)(size_t)lds + (unsigned)tid * 16u;
; #pragma unroll
;   for (int i = 0; i < 4; ++i) {
;     __builtin_amdgcn_global_load_lds((gptr_t*)(ap + (size_t)(32 * i) * lda), (lptr_t*)(lbase + i * 4096), 16, 0, 0);
;     __builtin_amdgcn_global_load_lds((gptr_t*)(bp + (size_t)((lr + 32 * i) & (bvalid - 1)) * ldb), (lptr_t*)(lbase + 16384 + i * 4096), 16, 0, 0);
;   }
; DI void phaseD_tile(const P& p, int layer, int mt, int nt, char* lds) {
;     ...
;   gemm_prefetch0((const bf16_t*)(p.ws + W_ZA) + (size_t)row0 * 512, 512, (const bf16_t*)(p.ws + W_WAO) + ((size_t)layer * 1024 + col0) * 512, 512, 128, lds);
; #pragma unroll
;   for (int mi = 0; mi < 4; ++mi)
; #pragma unroll
;     for (int ni = 0; ni < 4; ++ni)
; #pragma unroll
;       for (int j = 0; j < 4; ++j) acc[mi][ni][j] *= (float)((gpv[mi][ni] >> (8 * j)) & 255u) / fmaxf((float)((gav[mi][ni] >> (8 * j)) & 255u), 1.f);
	s_add_u32 s10, s97, s8
	v_readlane_b32 s5, v240, 45
	s_addc_u32 s11, s5, s9
	v_ashrrev_i32_e32 v100, 3, v106
	v_lshrrev_b32_e32 v0, 4, v106
	v_readlane_b32 s8, v240, 33
	v_ashrrev_i32_e32 v101, 31, v100
	v_xor_b32_e32 v0, v0, v106
	v_readlane_b32 s9, v240, 34
	s_add_u32 s8, s8, s12
	v_lshlrev_b64 v[102:103], 10, v[100:101]
	v_lshlrev_b32_e32 v0, 4, v0
	s_addc_u32 s9, s9, s13
	v_lshl_add_u64 v[102:103], s[10:11], 0, v[102:103]
	v_and_b32_e32 v0, 0x70, v0
	v_lshlrev_b32_e32 v107, 9, v100
	v_lshl_add_u64 v[102:103], v[102:103], 0, v[0:1]
	v_lshl_add_u64 v[104:105], s[8:9], 0, v[0:1]
	v_lshlrev_b32_e32 v106, 4, v106
	v_and_b32_e32 v0, 0xfe00, v107
	v_add_u32_e32 v108, 0x4000, v106
	v_readfirstlane_b32 s5, v106
	v_lshlrev_b32_e32 v0, 1, v0
	s_mov_b32 m0, s5
	v_lshl_add_u64 v[100:101], v[104:105], 0, v[0:1]
	v_readfirstlane_b32 s5, v108
	v_add_u32_e32 v0, 0x1000, v106
	global_load_lds_dwordx4 v[102:103], off
	s_mov_b32 m0, s5
	v_readfirstlane_b32 s5, v0
	v_add_u32_e32 v0, 0x4000, v107
	v_and_b32_e32 v0, 0xfe00, v0
	global_load_lds_dwordx4 v[100:101], off
	v_lshl_add_u64 v[100:101], v[102:103], 0, s[40:41]
	s_mov_b32 m0, s5
	v_lshlrev_b32_e32 v0, 1, v0
	global_load_lds_dwordx4 v[100:101], off
	v_lshl_add_u64 v[100:101], v[104:105], 0, v[0:1]
	v_add_u32_e32 v0, 0x5000, v106
	s_mov_b64 s[30:31], 0x100
	v_readfirstlane_b32 s5, v0
	v_add_u32_e32 v0, 0x2000, v106
	s_mov_b32 m0, s5
	v_readfirstlane_b32 s5, v0
	v_bitop3_b32 v0, v107, s33, v167 bitop3:0x6c
	global_load_lds_dwordx4 v[100:101], off
	v_lshl_add_u64 v[100:101], v[102:103], 0, s[42:43]
	s_mov_b32 m0, s5
	v_lshlrev_b32_e32 v0, 1, v0
	global_load_lds_dwordx4 v[100:101], off
	v_lshl_add_u64 v[100:101], v[104:105], 0, v[0:1]
	v_add_u32_e32 v0, 0x6000, v106
	s_nop 0
	v_readfirstlane_b32 s5, v0
	v_add_u32_e32 v0, 0x3000, v106
	s_mov_b32 m0, s5
	v_readfirstlane_b32 s5, v0
	v_add_u32_e32 v0, 0xc000, v107
	v_and_b32_e32 v0, 0xfe00, v0
	global_load_lds_dwordx4 v[100:101], off
	v_lshl_add_u64 v[100:101], v[102:103], 0, s[50:51]
	s_mov_b32 m0, s5
	v_lshlrev_b32_e32 v0, 1, v0
	global_load_lds_dwordx4 v[100:101], off
	v_lshl_add_u64 v[100:101], v[104:105], 0, v[0:1]
	v_add_u32_e32 v0, 0x7000, v106
	v_cvt_f32_ubyte2_e32 v104, v38
	v_readfirstlane_b32 s5, v0
	s_mov_b32 m0, s5
	v_cvt_f32_ubyte0_e32 v0, v46
	global_load_lds_dwordx4 v[100:101], off
	v_max_f32_e32 v100, 1.0, v0
	v_cvt_f32_ubyte1_e32 v0, v46
	v_max_f32_e32 v101, 1.0, v0
	v_cvt_f32_ubyte2_e32 v0, v46
	v_max_f32_e32 v102, 1.0, v0
	v_cvt_f32_ubyte3_e32 v0, v46
	v_max_f32_e32 v103, 1.0, v0
	v_cvt_f32_ubyte0_e32 v0, v38
	v_cvt_f32_ubyte1_e32 v46, v38
	v_cvt_f32_ubyte3_e32 v38, v38
	s_nop 0
	v_rcp_f32_e32 v105, v103
	s_nop 0
	v_mul_f32_e32 v105, v38, v105
	s_nop 0
	v_rcp_f32_e32 v38, v102
	s_nop 0
	v_mul_f32_e32 v104, v104, v38
	v_pk_mul_f32 v[12:13], v[104:105], v[12:13]
	v_rcp_f32_e32 v38, v101
	s_nop 0
	v_mul_f32_e32 v107, v46, v38
	s_nop 0
	v_rcp_f32_e32 v38, v100
	s_nop 0
	v_mul_f32_e32 v106, v0, v38
	v_cvt_f32_ubyte0_e32 v0, v47
	v_max_f32_e32 v104, 1.0, v0
	v_cvt_f32_ubyte1_e32 v0, v47
	v_max_f32_e32 v105, 1.0, v0
	v_cvt_f32_ubyte2_e32 v0, v47
	v_pk_mul_f32 v[10:11], v[106:107], v[10:11]
	v_max_f32_e32 v106, 1.0, v0
	v_cvt_f32_ubyte3_e32 v0, v47
	v_max_f32_e32 v107, 1.0, v0
	v_cvt_f32_ubyte0_e32 v0, v39
	v_cvt_f32_ubyte1_e32 v46, v39
	v_cvt_f32_ubyte2_e32 v38, v39
	v_cvt_f32_ubyte3_e32 v39, v39
	s_nop 0
	v_rcp_f32_e32 v47, v107
	s_nop 0
	v_mul_f32_e32 v39, v39, v47
	s_nop 0
	v_rcp_f32_e32 v47, v106
	s_nop 0
	v_mul_f32_e32 v38, v38, v47
	v_pk_mul_f32 v[24:25], v[38:39], v[24:25]
	v_cvt_f32_ubyte3_e32 v39, v40
	v_cvt_f32_ubyte2_e32 v38, v40
	v_rcp_f32_e32 v47, v105
	s_nop 0
	v_mul_f32_e32 v47, v46, v47
	s_nop 0
	v_rcp_f32_e32 v46, v104
	s_nop 0
	v_mul_f32_e32 v46, v0, v46
	v_cvt_f32_ubyte0_e32 v0, v48
	v_max_f32_e32 v108, 1.0, v0
	v_cvt_f32_ubyte1_e32 v0, v48
	v_max_f32_e32 v109, 1.0, v0
	v_cvt_f32_ubyte2_e32 v0, v48
	v_max_f32_e32 v110, 1.0, v0
	v_cvt_f32_ubyte3_e32 v0, v48
	v_max_f32_e32 v111, 1.0, v0
	v_pk_mul_f32 v[22:23], v[46:47], v[22:23]
	v_cvt_f32_ubyte0_e32 v0, v40
	v_cvt_f32_ubyte1_e32 v46, v40
	s_nop 0
	v_rcp_f32_e32 v40, v111
	s_nop 0
	v_mul_f32_e32 v39, v39, v40
	s_nop 0
	v_rcp_f32_e32 v40, v110
	s_nop 0
	v_mul_f32_e32 v38, v38, v40
	v_pk_mul_f32 v[32:33], v[38:39], v[32:33]
	v_cvt_f32_ubyte1_e32 v38, v41
	v_cvt_f32_ubyte2_e32 v39, v41
	v_rcp_f32_e32 v40, v109
	s_nop 0
	v_mul_f32_e32 v47, v46, v40
	s_nop 0
	v_rcp_f32_e32 v40, v108
	s_nop 0
	v_mul_f32_e32 v46, v0, v40
	v_cvt_f32_ubyte0_e32 v0, v49
	v_max_f32_e32 v112, 1.0, v0
	v_cvt_f32_ubyte1_e32 v0, v49
	v_max_f32_e32 v113, 1.0, v0
	v_cvt_f32_ubyte2_e32 v0, v49
	v_max_f32_e32 v114, 1.0, v0
	v_cvt_f32_ubyte3_e32 v0, v49
	v_max_f32_e32 v115, 1.0, v0
	v_cvt_f32_ubyte3_e32 v40, v41
	v_cvt_f32_ubyte0_e32 v0, v41
	v_pk_mul_f32 v[30:31], v[46:47], v[30:31]
	s_nop 0
	v_rcp_f32_e32 v41, v115
	s_nop 0
	v_mul_f32_e32 v41, v40, v41
	s_nop 0
	v_rcp_f32_e32 v40, v114
	s_nop 0
	v_mul_f32_e32 v40, v39, v40
	v_pk_mul_f32 v[40:41], v[40:41], v[96:97]
	v_rcp_f32_e32 v39, v113
	s_nop 0
	v_mul_f32_e32 v39, v38, v39
	s_nop 0
	v_rcp_f32_e32 v38, v112
	s_nop 0
	v_mul_f32_e32 v38, v0, v38
	v_cvt_f32_ubyte0_e32 v0, v58
	v_pk_mul_f32 v[38:39], v[38:39], v[94:95]
	v_max_f32_e32 v94, 1.0, v0
	v_cvt_f32_ubyte1_e32 v0, v58
	v_max_f32_e32 v95, 1.0, v0
	v_cvt_f32_ubyte2_e32 v0, v58
	v_max_f32_e32 v96, 1.0, v0
	v_cvt_f32_ubyte3_e32 v0, v58
	v_max_f32_e32 v97, 1.0, v0
	v_cvt_f32_ubyte3_e32 v48, v54
	v_cvt_f32_ubyte0_e32 v0, v54
	v_cvt_f32_ubyte1_e32 v46, v54
	v_cvt_f32_ubyte2_e32 v47, v54
	s_nop 0
	v_rcp_f32_e32 v49, v97
	s_nop 0
	v_mul_f32_e32 v49, v48, v49
	s_nop 0
	v_rcp_f32_e32 v48, v96
	s_nop 0
; DI void phaseD_tile(const P& p, int layer, int mt, int nt, char* lds) {
;     ...
; #pragma unroll
;   for (int mi = 0; mi < 4; ++mi)
; #pragma unroll
;     for (int ni = 0; ni < 4; ++ni)
; #pragma unroll
;       for (int j = 0; j < 4; ++j) acc[mi][ni][j] *= (float)((gpv[mi][ni] >> (8 * j)) & 255u) / fmaxf((float)((gav[mi][ni] >> (8 * j)) & 255u), 1.f);
	v_mul_f32_e32 v48, v47, v48
	v_pk_mul_f32 v[48:49], v[48:49], v[92:93]
	v_rcp_f32_e32 v47, v95
	s_nop 0
	v_mul_f32_e32 v47, v46, v47
	s_nop 0
	v_rcp_f32_e32 v46, v94
	s_nop 0
	v_mul_f32_e32 v46, v0, v46
	v_cvt_f32_ubyte0_e32 v0, v59
	v_pk_mul_f32 v[46:47], v[46:47], v[90:91]
	v_max_f32_e32 v90, 1.0, v0
	v_cvt_f32_ubyte1_e32 v0, v59
	v_max_f32_e32 v91, 1.0, v0
	v_cvt_f32_ubyte2_e32 v0, v59
	v_max_f32_e32 v92, 1.0, v0
	v_cvt_f32_ubyte3_e32 v0, v59
	v_max_f32_e32 v93, 1.0, v0
	v_cvt_f32_ubyte0_e32 v0, v55
	v_cvt_f32_ubyte1_e32 v58, v55
	v_cvt_f32_ubyte2_e32 v54, v55
	v_cvt_f32_ubyte3_e32 v55, v55
	s_nop 0
	v_rcp_f32_e32 v59, v93
	s_nop 0
	v_mul_f32_e32 v55, v55, v59
	s_nop 0
	v_rcp_f32_e32 v59, v92
	s_nop 0
	v_mul_f32_e32 v54, v54, v59
	v_pk_mul_f32 v[64:65], v[54:55], v[64:65]
	v_cvt_f32_ubyte3_e32 v55, v56
	v_cvt_f32_ubyte2_e32 v54, v56
	v_rcp_f32_e32 v59, v91
	s_nop 0
	v_mul_f32_e32 v59, v58, v59
	s_nop 0
	v_rcp_f32_e32 v58, v90
	s_nop 0
	v_mul_f32_e32 v58, v0, v58
	v_cvt_f32_ubyte0_e32 v0, v60
	v_max_f32_e32 v116, 1.0, v0
	v_cvt_f32_ubyte1_e32 v0, v60
	v_max_f32_e32 v117, 1.0, v0
	v_cvt_f32_ubyte2_e32 v0, v60
	v_max_f32_e32 v118, 1.0, v0
	v_cvt_f32_ubyte3_e32 v0, v60
	v_max_f32_e32 v119, 1.0, v0
	v_pk_mul_f32 v[62:63], v[58:59], v[62:63]
	v_cvt_f32_ubyte0_e32 v0, v56
	v_cvt_f32_ubyte1_e32 v58, v56
	s_nop 0
	v_rcp_f32_e32 v56, v119
	s_nop 0
	v_mul_f32_e32 v55, v55, v56
	s_nop 0
	v_rcp_f32_e32 v56, v118
	s_nop 0
	v_mul_f32_e32 v54, v54, v56
	v_pk_mul_f32 v[72:73], v[54:55], v[72:73]
	v_cvt_f32_ubyte1_e32 v54, v57
	v_cvt_f32_ubyte2_e32 v55, v57
	v_rcp_f32_e32 v56, v117
	s_nop 0
	v_mul_f32_e32 v59, v58, v56
	s_nop 0
	v_rcp_f32_e32 v56, v116
	s_nop 0
	v_mul_f32_e32 v58, v0, v56
	v_cvt_f32_ubyte0_e32 v0, v61
	v_max_f32_e32 v120, 1.0, v0
	v_cvt_f32_ubyte1_e32 v0, v61
	v_max_f32_e32 v121, 1.0, v0
	v_cvt_f32_ubyte2_e32 v0, v61
	v_max_f32_e32 v122, 1.0, v0
	v_cvt_f32_ubyte3_e32 v0, v61
	v_max_f32_e32 v123, 1.0, v0
	v_cvt_f32_ubyte3_e32 v56, v57
	v_cvt_f32_ubyte0_e32 v0, v57
	v_pk_mul_f32 v[70:71], v[58:59], v[70:71]
	s_nop 0
	v_rcp_f32_e32 v57, v123
	s_nop 0
	v_mul_f32_e32 v57, v56, v57
	s_nop 0
	v_rcp_f32_e32 v56, v122
	s_nop 0
	v_mul_f32_e32 v56, v55, v56
	v_pk_mul_f32 v[56:57], v[56:57], v[88:89]
	v_rcp_f32_e32 v55, v121
	s_nop 0
	v_mul_f32_e32 v55, v54, v55
	s_nop 0
	v_rcp_f32_e32 v54, v120
	s_nop 0
	v_mul_f32_e32 v54, v0, v54
	v_cvt_f32_ubyte0_e32 v0, v18
	v_pk_mul_f32 v[54:55], v[54:55], v[86:87]
	v_max_f32_e32 v86, 1.0, v0
	v_cvt_f32_ubyte1_e32 v0, v18
	v_max_f32_e32 v87, 1.0, v0
	v_cvt_f32_ubyte2_e32 v0, v18
	v_max_f32_e32 v88, 1.0, v0
	v_cvt_f32_ubyte3_e32 v0, v18
	v_max_f32_e32 v89, 1.0, v0
	v_cvt_f32_ubyte0_e32 v0, v14
	v_cvt_f32_ubyte1_e32 v18, v14
	v_cvt_f32_ubyte2_e32 v58, v14
	v_cvt_f32_ubyte3_e32 v14, v14
	s_nop 0
	v_rcp_f32_e32 v59, v89
	s_nop 0
	v_mul_f32_e32 v61, v14, v59
	s_nop 0
	v_rcp_f32_e32 v14, v88
	s_nop 0
	v_mul_f32_e32 v60, v58, v14
	v_pk_mul_f32 v[60:61], v[60:61], v[84:85]
	v_rcp_f32_e32 v14, v87
	s_nop 0
	v_mul_f32_e32 v59, v18, v14
	s_nop 0
	v_rcp_f32_e32 v14, v86
	s_nop 0
	v_mul_f32_e32 v58, v0, v14
	v_cvt_f32_ubyte0_e32 v0, v19
	v_pk_mul_f32 v[58:59], v[58:59], v[82:83]
	v_max_f32_e32 v82, 1.0, v0
	v_cvt_f32_ubyte1_e32 v0, v19
	v_max_f32_e32 v83, 1.0, v0
	v_cvt_f32_ubyte2_e32 v0, v19
	v_max_f32_e32 v84, 1.0, v0
	v_cvt_f32_ubyte3_e32 v0, v19
	v_max_f32_e32 v85, 1.0, v0
	v_cvt_f32_ubyte0_e32 v0, v15
	v_cvt_f32_ubyte1_e32 v18, v15
	v_cvt_f32_ubyte2_e32 v14, v15
	v_cvt_f32_ubyte3_e32 v15, v15
	s_nop 0
	v_rcp_f32_e32 v19, v85
	s_nop 0
	v_mul_f32_e32 v15, v15, v19
	s_nop 0
	v_rcp_f32_e32 v19, v84
	s_nop 0
	v_mul_f32_e32 v14, v14, v19
	v_pk_mul_f32 v[80:81], v[14:15], v[80:81]
	v_cvt_f32_ubyte3_e32 v15, v16
	v_cvt_f32_ubyte2_e32 v14, v16
	v_rcp_f32_e32 v19, v83
	s_nop 0
	v_mul_f32_e32 v19, v18, v19
	s_nop 0
	v_rcp_f32_e32 v18, v82
	s_nop 0
	v_mul_f32_e32 v18, v0, v18
	v_cvt_f32_ubyte0_e32 v0, v20
	v_max_f32_e32 v124, 1.0, v0
	v_cvt_f32_ubyte1_e32 v0, v20
	v_max_f32_e32 v125, 1.0, v0
	v_cvt_f32_ubyte2_e32 v0, v20
	v_max_f32_e32 v126, 1.0, v0
	v_cvt_f32_ubyte3_e32 v0, v20
	v_max_f32_e32 v127, 1.0, v0
	v_pk_mul_f32 v[78:79], v[18:19], v[78:79]
	v_cvt_f32_ubyte0_e32 v0, v16
	v_cvt_f32_ubyte1_e32 v18, v16
	s_nop 0
	v_rcp_f32_e32 v16, v127
	s_nop 0
	v_mul_f32_e32 v15, v15, v16
	s_nop 0
	v_rcp_f32_e32 v16, v126
	s_nop 0
	v_mul_f32_e32 v14, v14, v16
	v_pk_mul_f32 v[76:77], v[14:15], v[76:77]
	v_cvt_f32_ubyte1_e32 v14, v17
	v_cvt_f32_ubyte2_e32 v15, v17
	v_rcp_f32_e32 v16, v125
	s_nop 0
	v_mul_f32_e32 v19, v18, v16
	s_nop 0
	v_rcp_f32_e32 v16, v124
	s_nop 0
	v_mul_f32_e32 v18, v0, v16
	v_cvt_f32_ubyte0_e32 v0, v21
	v_max_f32_e32 v128, 1.0, v0
	v_cvt_f32_ubyte1_e32 v0, v21
	v_max_f32_e32 v129, 1.0, v0
	v_cvt_f32_ubyte2_e32 v0, v21
	v_max_f32_e32 v130, 1.0, v0
	v_cvt_f32_ubyte3_e32 v0, v21
	v_max_f32_e32 v131, 1.0, v0
	v_cvt_f32_ubyte3_e32 v16, v17
	v_cvt_f32_ubyte0_e32 v0, v17
	v_pk_mul_f32 v[74:75], v[18:19], v[74:75]
	s_nop 0
	v_rcp_f32_e32 v17, v131
	s_nop 0
	v_mul_f32_e32 v17, v16, v17
	s_nop 0
	v_rcp_f32_e32 v16, v130
	s_nop 0
	v_mul_f32_e32 v16, v15, v16
	v_pk_mul_f32 v[16:17], v[16:17], v[68:69]
	v_rcp_f32_e32 v15, v129
	s_nop 0
	v_mul_f32_e32 v15, v14, v15
	s_nop 0
	v_rcp_f32_e32 v14, v128
	s_nop 0
	v_mul_f32_e32 v14, v0, v14
	v_cvt_f32_ubyte0_e32 v0, v6
	v_pk_mul_f32 v[14:15], v[14:15], v[66:67]
	v_max_f32_e32 v66, 1.0, v0
	v_cvt_f32_ubyte1_e32 v0, v6
	v_max_f32_e32 v67, 1.0, v0
	v_cvt_f32_ubyte2_e32 v0, v6
	v_max_f32_e32 v68, 1.0, v0
	v_cvt_f32_ubyte3_e32 v0, v6
	v_max_f32_e32 v69, 1.0, v0
	v_cvt_f32_ubyte0_e32 v0, v2
	v_cvt_f32_ubyte1_e32 v6, v2
	v_cvt_f32_ubyte2_e32 v18, v2
	v_cvt_f32_ubyte3_e32 v2, v2
	s_nop 0
; #define MFMA16(a, b, c) __builtin_amdgcn_mfma_f32_16x16x32_bf16((a), (b), (c), 0, 0, 0)
; DI void gemm_tile(const bf16_t* __restrict__ A, int lda, const bf16_t* __restrict__ Bt, int ldb, int bvalid, int K, f32x4 (&acc)[4][4], char* lds, bool preloaded = false) {
;     ...
;   const bf16_t* ap = A + (size_t)lr * lda + ((lc ^ ((lr >> 1) & 7)) << 3);
;   const bf16_t* bp = Bt + ((lc ^ ((lr >> 1) & 7)) << 3);
;   typedef __attribute__((address_space(1))) const unsigned gptr_t;
;   typedef __attribute__((address_space(3))) unsigned lptr_t;
;   const unsigned lbase = (unsigned)(size_t)lds + (unsigned)tid * 16u;
;     ...
;   auto compute = [&](int st) {
;     const char* base = lds + st * 32768;
;     bf16x8 af[2][4], bfr[2][4];
; #pragma unroll
;     for (int s = 0; s < 2; ++s) {
;       const int ch = ((4 * s + fq) ^ fx) << 4;
; #pragma unroll
;       for (int mi = 0; mi < 4; ++mi) af[s][mi] = *(const bf16x8*)(base + (wm * 64 + mi * 16 + fr) * 128 + ch);
; #pragma unroll
;       for (int ni = 0; ni < 4; ++ni) bfr[s][ni] = *(const bf16x8*)(base + 16384 + (wn * 64 + ni * 16 + fr) * 128 + ch);
;     }
;     __builtin_amdgcn_s_setprio(1);
; #pragma unroll
;     for (int s = 0; s < 2; ++s)
; #pragma unroll
;       for (int mi = 0; mi < 4; ++mi)
; #pragma unroll
;         for (int ni = 0; ni < 4; ++ni) acc[mi][ni] = MFMA16(af[s][mi], bfr[s][ni], acc[mi][ni]);
;     __builtin_amdgcn_s_setprio(0);
;   };
;   const int nk = K >> 6;
;   if (!preloaded) { GLDS(0, 0) }
;   __syncthreads();
;   for (int kt = 0; kt < nk; ++kt) {
;     if (kt + 1 < nk) { GLDS((kt + 1) & 1, (kt + 1) << 6) }
; DI void phaseD_tile(const P& p, int layer, int mt, int nt, char* lds) {
;     ...
;       for (int j = 0; j < 4; ++j) acc[mi][ni][j] *= (float)((gpv[mi][ni] >> (8 * j)) & 255u) / fmaxf((float)((gav[mi][ni] >> (8 * j)) & 255u), 1.f);
;   gemm_tile((const bf16_t*)(p.ws + W_ZA) + (size_t)row0 * 512, 512, (const bf16_t*)(p.ws + W_WAO) + ((size_t)layer * 1024 + col0) * 512, 512, 128, 512, acc, lds, true);
	v_rcp_f32_e32 v19, v69
	s_nop 0
	v_mul_f32_e32 v21, v2, v19
	s_nop 0
	v_rcp_f32_e32 v2, v68
	s_nop 0
	v_mul_f32_e32 v20, v18, v2
	v_pk_mul_f32 v[20:21], v[20:21], v[52:53]
	v_rcp_f32_e32 v2, v67
	s_nop 0
	v_mul_f32_e32 v19, v6, v2
	s_nop 0
	v_rcp_f32_e32 v2, v66
	s_nop 0
	v_mul_f32_e32 v18, v0, v2
	v_cvt_f32_ubyte0_e32 v0, v7
	v_max_f32_e32 v52, 1.0, v0
	v_cvt_f32_ubyte1_e32 v0, v7
	v_max_f32_e32 v53, 1.0, v0
	v_cvt_f32_ubyte2_e32 v0, v7
	v_max_f32_e32 v132, 1.0, v0
	v_cvt_f32_ubyte3_e32 v0, v7
	v_max_f32_e32 v133, 1.0, v0
	v_cvt_f32_ubyte0_e32 v0, v3
	v_cvt_f32_ubyte1_e32 v6, v3
	v_cvt_f32_ubyte2_e32 v2, v3
	v_cvt_f32_ubyte3_e32 v3, v3
	v_pk_mul_f32 v[18:19], v[18:19], v[50:51]
	s_nop 0
	v_rcp_f32_e32 v7, v133
	s_nop 0
	v_mul_f32_e32 v3, v3, v7
	s_nop 0
	v_rcp_f32_e32 v7, v132
	s_nop 0
	v_mul_f32_e32 v2, v2, v7
	v_pk_mul_f32 v[44:45], v[2:3], v[44:45]
	v_cvt_f32_ubyte3_e32 v3, v4
	v_cvt_f32_ubyte2_e32 v2, v4
	v_rcp_f32_e32 v7, v53
	s_nop 0
	v_mul_f32_e32 v7, v6, v7
	s_nop 0
	v_rcp_f32_e32 v6, v52
	s_nop 0
	v_mul_f32_e32 v6, v0, v6
	v_cvt_f32_ubyte0_e32 v0, v8
	v_max_f32_e32 v134, 1.0, v0
	v_cvt_f32_ubyte1_e32 v0, v8
	v_max_f32_e32 v135, 1.0, v0
	v_cvt_f32_ubyte2_e32 v0, v8
	v_max_f32_e32 v136, 1.0, v0
	v_cvt_f32_ubyte3_e32 v0, v8
	v_max_f32_e32 v137, 1.0, v0
	v_pk_mul_f32 v[42:43], v[6:7], v[42:43]
	v_cvt_f32_ubyte0_e32 v0, v4
	v_cvt_f32_ubyte1_e32 v6, v4
	s_nop 0
	v_rcp_f32_e32 v4, v137
	s_nop 0
	v_mul_f32_e32 v3, v3, v4
	s_nop 0
	v_rcp_f32_e32 v4, v136
	s_nop 0
	v_mul_f32_e32 v2, v2, v4
	v_pk_mul_f32 v[36:37], v[2:3], v[36:37]
	v_cvt_f32_ubyte1_e32 v2, v5
	v_cvt_f32_ubyte2_e32 v3, v5
	v_rcp_f32_e32 v4, v135
	s_nop 0
	v_mul_f32_e32 v7, v6, v4
	s_nop 0
	v_rcp_f32_e32 v4, v134
	s_nop 0
	v_mul_f32_e32 v6, v0, v4
	v_cvt_f32_ubyte0_e32 v0, v9
	v_max_f32_e32 v138, 1.0, v0
	v_cvt_f32_ubyte1_e32 v0, v9
	v_max_f32_e32 v139, 1.0, v0
	v_cvt_f32_ubyte2_e32 v0, v9
	v_max_f32_e32 v140, 1.0, v0
	v_cvt_f32_ubyte3_e32 v0, v9
	v_max_f32_e32 v141, 1.0, v0
	v_cvt_f32_ubyte3_e32 v4, v5
	v_cvt_f32_ubyte0_e32 v0, v5
	v_pk_mul_f32 v[34:35], v[6:7], v[34:35]
	s_nop 0
	v_rcp_f32_e32 v5, v141
	s_nop 0
	v_mul_f32_e32 v5, v4, v5
	s_nop 0
	v_rcp_f32_e32 v4, v140
	s_nop 0
	v_mul_f32_e32 v4, v3, v4
	v_pk_mul_f32 v[4:5], v[4:5], v[28:29]
	v_rcp_f32_e32 v3, v139
	s_nop 0
	v_mul_f32_e32 v3, v2, v3
	s_nop 0
	v_rcp_f32_e32 v2, v138
	s_nop 0
	v_mul_f32_e32 v2, v0, v2
	v_pk_mul_f32 v[2:3], v[2:3], v[26:27]
	v_mov_b32_e32 v26, v158
	s_waitcnt vmcnt(0) lgkmcnt(0)
	v_ashrrev_i32_e32 v8, 3, v26
	v_lshrrev_b32_e32 v0, 4, v26
	v_ashrrev_i32_e32 v9, 31, v8
	v_xor_b32_e32 v0, v0, v26
	v_lshlrev_b64 v[6:7], 10, v[8:9]
	v_lshlrev_b32_e32 v0, 4, v0
	v_readfirstlane_b32 s5, v26
	v_lshl_add_u64 v[6:7], s[10:11], 0, v[6:7]
	v_and_b32_e32 v0, 0x70, v0
	v_lshl_add_u64 v[6:7], v[6:7], 0, v[0:1]
	v_lshl_add_u64 v[50:51], s[8:9], 0, v[0:1]
	s_lshl_b32 s8, s5, 7
	v_lshlrev_b32_e32 v0, 7, v26
	s_lshl_b32 s5, s5, 6
	v_bfe_u32 v27, v26, 4, 2
	v_bfe_u32 v29, v26, 1, 3
	s_and_b32 s8, s8, 0x2000
	v_and_b32_e32 v0, 0x780, v0
	s_and_b32 s5, s5, 0xffffe000
	v_lshlrev_b32_e32 v156, 4, v26
	v_or_b32_e32 v157, s8, v0
	v_or_b32_e32 v179, s5, v0
	v_bitop3_b32 v0, v27, v29, 4 bitop3:0x36
	v_lshrrev_b32_e32 v28, 1, v26
	v_lshlrev_b32_e32 v220, 4, v0
	v_lshlrev_b32_e32 v0, 9, v8
	v_add_u32_e32 v143, 0x8000, v156
	v_bitop3_b32 v9, v28, v27, 7 bitop3:0x6c
	v_and_b32_e32 v26, 0xfe00, v0
	v_add_u32_e32 v8, 0x4000, v0
	v_bitop3_b32 v146, v0, s33, v167 bitop3:0x6c
	v_add_u32_e32 v0, 0xc000, v0
	v_readfirstlane_b32 s13, v143
	v_lshlrev_b32_e32 v145, 4, v9
	v_and_b32_e32 v28, 0xfe00, v8
	v_and_b32_e32 v148, 0xfe00, v0
	v_lshl_add_u64 v[8:9], v[6:7], 0, s[38:39]
	v_add_u32_e32 v142, 0xc000, v156
	s_mov_b32 m0, s13
	v_lshlrev_b32_e32 v0, 1, v26
	s_barrier
	global_load_lds_dwordx4 v[8:9], off
	v_lshl_add_u64 v[8:9], v[50:51], 0, v[0:1]
	v_readfirstlane_b32 s12, v142
	v_add_u32_e32 v144, 0x9000, v156
	v_lshl_add_u64 v[26:27], v[8:9], 0, s[38:39]
	s_mov_b32 m0, s12
	v_readfirstlane_b32 s21, v144
	global_load_lds_dwordx4 v[26:27], off
	v_lshl_add_u64 v[26:27], v[6:7], 0, s[58:59]
	s_mov_b32 m0, s21
	v_lshlrev_b32_e32 v0, 1, v28
	global_load_lds_dwordx4 v[26:27], off
	v_lshl_add_u64 v[26:27], v[50:51], 0, v[0:1]
	v_add_u32_e32 v0, 0xd000, v156
	v_lshl_add_u64 v[28:29], v[26:27], 0, s[38:39]
	v_readfirstlane_b32 s5, v0
	v_add_u32_e32 v0, 0xa000, v156
	s_mov_b32 m0, s5
	v_readfirstlane_b32 s8, v0
	global_load_lds_dwordx4 v[28:29], off
	v_lshl_add_u64 v[28:29], v[6:7], 0, s[62:63]
	s_mov_b32 m0, s8
	v_lshlrev_b32_e32 v0, 1, v146
	global_load_lds_dwordx4 v[28:29], off
	v_lshl_add_u64 v[28:29], v[50:51], 0, v[0:1]
	v_add_u32_e32 v0, 0xe000, v156
	v_lshl_add_u64 v[146:147], v[28:29], 0, s[38:39]
	v_readfirstlane_b32 s9, v0
	v_add_u32_e32 v0, 0xb000, v156
	s_mov_b32 m0, s9
	v_readfirstlane_b32 s10, v0
	v_lshlrev_b32_e32 v0, 1, v148
	v_lshl_add_u64 v[50:51], v[50:51], 0, v[0:1]
	v_add_u32_e32 v0, 0xf000, v156
	global_load_lds_dwordx4 v[146:147], off
	v_lshl_add_u64 v[146:147], v[6:7], 0, s[68:69]
	s_mov_b32 m0, s10
	v_readfirstlane_b32 s11, v0
	global_load_lds_dwordx4 v[146:147], off
	v_lshl_add_u64 v[146:147], v[50:51], 0, s[38:39]
	s_mov_b32 m0, s11
	v_or_b32_e32 v0, v145, v179
	global_load_lds_dwordx4 v[146:147], off
	v_or_b32_e32 v145, v145, v157
	v_or_b32_e32 v146, v220, v179
	v_or_b32_e32 v147, v220, v157
	ds_read_b128 v[148:151], v0
	ds_read_b128 v[152:155], v0 offset:2048
	ds_read_b128 v[180:183], v0 offset:4096
	ds_read_b128 v[184:187], v0 offset:6144
	ds_read_b128 v[188:191], v145 offset:16384
	ds_read_b128 v[192:195], v145 offset:18432
	ds_read_b128 v[196:199], v145 offset:20480
	ds_read_b128 v[200:203], v145 offset:22528
	ds_read_b128 v[204:207], v146
	ds_read_b128 v[208:211], v146 offset:2048
	ds_read_b128 v[212:215], v146 offset:4096
	ds_read_b128 v[216:219], v146 offset:6144
	ds_read_b128 v[220:223], v147 offset:16384
	ds_read_b128 v[224:227], v147 offset:18432
	ds_read_b128 v[228:231], v147 offset:20480
	ds_read_b128 v[232:235], v147 offset:22528
	s_setprio 1
	s_waitcnt lgkmcnt(0)
; #define MFMA16(a, b, c) __builtin_amdgcn_mfma_f32_16x16x32_bf16((a), (b), (c), 0, 0, 0)
; DI void gemm_tile(const bf16_t* __restrict__ A, int lda, const bf16_t* __restrict__ Bt, int ldb, int bvalid, int K, f32x4 (&acc)[4][4], char* lds, bool preloaded = false) {
;     ...
;   auto compute = [&](int st) {
;     const char* base = lds + st * 32768;
;     bf16x8 af[2][4], bfr[2][4];
; #pragma unroll
;     for (int s = 0; s < 2; ++s) {
;       const int ch = ((4 * s + fq) ^ fx) << 4;
; #pragma unroll
;       for (int mi = 0; mi < 4; ++mi) af[s][mi] = *(const bf16x8*)(base + (wm * 64 + mi * 16 + fr) * 128 + ch);
; #pragma unroll
;       for (int ni = 0; ni < 4; ++ni) bfr[s][ni] = *(const bf16x8*)(base + 16384 + (wn * 64 + ni * 16 + fr) * 128 + ch);
;     }
;     __builtin_amdgcn_s_setprio(1);
; #pragma unroll
;     for (int s = 0; s < 2; ++s)
; #pragma unroll
;       for (int mi = 0; mi < 4; ++mi)
; #pragma unroll
;         for (int ni = 0; ni < 4; ++ni) acc[mi][ni] = MFMA16(af[s][mi], bfr[s][ni], acc[mi][ni]);
;     __builtin_amdgcn_s_setprio(0);
;   };
;   const int nk = K >> 6;
;   if (!preloaded) { GLDS(0, 0) }
;   __syncthreads();
;   for (int kt = 0; kt < nk; ++kt) {
;     if (kt + 1 < nk) { GLDS((kt + 1) & 1, (kt + 1) << 6) }
;     compute(kt & 1);
;     __syncthreads();
;   }
	v_mfma_f32_16x16x32_bf16 v[2:5], v[184:187], v[200:203], v[2:5]
	v_mfma_f32_16x16x32_bf16 v[10:13], v[148:151], v[188:191], v[10:13]
	v_mfma_f32_16x16x32_bf16 v[22:25], v[148:151], v[192:195], v[22:25]
	v_mfma_f32_16x16x32_bf16 v[30:33], v[148:151], v[196:199], v[30:33]
	v_mfma_f32_16x16x32_bf16 v[38:41], v[148:151], v[200:203], v[38:41]
	v_mfma_f32_16x16x32_bf16 v[46:49], v[152:155], v[188:191], v[46:49]
	v_mfma_f32_16x16x32_bf16 v[62:65], v[152:155], v[192:195], v[62:65]
	v_mfma_f32_16x16x32_bf16 v[70:73], v[152:155], v[196:199], v[70:73]
	v_mfma_f32_16x16x32_bf16 v[54:57], v[152:155], v[200:203], v[54:57]
	v_mfma_f32_16x16x32_bf16 v[58:61], v[180:183], v[188:191], v[58:61]
	v_mfma_f32_16x16x32_bf16 v[78:81], v[180:183], v[192:195], v[78:81]
	v_mfma_f32_16x16x32_bf16 v[74:77], v[180:183], v[196:199], v[74:77]
	v_mfma_f32_16x16x32_bf16 v[14:17], v[180:183], v[200:203], v[14:17]
	v_mfma_f32_16x16x32_bf16 v[18:21], v[184:187], v[188:191], v[18:21]
	v_mfma_f32_16x16x32_bf16 v[42:45], v[184:187], v[192:195], v[42:45]
	v_mfma_f32_16x16x32_bf16 v[34:37], v[184:187], v[196:199], v[34:37]
	v_mfma_f32_16x16x32_bf16 v[2:5], v[216:219], v[232:235], v[2:5]
	v_mfma_f32_16x16x32_bf16 v[10:13], v[204:207], v[220:223], v[10:13]
	v_mfma_f32_16x16x32_bf16 v[22:25], v[204:207], v[224:227], v[22:25]
	v_mfma_f32_16x16x32_bf16 v[30:33], v[204:207], v[228:231], v[30:33]
	v_mfma_f32_16x16x32_bf16 v[38:41], v[204:207], v[232:235], v[38:41]
	v_mfma_f32_16x16x32_bf16 v[46:49], v[208:211], v[220:223], v[46:49]
	v_mfma_f32_16x16x32_bf16 v[62:65], v[208:211], v[224:227], v[62:65]
	v_mfma_f32_16x16x32_bf16 v[70:73], v[208:211], v[228:231], v[70:73]
	v_mfma_f32_16x16x32_bf16 v[54:57], v[208:211], v[232:235], v[54:57]
	v_mfma_f32_16x16x32_bf16 v[58:61], v[212:215], v[220:223], v[58:61]
	v_mfma_f32_16x16x32_bf16 v[78:81], v[212:215], v[224:227], v[78:81]
	v_mfma_f32_16x16x32_bf16 v[74:77], v[212:215], v[228:231], v[74:77]
	v_mfma_f32_16x16x32_bf16 v[14:17], v[212:215], v[232:235], v[14:17]
	v_mfma_f32_16x16x32_bf16 v[18:21], v[216:219], v[220:223], v[18:21]
	v_mfma_f32_16x16x32_bf16 v[42:45], v[216:219], v[224:227], v[42:45]
	v_mfma_f32_16x16x32_bf16 v[34:37], v[216:219], v[228:231], v[34:37]
	s_setprio 0
	v_add_u32_e32 v150, 0x4000, v156
	v_readfirstlane_b32 s25, v156
	v_lshl_add_u64 v[148:149], v[6:7], 0, s[30:31]
	s_mov_b32 m0, s25
	v_readfirstlane_b32 s22, v150
	v_add_u32_e32 v150, 0x1000, v156
	s_waitcnt vmcnt(0)
	s_barrier
	global_load_lds_dwordx4 v[148:149], off
	v_lshl_add_u64 v[148:149], v[8:9], 0, s[30:31]
	s_mov_b32 m0, s22
	v_readfirstlane_b32 s23, v150
	v_add_u32_e32 v150, 0x5000, v156
	global_load_lds_dwordx4 v[148:149], off
	v_lshl_add_u64 v[148:149], v[6:7], 0, s[70:71]
	s_mov_b32 m0, s23
	v_readfirstlane_b32 s24, v150
	v_add_u32_e32 v150, 0x2000, v156
	global_load_lds_dwordx4 v[148:149], off
	v_lshl_add_u64 v[148:149], v[26:27], 0, s[30:31]
	s_mov_b32 m0, s24
	v_readfirstlane_b32 s26, v150
	v_add_u32_e32 v150, 0x6000, v156
	global_load_lds_dwordx4 v[148:149], off
	v_lshl_add_u64 v[148:149], v[6:7], 0, s[92:93]
	s_mov_b32 m0, s26
	v_readfirstlane_b32 s27, v150
	global_load_lds_dwordx4 v[148:149], off
	v_lshl_add_u64 v[148:149], v[28:29], 0, s[30:31]
	s_mov_b32 m0, s27
	s_mov_b64 s[28:29], 0x18100
	v_add_u32_e32 v150, 0x3000, v156
	global_load_lds_dwordx4 v[148:149], off
	v_lshl_add_u64 v[148:149], v[6:7], 0, s[28:29]
	v_readfirstlane_b32 s28, v150
	v_add_u32_e32 v150, 0x7000, v156
	s_mov_b32 m0, s28
	v_readfirstlane_b32 s29, v150
	global_load_lds_dwordx4 v[148:149], off
	v_lshl_add_u64 v[148:149], v[50:51], 0, s[30:31]
	s_mov_b32 m0, s29
	s_nop 0
	global_load_lds_dwordx4 v[148:149], off
	ds_read_b128 v[148:151], v0 offset:32768
	ds_read_b128 v[152:155], v0 offset:34816
	ds_read_b128 v[180:183], v0 offset:36864
	ds_read_b128 v[184:187], v0 offset:38912
	ds_read_b128 v[188:191], v145 offset:49152
	ds_read_b128 v[192:195], v145 offset:51200
	ds_read_b128 v[196:199], v145 offset:53248
	ds_read_b128 v[200:203], v145 offset:55296
	ds_read_b128 v[204:207], v146 offset:32768
	ds_read_b128 v[208:211], v146 offset:34816
	ds_read_b128 v[212:215], v146 offset:36864
	ds_read_b128 v[216:219], v146 offset:38912
	ds_read_b128 v[220:223], v147 offset:49152
	ds_read_b128 v[224:227], v147 offset:51200
	ds_read_b128 v[228:231], v147 offset:53248
	ds_read_b128 v[232:235], v147 offset:55296
	s_setprio 1
	s_waitcnt lgkmcnt(0)
	v_mfma_f32_16x16x32_bf16 v[2:5], v[184:187], v[200:203], v[2:5]
	v_mfma_f32_16x16x32_bf16 v[10:13], v[148:151], v[188:191], v[10:13]
	v_mfma_f32_16x16x32_bf16 v[22:25], v[148:151], v[192:195], v[22:25]
	v_mfma_f32_16x16x32_bf16 v[30:33], v[148:151], v[196:199], v[30:33]
	v_mfma_f32_16x16x32_bf16 v[38:41], v[148:151], v[200:203], v[38:41]
	v_mfma_f32_16x16x32_bf16 v[46:49], v[152:155], v[188:191], v[46:49]
	v_mfma_f32_16x16x32_bf16 v[62:65], v[152:155], v[192:195], v[62:65]
	v_mfma_f32_16x16x32_bf16 v[70:73], v[152:155], v[196:199], v[70:73]
	v_mfma_f32_16x16x32_bf16 v[54:57], v[152:155], v[200:203], v[54:57]
	v_mfma_f32_16x16x32_bf16 v[58:61], v[180:183], v[188:191], v[58:61]
	v_mfma_f32_16x16x32_bf16 v[78:81], v[180:183], v[192:195], v[78:81]
	v_mfma_f32_16x16x32_bf16 v[74:77], v[180:183], v[196:199], v[74:77]
	v_mfma_f32_16x16x32_bf16 v[14:17], v[180:183], v[200:203], v[14:17]
	v_mfma_f32_16x16x32_bf16 v[18:21], v[184:187], v[188:191], v[18:21]
	v_mfma_f32_16x16x32_bf16 v[42:45], v[184:187], v[192:195], v[42:45]
	v_mfma_f32_16x16x32_bf16 v[34:37], v[184:187], v[196:199], v[34:37]
	v_mfma_f32_16x16x32_bf16 v[2:5], v[216:219], v[232:235], v[2:5]
	v_mfma_f32_16x16x32_bf16 v[10:13], v[204:207], v[220:223], v[10:13]
	v_mfma_f32_16x16x32_bf16 v[22:25], v[204:207], v[224:227], v[22:25]
	v_mfma_f32_16x16x32_bf16 v[30:33], v[204:207], v[228:231], v[30:33]
	v_mfma_f32_16x16x32_bf16 v[38:41], v[204:207], v[232:235], v[38:41]
	v_mfma_f32_16x16x32_bf16 v[46:49], v[208:211], v[220:223], v[46:49]
	v_mfma_f32_16x16x32_bf16 v[62:65], v[208:211], v[224:227], v[62:65]
	v_mfma_f32_16x16x32_bf16 v[70:73], v[208:211], v[228:231], v[70:73]
	v_mfma_f32_16x16x32_bf16 v[54:57], v[208:211], v[232:235], v[54:57]
	v_mfma_f32_16x16x32_bf16 v[58:61], v[212:215], v[220:223], v[58:61]
	v_mfma_f32_16x16x32_bf16 v[78:81], v[212:215], v[224:227], v[78:81]
	v_mfma_f32_16x16x32_bf16 v[74:77], v[212:215], v[228:231], v[74:77]
	v_mfma_f32_16x16x32_bf16 v[14:17], v[212:215], v[232:235], v[14:17]
	v_mfma_f32_16x16x32_bf16 v[18:21], v[216:219], v[220:223], v[18:21]
	v_mfma_f32_16x16x32_bf16 v[42:45], v[216:219], v[224:227], v[42:45]
	v_mfma_f32_16x16x32_bf16 v[34:37], v[216:219], v[228:231], v[34:37]
	s_setprio 0
	s_mov_b32 m0, s13
	v_lshl_add_u64 v[148:149], v[6:7], 0, s[0:1]
	s_waitcnt vmcnt(0)
	s_barrier
; #define MFMA16(a, b, c) __builtin_amdgcn_mfma_f32_16x16x32_bf16((a), (b), (c), 0, 0, 0)
; DI void gemm_tile(const bf16_t* __restrict__ A, int lda, const bf16_t* __restrict__ Bt, int ldb, int bvalid, int K, f32x4 (&acc)[4][4], char* lds, bool preloaded = false) {
;     ...
;   auto compute = [&](int st) {
;     const char* base = lds + st * 32768;
;     bf16x8 af[2][4], bfr[2][4];
; #pragma unroll
;     for (int s = 0; s < 2; ++s) {
;       const int ch = ((4 * s + fq) ^ fx) << 4;
; #pragma unroll
;       for (int mi = 0; mi < 4; ++mi) af[s][mi] = *(const bf16x8*)(base + (wm * 64 + mi * 16 + fr) * 128 + ch);
; #pragma unroll
;       for (int ni = 0; ni < 4; ++ni) bfr[s][ni] = *(const bf16x8*)(base + 16384 + (wn * 64 + ni * 16 + fr) * 128 + ch);
;     }
;     __builtin_amdgcn_s_setprio(1);
; #pragma unroll
;     for (int s = 0; s < 2; ++s)
; #pragma unroll
;       for (int mi = 0; mi < 4; ++mi)
; #pragma unroll
;         for (int ni = 0; ni < 4; ++ni) acc[mi][ni] = MFMA16(af[s][mi], bfr[s][ni], acc[mi][ni]);
;     __builtin_amdgcn_s_setprio(0);
;   };
;   const int nk = K >> 6;
;   if (!preloaded) { GLDS(0, 0) }
;   __syncthreads();
;   for (int kt = 0; kt < nk; ++kt) {
;     if (kt + 1 < nk) { GLDS((kt + 1) & 1, (kt + 1) << 6) }
;     compute(kt & 1);
;     __syncthreads();
;   }
	global_load_lds_dwordx4 v[148:149], off
	v_lshl_add_u64 v[148:149], v[8:9], 0, s[0:1]
	s_mov_b32 m0, s12
	s_mov_b64 s[30:31], 0x8180
	global_load_lds_dwordx4 v[148:149], off
	v_lshl_add_u64 v[148:149], v[6:7], 0, s[30:31]
	s_mov_b32 m0, s21
	s_mov_b64 s[30:31], 0x10180
	global_load_lds_dwordx4 v[148:149], off
	v_lshl_add_u64 v[148:149], v[26:27], 0, s[0:1]
	s_mov_b32 m0, s5
	s_nop 0
	global_load_lds_dwordx4 v[148:149], off
	v_lshl_add_u64 v[148:149], v[6:7], 0, s[30:31]
	s_mov_b32 m0, s8
	s_mov_b64 s[30:31], 0x18180
	global_load_lds_dwordx4 v[148:149], off
	v_lshl_add_u64 v[148:149], v[28:29], 0, s[0:1]
	s_mov_b32 m0, s9
	s_nop 0
	global_load_lds_dwordx4 v[148:149], off
	v_lshl_add_u64 v[148:149], v[6:7], 0, s[30:31]
	s_mov_b32 m0, s10
	s_nop 0
	global_load_lds_dwordx4 v[148:149], off
	v_lshl_add_u64 v[148:149], v[50:51], 0, s[0:1]
	s_mov_b32 m0, s11
	s_nop 0
	global_load_lds_dwordx4 v[148:149], off
	ds_read_b128 v[148:151], v0
	ds_read_b128 v[152:155], v0 offset:2048
	ds_read_b128 v[180:183], v0 offset:4096
	ds_read_b128 v[184:187], v0 offset:6144
	ds_read_b128 v[188:191], v145 offset:16384
	ds_read_b128 v[192:195], v145 offset:18432
	ds_read_b128 v[196:199], v145 offset:20480
	ds_read_b128 v[200:203], v145 offset:22528
	ds_read_b128 v[204:207], v146
	ds_read_b128 v[208:211], v146 offset:2048
	ds_read_b128 v[212:215], v146 offset:4096
	ds_read_b128 v[216:219], v146 offset:6144
	ds_read_b128 v[220:223], v147 offset:16384
	ds_read_b128 v[224:227], v147 offset:18432
	ds_read_b128 v[228:231], v147 offset:20480
	ds_read_b128 v[232:235], v147 offset:22528
	s_setprio 1
	s_waitcnt lgkmcnt(0)
	v_mfma_f32_16x16x32_bf16 v[2:5], v[184:187], v[200:203], v[2:5]
	v_mfma_f32_16x16x32_bf16 v[10:13], v[148:151], v[188:191], v[10:13]
	v_mfma_f32_16x16x32_bf16 v[22:25], v[148:151], v[192:195], v[22:25]
	v_mfma_f32_16x16x32_bf16 v[30:33], v[148:151], v[196:199], v[30:33]
	v_mfma_f32_16x16x32_bf16 v[38:41], v[148:151], v[200:203], v[38:41]
	v_mfma_f32_16x16x32_bf16 v[46:49], v[152:155], v[188:191], v[46:49]
	v_mfma_f32_16x16x32_bf16 v[62:65], v[152:155], v[192:195], v[62:65]
	v_mfma_f32_16x16x32_bf16 v[70:73], v[152:155], v[196:199], v[70:73]
	v_mfma_f32_16x16x32_bf16 v[54:57], v[152:155], v[200:203], v[54:57]
	v_mfma_f32_16x16x32_bf16 v[58:61], v[180:183], v[188:191], v[58:61]
	v_mfma_f32_16x16x32_bf16 v[78:81], v[180:183], v[192:195], v[78:81]
	v_mfma_f32_16x16x32_bf16 v[74:77], v[180:183], v[196:199], v[74:77]
	v_mfma_f32_16x16x32_bf16 v[14:17], v[180:183], v[200:203], v[14:17]
	v_mfma_f32_16x16x32_bf16 v[18:21], v[184:187], v[188:191], v[18:21]
	v_mfma_f32_16x16x32_bf16 v[42:45], v[184:187], v[192:195], v[42:45]
	v_mfma_f32_16x16x32_bf16 v[34:37], v[184:187], v[196:199], v[34:37]
	v_mfma_f32_16x16x32_bf16 v[2:5], v[216:219], v[232:235], v[2:5]
	v_mfma_f32_16x16x32_bf16 v[10:13], v[204:207], v[220:223], v[10:13]
	v_mfma_f32_16x16x32_bf16 v[22:25], v[204:207], v[224:227], v[22:25]
	v_mfma_f32_16x16x32_bf16 v[30:33], v[204:207], v[228:231], v[30:33]
	v_mfma_f32_16x16x32_bf16 v[38:41], v[204:207], v[232:235], v[38:41]
	v_mfma_f32_16x16x32_bf16 v[46:49], v[208:211], v[220:223], v[46:49]
	v_mfma_f32_16x16x32_bf16 v[62:65], v[208:211], v[224:227], v[62:65]
	v_mfma_f32_16x16x32_bf16 v[70:73], v[208:211], v[228:231], v[70:73]
	v_mfma_f32_16x16x32_bf16 v[54:57], v[208:211], v[232:235], v[54:57]
	v_mfma_f32_16x16x32_bf16 v[58:61], v[212:215], v[220:223], v[58:61]
	v_mfma_f32_16x16x32_bf16 v[78:81], v[212:215], v[224:227], v[78:81]
	v_mfma_f32_16x16x32_bf16 v[74:77], v[212:215], v[228:231], v[74:77]
	v_mfma_f32_16x16x32_bf16 v[14:17], v[212:215], v[232:235], v[14:17]
	v_mfma_f32_16x16x32_bf16 v[18:21], v[216:219], v[220:223], v[18:21]
	v_mfma_f32_16x16x32_bf16 v[42:45], v[216:219], v[224:227], v[42:45]
	v_mfma_f32_16x16x32_bf16 v[34:37], v[216:219], v[228:231], v[34:37]
	s_setprio 0
	s_mov_b32 m0, s25
	v_lshl_add_u64 v[148:149], v[6:7], 0, s[36:37]
	s_waitcnt vmcnt(0)
	s_barrier
	global_load_lds_dwordx4 v[148:149], off
	v_lshl_add_u64 v[148:149], v[8:9], 0, s[36:37]
	s_mov_b32 m0, s22
	s_mov_b64 s[0:1], 0x8200
	global_load_lds_dwordx4 v[148:149], off
	v_lshl_add_u64 v[148:149], v[6:7], 0, s[0:1]
	s_mov_b32 m0, s23
	s_mov_b64 s[0:1], 0x10200
	global_load_lds_dwordx4 v[148:149], off
	v_lshl_add_u64 v[148:149], v[26:27], 0, s[36:37]
	s_mov_b32 m0, s24
	s_nop 0
	global_load_lds_dwordx4 v[148:149], off
	v_lshl_add_u64 v[148:149], v[6:7], 0, s[0:1]
	s_mov_b32 m0, s26
	s_mov_b64 s[0:1], 0x18200
	global_load_lds_dwordx4 v[148:149], off
	v_lshl_add_u64 v[148:149], v[28:29], 0, s[36:37]
	s_mov_b32 m0, s27
	s_nop 0
	global_load_lds_dwordx4 v[148:149], off
	v_lshl_add_u64 v[148:149], v[6:7], 0, s[0:1]
	s_mov_b32 m0, s28
	s_nop 0
	global_load_lds_dwordx4 v[148:149], off
	v_lshl_add_u64 v[148:149], v[50:51], 0, s[36:37]
	s_mov_b32 m0, s29
	s_nop 0
	global_load_lds_dwordx4 v[148:149], off
	ds_read_b128 v[148:151], v0 offset:32768
	ds_read_b128 v[152:155], v0 offset:34816
	ds_read_b128 v[180:183], v0 offset:36864
	ds_read_b128 v[184:187], v0 offset:38912
	ds_read_b128 v[188:191], v145 offset:49152
	ds_read_b128 v[192:195], v145 offset:51200
	ds_read_b128 v[196:199], v145 offset:53248
	ds_read_b128 v[200:203], v145 offset:55296
	ds_read_b128 v[204:207], v146 offset:32768
	ds_read_b128 v[208:211], v146 offset:34816
	ds_read_b128 v[212:215], v146 offset:36864
	ds_read_b128 v[216:219], v146 offset:38912
	ds_read_b128 v[220:223], v147 offset:49152
	ds_read_b128 v[224:227], v147 offset:51200
	ds_read_b128 v[228:231], v147 offset:53248
	ds_read_b128 v[232:235], v147 offset:55296
	s_setprio 1
	s_waitcnt lgkmcnt(0)
; #define MFMA16(a, b, c) __builtin_amdgcn_mfma_f32_16x16x32_bf16((a), (b), (c), 0, 0, 0)
; DI void gemm_tile(const bf16_t* __restrict__ A, int lda, const bf16_t* __restrict__ Bt, int ldb, int bvalid, int K, f32x4 (&acc)[4][4], char* lds, bool preloaded = false) {
;     ...
;   auto compute = [&](int st) {
;     const char* base = lds + st * 32768;
;     bf16x8 af[2][4], bfr[2][4];
; #pragma unroll
;     for (int s = 0; s < 2; ++s) {
;       const int ch = ((4 * s + fq) ^ fx) << 4;
; #pragma unroll
;       for (int mi = 0; mi < 4; ++mi) af[s][mi] = *(const bf16x8*)(base + (wm * 64 + mi * 16 + fr) * 128 + ch);
; #pragma unroll
;       for (int ni = 0; ni < 4; ++ni) bfr[s][ni] = *(const bf16x8*)(base + 16384 + (wn * 64 + ni * 16 + fr) * 128 + ch);
;     }
;     __builtin_amdgcn_s_setprio(1);
; #pragma unroll
;     for (int s = 0; s < 2; ++s)
; #pragma unroll
;       for (int mi = 0; mi < 4; ++mi)
; #pragma unroll
;         for (int ni = 0; ni < 4; ++ni) acc[mi][ni] = MFMA16(af[s][mi], bfr[s][ni], acc[mi][ni]);
;     __builtin_amdgcn_s_setprio(0);
;   };
;   const int nk = K >> 6;
;   if (!preloaded) { GLDS(0, 0) }
;   __syncthreads();
;   for (int kt = 0; kt < nk; ++kt) {
;     if (kt + 1 < nk) { GLDS((kt + 1) & 1, (kt + 1) << 6) }
;     compute(kt & 1);
;     __syncthreads();
;   }
	v_mfma_f32_16x16x32_bf16 v[2:5], v[184:187], v[200:203], v[2:5]
	v_mfma_f32_16x16x32_bf16 v[10:13], v[148:151], v[188:191], v[10:13]
	v_mfma_f32_16x16x32_bf16 v[22:25], v[148:151], v[192:195], v[22:25]
	v_mfma_f32_16x16x32_bf16 v[30:33], v[148:151], v[196:199], v[30:33]
	v_mfma_f32_16x16x32_bf16 v[38:41], v[148:151], v[200:203], v[38:41]
	v_mfma_f32_16x16x32_bf16 v[46:49], v[152:155], v[188:191], v[46:49]
	v_mfma_f32_16x16x32_bf16 v[62:65], v[152:155], v[192:195], v[62:65]
	v_mfma_f32_16x16x32_bf16 v[70:73], v[152:155], v[196:199], v[70:73]
	v_mfma_f32_16x16x32_bf16 v[54:57], v[152:155], v[200:203], v[54:57]
	v_mfma_f32_16x16x32_bf16 v[58:61], v[180:183], v[188:191], v[58:61]
	v_mfma_f32_16x16x32_bf16 v[78:81], v[180:183], v[192:195], v[78:81]
	v_mfma_f32_16x16x32_bf16 v[74:77], v[180:183], v[196:199], v[74:77]
	v_mfma_f32_16x16x32_bf16 v[14:17], v[180:183], v[200:203], v[14:17]
	v_mfma_f32_16x16x32_bf16 v[18:21], v[184:187], v[188:191], v[18:21]
	v_mfma_f32_16x16x32_bf16 v[42:45], v[184:187], v[192:195], v[42:45]
	v_mfma_f32_16x16x32_bf16 v[34:37], v[184:187], v[196:199], v[34:37]
	v_mfma_f32_16x16x32_bf16 v[2:5], v[216:219], v[232:235], v[2:5]
	v_mfma_f32_16x16x32_bf16 v[10:13], v[204:207], v[220:223], v[10:13]
	v_mfma_f32_16x16x32_bf16 v[22:25], v[204:207], v[224:227], v[22:25]
	v_mfma_f32_16x16x32_bf16 v[30:33], v[204:207], v[228:231], v[30:33]
	v_mfma_f32_16x16x32_bf16 v[38:41], v[204:207], v[232:235], v[38:41]
	v_mfma_f32_16x16x32_bf16 v[46:49], v[208:211], v[220:223], v[46:49]
	v_mfma_f32_16x16x32_bf16 v[62:65], v[208:211], v[224:227], v[62:65]
	v_mfma_f32_16x16x32_bf16 v[70:73], v[208:211], v[228:231], v[70:73]
	v_mfma_f32_16x16x32_bf16 v[54:57], v[208:211], v[232:235], v[54:57]
	v_mfma_f32_16x16x32_bf16 v[58:61], v[212:215], v[220:223], v[58:61]
	v_mfma_f32_16x16x32_bf16 v[78:81], v[212:215], v[224:227], v[78:81]
	v_mfma_f32_16x16x32_bf16 v[74:77], v[212:215], v[228:231], v[74:77]
	v_mfma_f32_16x16x32_bf16 v[14:17], v[212:215], v[232:235], v[14:17]
	v_mfma_f32_16x16x32_bf16 v[18:21], v[216:219], v[220:223], v[18:21]
	v_mfma_f32_16x16x32_bf16 v[42:45], v[216:219], v[224:227], v[42:45]
	v_mfma_f32_16x16x32_bf16 v[34:37], v[216:219], v[228:231], v[34:37]
	s_setprio 0
	s_mov_b32 m0, s13
	v_lshl_add_u64 v[148:149], v[6:7], 0, s[2:3]
	s_waitcnt vmcnt(0)
	s_barrier
	global_load_lds_dwordx4 v[148:149], off
	v_lshl_add_u64 v[148:149], v[8:9], 0, s[2:3]
	s_mov_b32 m0, s12
	s_mov_b64 s[0:1], 0x8280
	global_load_lds_dwordx4 v[148:149], off
	v_lshl_add_u64 v[148:149], v[6:7], 0, s[0:1]
	s_mov_b32 m0, s21
	s_mov_b64 s[0:1], 0x10280
	global_load_lds_dwordx4 v[148:149], off
	v_lshl_add_u64 v[148:149], v[26:27], 0, s[2:3]
	s_mov_b32 m0, s5
	s_nop 0
	global_load_lds_dwordx4 v[148:149], off
	v_lshl_add_u64 v[148:149], v[6:7], 0, s[0:1]
	s_mov_b32 m0, s8
	s_mov_b64 s[0:1], 0x18280
	global_load_lds_dwordx4 v[148:149], off
	v_lshl_add_u64 v[148:149], v[28:29], 0, s[2:3]
	s_mov_b32 m0, s9
	s_nop 0
	global_load_lds_dwordx4 v[148:149], off
	v_lshl_add_u64 v[148:149], v[6:7], 0, s[0:1]
	s_mov_b32 m0, s10
	s_nop 0
	global_load_lds_dwordx4 v[148:149], off
	v_lshl_add_u64 v[148:149], v[50:51], 0, s[2:3]
	s_mov_b32 m0, s11
	s_nop 0
	global_load_lds_dwordx4 v[148:149], off
	ds_read_b128 v[148:151], v0
	ds_read_b128 v[152:155], v0 offset:2048
	ds_read_b128 v[180:183], v0 offset:4096
	ds_read_b128 v[184:187], v0 offset:6144
	ds_read_b128 v[188:191], v145 offset:16384
	ds_read_b128 v[192:195], v145 offset:18432
	ds_read_b128 v[196:199], v145 offset:20480
	ds_read_b128 v[200:203], v145 offset:22528
	ds_read_b128 v[204:207], v146
	ds_read_b128 v[208:211], v146 offset:2048
	ds_read_b128 v[212:215], v146 offset:4096
	ds_read_b128 v[216:219], v146 offset:6144
	ds_read_b128 v[220:223], v147 offset:16384
	ds_read_b128 v[224:227], v147 offset:18432
	ds_read_b128 v[228:231], v147 offset:20480
	ds_read_b128 v[232:235], v147 offset:22528
	s_setprio 1
	s_waitcnt lgkmcnt(0)
	v_mfma_f32_16x16x32_bf16 v[2:5], v[184:187], v[200:203], v[2:5]
	v_mfma_f32_16x16x32_bf16 v[10:13], v[148:151], v[188:191], v[10:13]
	v_mfma_f32_16x16x32_bf16 v[22:25], v[148:151], v[192:195], v[22:25]
	v_mfma_f32_16x16x32_bf16 v[30:33], v[148:151], v[196:199], v[30:33]
	v_mfma_f32_16x16x32_bf16 v[38:41], v[148:151], v[200:203], v[38:41]
	v_mfma_f32_16x16x32_bf16 v[46:49], v[152:155], v[188:191], v[46:49]
	v_mfma_f32_16x16x32_bf16 v[62:65], v[152:155], v[192:195], v[62:65]
	v_mfma_f32_16x16x32_bf16 v[70:73], v[152:155], v[196:199], v[70:73]
	v_mfma_f32_16x16x32_bf16 v[54:57], v[152:155], v[200:203], v[54:57]
	v_mfma_f32_16x16x32_bf16 v[58:61], v[180:183], v[188:191], v[58:61]
	v_mfma_f32_16x16x32_bf16 v[78:81], v[180:183], v[192:195], v[78:81]
	v_mfma_f32_16x16x32_bf16 v[74:77], v[180:183], v[196:199], v[74:77]
	v_mfma_f32_16x16x32_bf16 v[14:17], v[180:183], v[200:203], v[14:17]
	v_mfma_f32_16x16x32_bf16 v[18:21], v[184:187], v[188:191], v[18:21]
	v_mfma_f32_16x16x32_bf16 v[42:45], v[184:187], v[192:195], v[42:45]
	v_mfma_f32_16x16x32_bf16 v[34:37], v[184:187], v[196:199], v[34:37]
	v_mfma_f32_16x16x32_bf16 v[2:5], v[216:219], v[232:235], v[2:5]
	v_mfma_f32_16x16x32_bf16 v[10:13], v[204:207], v[220:223], v[10:13]
	v_mfma_f32_16x16x32_bf16 v[22:25], v[204:207], v[224:227], v[22:25]
	v_mfma_f32_16x16x32_bf16 v[30:33], v[204:207], v[228:231], v[30:33]
	v_mfma_f32_16x16x32_bf16 v[38:41], v[204:207], v[232:235], v[38:41]
	v_mfma_f32_16x16x32_bf16 v[46:49], v[208:211], v[220:223], v[46:49]
	v_mfma_f32_16x16x32_bf16 v[62:65], v[208:211], v[224:227], v[62:65]
	v_mfma_f32_16x16x32_bf16 v[70:73], v[208:211], v[228:231], v[70:73]
	v_mfma_f32_16x16x32_bf16 v[54:57], v[208:211], v[232:235], v[54:57]
	v_mfma_f32_16x16x32_bf16 v[58:61], v[212:215], v[220:223], v[58:61]
	v_mfma_f32_16x16x32_bf16 v[78:81], v[212:215], v[224:227], v[78:81]
	v_mfma_f32_16x16x32_bf16 v[74:77], v[212:215], v[228:231], v[74:77]
	v_mfma_f32_16x16x32_bf16 v[14:17], v[212:215], v[232:235], v[14:17]
	v_mfma_f32_16x16x32_bf16 v[18:21], v[216:219], v[220:223], v[18:21]
	v_mfma_f32_16x16x32_bf16 v[42:45], v[216:219], v[224:227], v[42:45]
	v_mfma_f32_16x16x32_bf16 v[34:37], v[216:219], v[228:231], v[34:37]
	s_setprio 0
	s_mov_b32 m0, s25
	v_lshl_add_u64 v[148:149], v[6:7], 0, s[14:15]
	s_waitcnt vmcnt(0)
	s_barrier
; #define MFMA16(a, b, c) __builtin_amdgcn_mfma_f32_16x16x32_bf16((a), (b), (c), 0, 0, 0)
; DI void gemm_tile(const bf16_t* __restrict__ A, int lda, const bf16_t* __restrict__ Bt, int ldb, int bvalid, int K, f32x4 (&acc)[4][4], char* lds, bool preloaded = false) {
;     ...
;   auto compute = [&](int st) {
;     const char* base = lds + st * 32768;
;     bf16x8 af[2][4], bfr[2][4];
; #pragma unroll
;     for (int s = 0; s < 2; ++s) {
;       const int ch = ((4 * s + fq) ^ fx) << 4;
; #pragma unroll
;       for (int mi = 0; mi < 4; ++mi) af[s][mi] = *(const bf16x8*)(base + (wm * 64 + mi * 16 + fr) * 128 + ch);
; #pragma unroll
;       for (int ni = 0; ni < 4; ++ni) bfr[s][ni] = *(const bf16x8*)(base + 16384 + (wn * 64 + ni * 16 + fr) * 128 + ch);
;     }
;     __builtin_amdgcn_s_setprio(1);
; #pragma unroll
;     for (int s = 0; s < 2; ++s)
; #pragma unroll
;       for (int mi = 0; mi < 4; ++mi)
; #pragma unroll
;         for (int ni = 0; ni < 4; ++ni) acc[mi][ni] = MFMA16(af[s][mi], bfr[s][ni], acc[mi][ni]);
;     __builtin_amdgcn_s_setprio(0);
;   };
;   const int nk = K >> 6;
;   if (!preloaded) { GLDS(0, 0) }
;   __syncthreads();
;   for (int kt = 0; kt < nk; ++kt) {
;     if (kt + 1 < nk) { GLDS((kt + 1) & 1, (kt + 1) << 6) }
;     compute(kt & 1);
;     __syncthreads();
;   }
	global_load_lds_dwordx4 v[148:149], off
	v_lshl_add_u64 v[148:149], v[8:9], 0, s[14:15]
	s_mov_b32 m0, s22
	s_mov_b64 s[0:1], 0x8300
	global_load_lds_dwordx4 v[148:149], off
	v_lshl_add_u64 v[148:149], v[6:7], 0, s[0:1]
	s_mov_b32 m0, s23
	s_mov_b64 s[0:1], 0x10300
	global_load_lds_dwordx4 v[148:149], off
	v_lshl_add_u64 v[148:149], v[26:27], 0, s[14:15]
	s_mov_b32 m0, s24
	s_nop 0
	global_load_lds_dwordx4 v[148:149], off
	v_lshl_add_u64 v[148:149], v[6:7], 0, s[0:1]
	s_mov_b32 m0, s26
	s_mov_b64 s[0:1], 0x18300
	global_load_lds_dwordx4 v[148:149], off
	v_lshl_add_u64 v[148:149], v[28:29], 0, s[14:15]
	s_mov_b32 m0, s27
	s_nop 0
	global_load_lds_dwordx4 v[148:149], off
	v_lshl_add_u64 v[148:149], v[6:7], 0, s[0:1]
	s_mov_b32 m0, s28
	s_nop 0
	global_load_lds_dwordx4 v[148:149], off
	v_lshl_add_u64 v[148:149], v[50:51], 0, s[14:15]
	s_mov_b32 m0, s29
	s_nop 0
	global_load_lds_dwordx4 v[148:149], off
	ds_read_b128 v[148:151], v0 offset:32768
	ds_read_b128 v[152:155], v0 offset:34816
	ds_read_b128 v[180:183], v0 offset:36864
	ds_read_b128 v[184:187], v0 offset:38912
	ds_read_b128 v[188:191], v145 offset:49152
	ds_read_b128 v[192:195], v145 offset:51200
	ds_read_b128 v[196:199], v145 offset:53248
	ds_read_b128 v[200:203], v145 offset:55296
	ds_read_b128 v[204:207], v146 offset:32768
	ds_read_b128 v[208:211], v146 offset:34816
	ds_read_b128 v[212:215], v146 offset:36864
	ds_read_b128 v[216:219], v146 offset:38912
	ds_read_b128 v[220:223], v147 offset:49152
	ds_read_b128 v[224:227], v147 offset:51200
	ds_read_b128 v[228:231], v147 offset:53248
	ds_read_b128 v[232:235], v147 offset:55296
	s_setprio 1
	s_waitcnt lgkmcnt(0)
	v_mfma_f32_16x16x32_bf16 v[2:5], v[184:187], v[200:203], v[2:5]
	v_mfma_f32_16x16x32_bf16 v[10:13], v[148:151], v[188:191], v[10:13]
	v_mfma_f32_16x16x32_bf16 v[22:25], v[148:151], v[192:195], v[22:25]
	v_mfma_f32_16x16x32_bf16 v[30:33], v[148:151], v[196:199], v[30:33]
	v_mfma_f32_16x16x32_bf16 v[38:41], v[148:151], v[200:203], v[38:41]
	v_mfma_f32_16x16x32_bf16 v[46:49], v[152:155], v[188:191], v[46:49]
	v_mfma_f32_16x16x32_bf16 v[62:65], v[152:155], v[192:195], v[62:65]
	v_mfma_f32_16x16x32_bf16 v[70:73], v[152:155], v[196:199], v[70:73]
	v_mfma_f32_16x16x32_bf16 v[54:57], v[152:155], v[200:203], v[54:57]
	v_mfma_f32_16x16x32_bf16 v[58:61], v[180:183], v[188:191], v[58:61]
	v_mfma_f32_16x16x32_bf16 v[78:81], v[180:183], v[192:195], v[78:81]
	v_mfma_f32_16x16x32_bf16 v[74:77], v[180:183], v[196:199], v[74:77]
	v_mfma_f32_16x16x32_bf16 v[14:17], v[180:183], v[200:203], v[14:17]
	v_mfma_f32_16x16x32_bf16 v[18:21], v[184:187], v[188:191], v[18:21]
	v_mfma_f32_16x16x32_bf16 v[42:45], v[184:187], v[192:195], v[42:45]
	v_mfma_f32_16x16x32_bf16 v[34:37], v[184:187], v[196:199], v[34:37]
	v_mfma_f32_16x16x32_bf16 v[2:5], v[216:219], v[232:235], v[2:5]
	v_mfma_f32_16x16x32_bf16 v[10:13], v[204:207], v[220:223], v[10:13]
	v_mfma_f32_16x16x32_bf16 v[22:25], v[204:207], v[224:227], v[22:25]
	v_mfma_f32_16x16x32_bf16 v[30:33], v[204:207], v[228:231], v[30:33]
	v_mfma_f32_16x16x32_bf16 v[38:41], v[204:207], v[232:235], v[38:41]
	v_mfma_f32_16x16x32_bf16 v[46:49], v[208:211], v[220:223], v[46:49]
	v_mfma_f32_16x16x32_bf16 v[62:65], v[208:211], v[224:227], v[62:65]
	v_mfma_f32_16x16x32_bf16 v[70:73], v[208:211], v[228:231], v[70:73]
	v_mfma_f32_16x16x32_bf16 v[54:57], v[208:211], v[232:235], v[54:57]
	v_mfma_f32_16x16x32_bf16 v[58:61], v[212:215], v[220:223], v[58:61]
	v_mfma_f32_16x16x32_bf16 v[78:81], v[212:215], v[224:227], v[78:81]
	v_mfma_f32_16x16x32_bf16 v[74:77], v[212:215], v[228:231], v[74:77]
	v_mfma_f32_16x16x32_bf16 v[14:17], v[212:215], v[232:235], v[14:17]
	v_mfma_f32_16x16x32_bf16 v[18:21], v[216:219], v[220:223], v[18:21]
	v_mfma_f32_16x16x32_bf16 v[42:45], v[216:219], v[224:227], v[42:45]
	v_mfma_f32_16x16x32_bf16 v[34:37], v[216:219], v[228:231], v[34:37]
	s_setprio 0
	v_readfirstlane_b32 s12, v143
	v_lshl_add_u64 v[148:149], v[6:7], 0, s[64:65]
	s_mov_b32 m0, s12
	v_readfirstlane_b32 s12, v142
	s_waitcnt vmcnt(0)
	s_barrier
	global_load_lds_dwordx4 v[148:149], off
	v_lshl_add_u64 v[8:9], v[8:9], 0, s[64:65]
	s_mov_b32 m0, s12
	s_mov_b64 s[0:1], 0x8380
	v_readfirstlane_b32 s12, v144
	global_load_lds_dwordx4 v[8:9], off
	v_lshl_add_u64 v[8:9], v[6:7], 0, s[0:1]
	s_mov_b32 m0, s12
	s_mov_b64 s[0:1], 0x10380
	global_load_lds_dwordx4 v[8:9], off
	v_lshl_add_u64 v[8:9], v[26:27], 0, s[64:65]
	s_mov_b32 m0, s5
	s_nop 0
	global_load_lds_dwordx4 v[8:9], off
	v_lshl_add_u64 v[8:9], v[6:7], 0, s[0:1]
	s_mov_b32 m0, s8
	s_mov_b64 s[0:1], 0x18380
	global_load_lds_dwordx4 v[8:9], off
	v_lshl_add_u64 v[8:9], v[28:29], 0, s[64:65]
	s_mov_b32 m0, s9
	v_lshl_add_u64 v[6:7], v[6:7], 0, s[0:1]
	global_load_lds_dwordx4 v[8:9], off
	s_mov_b32 m0, s10
	s_nop 0
	global_load_lds_dwordx4 v[6:7], off
	v_lshl_add_u64 v[6:7], v[50:51], 0, s[64:65]
	s_mov_b32 m0, s11
	s_nop 0
	global_load_lds_dwordx4 v[6:7], off
	ds_read_b128 v[6:9], v0
	ds_read_b128 v[26:29], v0 offset:2048
	ds_read_b128 v[148:151], v0 offset:4096
	ds_read_b128 v[152:155], v0 offset:6144
	ds_read_b128 v[180:183], v145 offset:16384
	ds_read_b128 v[184:187], v145 offset:18432
	ds_read_b128 v[188:191], v145 offset:20480
	ds_read_b128 v[192:195], v145 offset:22528
	ds_read_b128 v[196:199], v146
	ds_read_b128 v[200:203], v146 offset:2048
	ds_read_b128 v[204:207], v146 offset:4096
	ds_read_b128 v[208:211], v146 offset:6144
	ds_read_b128 v[212:215], v147 offset:16384
	ds_read_b128 v[216:219], v147 offset:18432
	ds_read_b128 v[220:223], v147 offset:20480
	ds_read_b128 v[224:227], v147 offset:22528
	s_setprio 1
	s_waitcnt lgkmcnt(0)
; #define MFMA16(a, b, c) __builtin_amdgcn_mfma_f32_16x16x32_bf16((a), (b), (c), 0, 0, 0)
; DI void gemm_tile(const bf16_t* __restrict__ A, int lda, const bf16_t* __restrict__ Bt, int ldb, int bvalid, int K, f32x4 (&acc)[4][4], char* lds, bool preloaded = false) {
;     ...
;   auto compute = [&](int st) {
;     const char* base = lds + st * 32768;
;     bf16x8 af[2][4], bfr[2][4];
; #pragma unroll
;     for (int s = 0; s < 2; ++s) {
;       const int ch = ((4 * s + fq) ^ fx) << 4;
; #pragma unroll
;       for (int mi = 0; mi < 4; ++mi) af[s][mi] = *(const bf16x8*)(base + (wm * 64 + mi * 16 + fr) * 128 + ch);
; #pragma unroll
;       for (int ni = 0; ni < 4; ++ni) bfr[s][ni] = *(const bf16x8*)(base + 16384 + (wn * 64 + ni * 16 + fr) * 128 + ch);
;     }
;     __builtin_amdgcn_s_setprio(1);
; #pragma unroll
;     for (int s = 0; s < 2; ++s)
; #pragma unroll
;       for (int mi = 0; mi < 4; ++mi)
; #pragma unroll
;         for (int ni = 0; ni < 4; ++ni) acc[mi][ni] = MFMA16(af[s][mi], bfr[s][ni], acc[mi][ni]);
;     __builtin_amdgcn_s_setprio(0);
;   };
;   const int nk = K >> 6;
;   if (!preloaded) { GLDS(0, 0) }
;   __syncthreads();
;   for (int kt = 0; kt < nk; ++kt) {
;     if (kt + 1 < nk) { GLDS((kt + 1) & 1, (kt + 1) << 6) }
;     compute(kt & 1);
;     __syncthreads();
;   }
; DI void phaseD_tile(const P& p, int layer, int mt, int nt, char* lds) {
;     ...
; #pragma unroll
;   for (int mi = 0; mi < 4; ++mi)
; #pragma unroll
;     for (int ni = 0; ni < 4; ++ni)
; #pragma unroll
;       for (int j = 0; j < 4; ++j) acc[mi][ni][j] *= fmaxf((float)((gav[mi][ni] >> (8 * j)) & 255u), 1.f) * (1.f / 255.f);
	v_mfma_f32_16x16x32_bf16 v[2:5], v[152:155], v[192:195], v[2:5]
	v_mfma_f32_16x16x32_bf16 v[10:13], v[6:9], v[180:183], v[10:13]
	v_mfma_f32_16x16x32_bf16 v[22:25], v[6:9], v[184:187], v[22:25]
	v_mfma_f32_16x16x32_bf16 v[30:33], v[6:9], v[188:191], v[30:33]
	v_mfma_f32_16x16x32_bf16 v[6:9], v[6:9], v[192:195], v[38:41]
	v_mfma_f32_16x16x32_bf16 v[38:41], v[26:29], v[180:183], v[46:49]
	v_mfma_f32_16x16x32_bf16 v[46:49], v[26:29], v[184:187], v[62:65]
	v_mfma_f32_16x16x32_bf16 v[62:65], v[26:29], v[188:191], v[70:73]
	v_mfma_f32_16x16x32_bf16 v[26:29], v[26:29], v[192:195], v[54:57]
	v_mfma_f32_16x16x32_bf16 v[54:57], v[148:151], v[180:183], v[58:61]
	v_mfma_f32_16x16x32_bf16 v[58:61], v[148:151], v[184:187], v[78:81]
	v_mfma_f32_16x16x32_bf16 v[70:73], v[148:151], v[188:191], v[74:77]
	v_mfma_f32_16x16x32_bf16 v[14:17], v[148:151], v[192:195], v[14:17]
	v_mfma_f32_16x16x32_bf16 v[18:21], v[152:155], v[180:183], v[18:21]
	v_mfma_f32_16x16x32_bf16 v[42:45], v[152:155], v[184:187], v[42:45]
	v_mfma_f32_16x16x32_bf16 v[34:37], v[152:155], v[188:191], v[34:37]
	v_mfma_f32_16x16x32_bf16 v[2:5], v[208:211], v[224:227], v[2:5]
	v_mfma_f32_16x16x32_bf16 v[10:13], v[196:199], v[212:215], v[10:13]
	v_mfma_f32_16x16x32_bf16 v[22:25], v[196:199], v[216:219], v[22:25]
	v_mfma_f32_16x16x32_bf16 v[30:33], v[196:199], v[220:223], v[30:33]
	v_mfma_f32_16x16x32_bf16 v[6:9], v[196:199], v[224:227], v[6:9]
	v_mfma_f32_16x16x32_bf16 v[38:41], v[200:203], v[212:215], v[38:41]
	v_mfma_f32_16x16x32_bf16 v[46:49], v[200:203], v[216:219], v[46:49]
	v_mfma_f32_16x16x32_bf16 v[62:65], v[200:203], v[220:223], v[62:65]
	v_mfma_f32_16x16x32_bf16 v[26:29], v[200:203], v[224:227], v[26:29]
	v_mfma_f32_16x16x32_bf16 v[54:57], v[204:207], v[212:215], v[54:57]
	v_mfma_f32_16x16x32_bf16 v[58:61], v[204:207], v[216:219], v[58:61]
	v_mfma_f32_16x16x32_bf16 v[70:73], v[204:207], v[220:223], v[70:73]
	v_mfma_f32_16x16x32_bf16 v[14:17], v[204:207], v[224:227], v[14:17]
	v_mfma_f32_16x16x32_bf16 v[18:21], v[208:211], v[212:215], v[18:21]
	v_mfma_f32_16x16x32_bf16 v[42:45], v[208:211], v[216:219], v[42:45]
	v_mfma_f32_16x16x32_bf16 v[34:37], v[208:211], v[220:223], v[34:37]
	s_setprio 0
	s_waitcnt vmcnt(0)
	s_barrier
	ds_read_b128 v[74:77], v0 offset:32768
	ds_read_b128 v[78:81], v0 offset:34816
	ds_read_b128 v[148:151], v0 offset:36864
	ds_read_b128 v[152:155], v0 offset:38912
	ds_read_b128 v[180:183], v145 offset:49152
	ds_read_b128 v[184:187], v145 offset:51200
	ds_read_b128 v[188:191], v145 offset:53248
	ds_read_b128 v[142:145], v145 offset:55296
	ds_read_b128 v[192:195], v146 offset:32768
	ds_read_b128 v[196:199], v146 offset:34816
	ds_read_b128 v[200:203], v146 offset:36864
	ds_read_b128 v[204:207], v146 offset:38912
	ds_read_b128 v[208:211], v147 offset:49152
	ds_read_b128 v[212:215], v147 offset:51200
	ds_read_b128 v[216:219], v147 offset:53248
	ds_read_b128 v[220:223], v147 offset:55296
	s_setprio 1
	s_waitcnt lgkmcnt(8)
	v_mfma_f32_16x16x32_bf16 v[2:5], v[152:155], v[142:145], v[2:5]
	v_mfma_f32_16x16x32_bf16 v[10:13], v[74:77], v[180:183], v[10:13]
	v_mfma_f32_16x16x32_bf16 v[22:25], v[74:77], v[184:187], v[22:25]
	v_mfma_f32_16x16x32_bf16 v[30:33], v[74:77], v[188:191], v[30:33]
	v_mfma_f32_16x16x32_bf16 v[6:9], v[74:77], v[142:145], v[6:9]
	v_mfma_f32_16x16x32_bf16 v[38:41], v[78:81], v[180:183], v[38:41]
	v_mfma_f32_16x16x32_bf16 v[46:49], v[78:81], v[184:187], v[46:49]
	v_mfma_f32_16x16x32_bf16 v[62:65], v[78:81], v[188:191], v[62:65]
	v_mfma_f32_16x16x32_bf16 v[26:29], v[78:81], v[142:145], v[26:29]
	v_mfma_f32_16x16x32_bf16 v[54:57], v[148:151], v[180:183], v[54:57]
	v_mfma_f32_16x16x32_bf16 v[58:61], v[148:151], v[184:187], v[58:61]
	v_mfma_f32_16x16x32_bf16 v[70:73], v[148:151], v[188:191], v[70:73]
	v_mfma_f32_16x16x32_bf16 v[14:17], v[148:151], v[142:145], v[14:17]
	v_mfma_f32_16x16x32_bf16 v[18:21], v[152:155], v[180:183], v[18:21]
	v_mfma_f32_16x16x32_bf16 v[42:45], v[152:155], v[184:187], v[42:45]
	v_mfma_f32_16x16x32_bf16 v[34:37], v[152:155], v[188:191], v[34:37]
	s_waitcnt lgkmcnt(0)
	v_mfma_f32_16x16x32_bf16 v[2:5], v[204:207], v[220:223], v[2:5]
	v_mfma_f32_16x16x32_bf16 v[10:13], v[192:195], v[208:211], v[10:13]
	v_mfma_f32_16x16x32_bf16 v[22:25], v[192:195], v[212:215], v[22:25]
	v_mfma_f32_16x16x32_bf16 v[30:33], v[192:195], v[216:219], v[30:33]
	v_mfma_f32_16x16x32_bf16 v[6:9], v[192:195], v[220:223], v[6:9]
	v_mfma_f32_16x16x32_bf16 v[38:41], v[196:199], v[208:211], v[38:41]
	v_mfma_f32_16x16x32_bf16 v[46:49], v[196:199], v[212:215], v[46:49]
	v_mfma_f32_16x16x32_bf16 v[62:65], v[196:199], v[216:219], v[62:65]
	v_mfma_f32_16x16x32_bf16 v[26:29], v[196:199], v[220:223], v[26:29]
	v_mfma_f32_16x16x32_bf16 v[54:57], v[200:203], v[208:211], v[54:57]
	v_mfma_f32_16x16x32_bf16 v[58:61], v[200:203], v[212:215], v[58:61]
	v_mfma_f32_16x16x32_bf16 v[70:73], v[200:203], v[216:219], v[70:73]
	v_mfma_f32_16x16x32_bf16 v[14:17], v[200:203], v[220:223], v[14:17]
	v_mfma_f32_16x16x32_bf16 v[18:21], v[204:207], v[208:211], v[18:21]
	v_mfma_f32_16x16x32_bf16 v[42:45], v[204:207], v[212:215], v[42:45]
	v_mfma_f32_16x16x32_bf16 v[34:37], v[204:207], v[216:219], v[34:37]
	s_setprio 0
	v_mul_f32_e32 v0, 0x3b808081, v100
	v_mul_f32_e32 v10, v0, v10
	v_mul_f32_e32 v0, 0x3b808081, v101
	v_mul_f32_e32 v11, v0, v11
	v_mul_f32_e32 v0, 0x3b808081, v102
	v_mul_f32_e32 v12, v0, v12
	v_mul_f32_e32 v0, 0x3b808081, v103
	v_mul_f32_e32 v13, v0, v13
	v_mul_f32_e32 v0, 0x3b808081, v104
	v_mul_f32_e32 v22, v0, v22
	v_mul_f32_e32 v0, 0x3b808081, v105
	v_mul_f32_e32 v23, v0, v23
	v_mul_f32_e32 v0, 0x3b808081, v106
	v_mul_f32_e32 v24, v0, v24
	v_mul_f32_e32 v0, 0x3b808081, v107
; DI void stage_acc(const f32x4 (&acc)[4][4], float* tile, int wm, int wn, int fr, int fq) {
; #pragma unroll
;   for (int mi = 0; mi < 4; ++mi)
; #pragma unroll
;     for (int ni = 0; ni < 4; ++ni)
; #pragma unroll
;       for (int j = 0; j < 4; ++j) tile[(wm * 64 + mi * 16 + fq * 4 + j) * EPS + wn * 64 + ni * 16 + fr] = acc[mi][ni][j];
; }
; DI void phaseD_tile(const P& p, int layer, int mt, int nt, char* lds) {
;     ...
;   for (int mi = 0; mi < 4; ++mi)
; #pragma unroll
;     for (int ni = 0; ni < 4; ++ni)
; #pragma unroll
;       for (int j = 0; j < 4; ++j) acc[mi][ni][j] *= fmaxf((float)((gav[mi][ni] >> (8 * j)) & 255u), 1.f) * (1.f / 255.f);
;   float* tile = (float*)lds;
;   stage_acc(acc, tile, wm, wn, fr, fq);
;   __syncthreads();
	v_mul_f32_e32 v25, v0, v25
	v_mul_f32_e32 v0, 0x3b808081, v108
	v_mul_f32_e32 v30, v0, v30
	v_mul_f32_e32 v0, 0x3b808081, v109
	v_mul_f32_e32 v31, v0, v31
	v_mul_f32_e32 v0, 0x3b808081, v110
	v_mul_f32_e32 v32, v0, v32
	v_mul_f32_e32 v0, 0x3b808081, v111
	v_mul_f32_e32 v33, v0, v33
	v_mul_f32_e32 v0, 0x3b808081, v112
	v_mul_f32_e32 v6, v0, v6
	v_mul_f32_e32 v0, 0x3b808081, v113
	v_mul_f32_e32 v7, v0, v7
	v_mul_f32_e32 v0, 0x3b808081, v114
	v_mul_f32_e32 v8, v0, v8
	v_mul_f32_e32 v0, 0x3b808081, v115
	v_mul_f32_e32 v9, v0, v9
	v_mul_f32_e32 v0, 0x3b808081, v94
	v_mul_f32_e32 v38, v0, v38
	v_mul_f32_e32 v0, 0x3b808081, v95
	v_mul_f32_e32 v39, v0, v39
	v_mul_f32_e32 v0, 0x3b808081, v96
	v_mul_f32_e32 v40, v0, v40
	v_mul_f32_e32 v0, 0x3b808081, v97
	v_mul_f32_e32 v41, v0, v41
	v_mul_f32_e32 v0, 0x3b808081, v90
	v_mul_f32_e32 v46, v0, v46
	v_mul_f32_e32 v0, 0x3b808081, v91
	v_mul_f32_e32 v47, v0, v47
	v_mul_f32_e32 v0, 0x3b808081, v92
	v_mul_f32_e32 v48, v0, v48
	v_mul_f32_e32 v0, 0x3b808081, v93
	v_mul_f32_e32 v49, v0, v49
	v_mul_f32_e32 v0, 0x3b808081, v116
	v_mul_f32_e32 v50, v0, v62
	v_mul_f32_e32 v0, 0x3b808081, v117
	v_mul_f32_e32 v51, v0, v63
	v_mul_f32_e32 v0, 0x3b808081, v118
	v_mul_f32_e32 v62, v0, v64
	v_mul_f32_e32 v0, 0x3b808081, v119
	v_mul_f32_e32 v63, v0, v65
	v_mul_f32_e32 v0, 0x3b808081, v120
	v_mul_f32_e32 v26, v0, v26
	v_mul_f32_e32 v0, 0x3b808081, v121
	v_mul_f32_e32 v27, v0, v27
	v_mul_f32_e32 v0, 0x3b808081, v122
	v_mul_f32_e32 v28, v0, v28
	v_mul_f32_e32 v0, 0x3b808081, v123
	v_mul_f32_e32 v29, v0, v29
	v_mul_f32_e32 v0, 0x3b808081, v86
	v_mul_f32_e32 v54, v0, v54
	v_mul_f32_e32 v0, 0x3b808081, v87
	v_mul_f32_e32 v55, v0, v55
	v_mul_f32_e32 v0, 0x3b808081, v88
	v_mul_f32_e32 v56, v0, v56
	v_mul_f32_e32 v0, 0x3b808081, v89
	v_mul_f32_e32 v57, v0, v57
	v_mul_f32_e32 v0, 0x3b808081, v82
	v_mul_f32_e32 v58, v0, v58
	v_mul_f32_e32 v0, 0x3b808081, v83
	v_mul_f32_e32 v59, v0, v59
	v_mul_f32_e32 v0, 0x3b808081, v84
	v_mul_f32_e32 v60, v0, v60
	v_mul_f32_e32 v0, 0x3b808081, v85
	v_mul_f32_e32 v61, v0, v61
	v_mul_f32_e32 v0, 0x3b808081, v124
	v_mul_f32_e32 v64, v0, v70
	v_mul_f32_e32 v0, 0x3b808081, v125
	v_mul_f32_e32 v65, v0, v71
	v_mul_f32_e32 v0, 0x3b808081, v126
	v_mul_f32_e32 v70, v0, v72
	v_mul_f32_e32 v0, 0x3b808081, v127
	v_mul_f32_e32 v71, v0, v73
	v_mul_f32_e32 v0, 0x3b808081, v128
	v_mul_f32_e32 v14, v0, v14
	v_mul_f32_e32 v0, 0x3b808081, v129
	v_mul_f32_e32 v15, v0, v15
	v_mul_f32_e32 v0, 0x3b808081, v130
	v_mul_f32_e32 v16, v0, v16
	v_mul_f32_e32 v0, 0x3b808081, v131
	v_mul_f32_e32 v17, v0, v17
	v_mul_f32_e32 v0, 0x3b808081, v66
	v_mul_f32_e32 v18, v0, v18
	v_mul_f32_e32 v0, 0x3b808081, v67
	v_mul_f32_e32 v19, v0, v19
	v_mul_f32_e32 v0, 0x3b808081, v68
	v_mul_f32_e32 v20, v0, v20
	v_mul_f32_e32 v0, 0x3b808081, v69
	v_mul_f32_e32 v21, v0, v21
	v_mul_f32_e32 v0, 0x3b808081, v52
	v_mul_f32_e32 v42, v0, v42
	v_mul_f32_e32 v0, 0x3b808081, v53
	v_mul_f32_e32 v43, v0, v43
	v_mul_f32_e32 v0, 0x3b808081, v132
	v_mul_f32_e32 v44, v0, v44
	v_mul_f32_e32 v0, 0x3b808081, v133
	v_mul_f32_e32 v45, v0, v45
	v_mul_f32_e32 v0, 0x3b808081, v134
	v_mul_f32_e32 v34, v0, v34
	v_mul_f32_e32 v0, 0x3b808081, v135
	v_mul_f32_e32 v35, v0, v35
	v_mul_f32_e32 v0, 0x3b808081, v136
	v_mul_f32_e32 v36, v0, v36
	v_mul_f32_e32 v0, 0x3b808081, v137
	v_mul_f32_e32 v37, v0, v37
	v_mul_f32_e32 v0, 0x3b808081, v138
	v_mul_f32_e32 v52, v0, v2
	v_mul_f32_e32 v0, 0x3b808081, v139
	v_mul_f32_e32 v53, v0, v3
	v_mul_f32_e32 v0, 0x3b808081, v140
	v_mul_f32_e32 v4, v0, v4
	v_mul_f32_e32 v0, 0x3b808081, v141
	v_bfe_u32 v66, v99, 4, 2
	v_mul_f32_e32 v5, v0, v5
	v_lshlrev_b32_e32 v0, 2, v66
	s_lshl_b32 s5, s20, 8
	v_lshl_or_b32 v2, s19, 6, v0
	v_lshl_or_b32 v0, v98, 2, s5
	v_mad_u64_u32 v[2:3], s[8:9], v2, s56, v[0:1]
	v_add_u32_e32 v0, 0x400, v2
	s_lshl_b32 s8, s19, 2
	s_lshl_b64 s[6:7], s[6:7], 1
	s_mov_b64 s[58:59], s[60:61]
	s_barrier
	ds_write2_b32 v2, v10, v22 offset1:16
	ds_write2_b32 v2, v11, v23 offset0:132 offset1:148
	ds_write2_b32 v0, v12, v24 offset0:8 offset1:24
	ds_write2_b32 v0, v13, v25 offset0:140 offset1:156
	ds_write2_b32 v2, v30, v6 offset0:32 offset1:48
	ds_write2_b32 v2, v31, v7 offset0:164 offset1:180
	ds_write2_b32 v0, v32, v8 offset0:40 offset1:56
	ds_write2_b32 v0, v33, v9 offset0:172 offset1:188
	v_add_u32_e32 v0, 0x2000, v2
	v_add_u32_e32 v3, 0x2400, v2
	s_add_u32 s6, s58, s6
	ds_write2_b32 v0, v38, v46 offset0:64 offset1:80
	ds_write2_b32 v0, v39, v47 offset0:196 offset1:212
	ds_write2_b32 v3, v40, v48 offset0:72 offset1:88
	ds_write2_b32 v3, v41, v49 offset0:204 offset1:220
	ds_write2_b32 v0, v50, v26 offset0:96 offset1:112
	ds_write2_b32 v0, v51, v27 offset0:228 offset1:244
	ds_write2_b32 v3, v62, v28 offset0:104 offset1:120
	ds_write2_b32 v3, v63, v29 offset0:236 offset1:252
	v_add_u32_e32 v0, 0x4000, v2
	v_add_u32_e32 v3, 0x4400, v2
	v_add_u32_e32 v6, 0x4800, v2
	s_addc_u32 s7, s59, s7
	s_lshl_b32 s9, s20, 7
	ds_write2_b32 v0, v54, v58 offset0:128 offset1:144
	ds_write2_b32 v3, v55, v59 offset0:4 offset1:20
	ds_write2_b32 v3, v56, v60 offset0:136 offset1:152
	ds_write2_b32 v6, v57, v61 offset0:12 offset1:28
	ds_write2_b32 v0, v64, v14 offset0:160 offset1:176
	ds_write2_b32 v3, v65, v15 offset0:36 offset1:52
	ds_write2_b32 v3, v70, v16 offset0:168 offset1:184
	ds_write2_b32 v6, v71, v17 offset0:44 offset1:60
	v_add_u32_e32 v0, 0x6000, v2
	v_add_u32_e32 v3, 0x6400, v2
	v_add_u32_e32 v2, 0x6800, v2
	s_add_u32 s6, s6, s9
	s_mulk_i32 s19, 0x840
	ds_write2_b32 v0, v18, v42 offset0:192 offset1:208
	ds_write2_b32 v3, v19, v43 offset0:68 offset1:84
	ds_write2_b32 v3, v20, v44 offset0:200 offset1:216
	ds_write2_b32 v2, v21, v45 offset0:76 offset1:92
	ds_write2_b32 v0, v34, v52 offset0:224 offset1:240
	ds_write2_b32 v3, v35, v53 offset0:100 offset1:116
	ds_write2_b32 v3, v36, v4 offset0:232 offset1:248
	ds_write2_b32 v2, v37, v5 offset0:108 offset1:124
	s_addc_u32 s7, s7, 0
	v_lshlrev_b32_e32 v0, 3, v98
	s_add_i32 s8, s8, s4
	v_mul_u32_u24_e32 v4, 0x210, v66
	s_add_i32 s5, s5, s19
	v_lshlrev_b32_e32 v5, 4, v98
	v_lshl_add_u64 v[2:3], s[6:7], 0, v[0:1]
	v_or_b32_e32 v0, s8, v66
	v_add3_u32 v4, s5, v4, v5
	s_mov_b32 s4, 0
	s_movk_i32 s5, 0x880
	s_waitcnt lgkmcnt(0)
	s_barrier

; DI unsigned pk2(float lo, float hi) { unsigned r; asm("v_cvt_pk_bf16_f32 %0, %1, %2" : "=v"(r) : "v"(lo), "v"(hi)); return r; }
; DI void attn_item(const P& p, bool isS, int b, int h, int qblk, char* lds) {
;     ...
;   const float ltot = lsum + __shfl_xor(lsum, 32);
;   const float inv = 1.f / ltot;
;   if (wvalid) {
;     bf16_t* za = (bf16_t*)(p.ws + W_ZA) + (size_t)qrow * 512 + h * 64;
; #pragma unroll
;     for (int db = 0; db < 2; ++db)
; #pragma unroll
;       for (int g4 = 0; g4 < 4; ++g4) {
;         const int d = db * 32 + 8 * g4 + 4 * hl;
;         const u32x2 z = *(const u32x2*)(za + d);
;         const float z0 = __uint_as_float(z.x << 16), z1 = __uint_as_float(z.x & 0xffff0000u), z2 = __uint_as_float(z.y << 16), z3 = __uint_as_float(z.y & 0xffff0000u);
;         *(u32x2*)(za + d) = u32x2{pk2(ot[db][4 * g4] * inv * z0, ot[db][4 * g4 + 1] * inv * z1), pk2(ot[db][4 * g4 + 2] * inv * z2, ot[db][4 * g4 + 3] * inv * z3)};
;       }
;   }
.LBB0_313:
	v_and_b32_e32 v34, 64, v170
	v_xor_b32_e32 v0, 32, v170
	v_add_u32_e32 v34, 64, v34
	v_cmp_lt_i32_e32 vcc, v0, v34
	s_nop 1
	v_cndmask_b32_e32 v0, v170, v0, vcc
	v_lshlrev_b32_e32 v0, 2, v0
	ds_bpermute_b32 v0, v0, v140
	s_waitcnt lgkmcnt(0)
	v_add_f32_e32 v0, v140, v0
	s_nop 0
	v_rcp_f32_e32 v36, v0
	s_nop 0
	v_lshl_add_u64 v[34:35], v[120:121], 1, s[8:9]
	v_lshlrev_b32_e32 v0, 1, v119
	v_lshl_add_u64 v[34:35], v[34:35], 0, v[0:1]
	global_load_dwordx2 v[38:39], v[34:35], off
	v_mul_f32_e32 v18, v18, v36
	v_mul_f32_e32 v2, v2, v36
	s_waitcnt vmcnt(0)
	v_lshlrev_b32_e32 v0, 16, v38
	v_and_b32_e32 v37, 0xffff0000, v38
	v_mul_f32_e32 v0, v18, v0
	v_mul_f32_e32 v18, v19, v36
	v_lshlrev_b32_e32 v38, 16, v39
	v_and_b32_e32 v39, 0xffff0000, v39
	v_mul_f32_e32 v18, v18, v37
	v_mul_f32_e32 v19, v21, v36
	v_cvt_pk_bf16_f32 v18, v0, v18
	v_mul_f32_e32 v0, v20, v36
	v_mul_f32_e32 v19, v19, v39
	v_mul_f32_e32 v0, v0, v38
	v_cvt_pk_bf16_f32 v19, v0, v19
	global_store_dwordx2 v[34:35], v[18:19], off
	global_load_dwordx2 v[18:19], v[34:35], off offset:16
	v_mul_f32_e32 v21, v22, v36
	s_waitcnt vmcnt(0)
	v_lshlrev_b32_e32 v0, 16, v18
	v_and_b32_e32 v18, 0xffff0000, v18
	v_mul_f32_e32 v0, v21, v0
	v_mul_f32_e32 v21, v23, v36
	v_mul_f32_e32 v18, v21, v18
	v_lshlrev_b32_e32 v20, 16, v19
	v_cvt_pk_bf16_f32 v18, v0, v18
	v_mul_f32_e32 v0, v24, v36
	v_and_b32_e32 v19, 0xffff0000, v19
	v_mul_f32_e32 v0, v0, v20
	v_mul_f32_e32 v20, v25, v36
	v_mul_f32_e32 v19, v20, v19
	v_cvt_pk_bf16_f32 v19, v0, v19
	global_store_dwordx2 v[34:35], v[18:19], off offset:16
	global_load_dwordx2 v[18:19], v[34:35], off offset:32
	v_mul_f32_e32 v21, v26, v36
	s_waitcnt vmcnt(0)
	v_lshlrev_b32_e32 v0, 16, v18
	v_and_b32_e32 v18, 0xffff0000, v18
	v_mul_f32_e32 v0, v21, v0
	v_mul_f32_e32 v21, v27, v36
	v_mul_f32_e32 v18, v21, v18
	v_lshlrev_b32_e32 v20, 16, v19
	v_cvt_pk_bf16_f32 v18, v0, v18
	v_mul_f32_e32 v0, v28, v36
	v_and_b32_e32 v19, 0xffff0000, v19
	v_mul_f32_e32 v0, v0, v20
	v_mul_f32_e32 v20, v29, v36
	v_mul_f32_e32 v19, v20, v19
	v_cvt_pk_bf16_f32 v19, v0, v19
	global_store_dwordx2 v[34:35], v[18:19], off offset:32
	global_load_dwordx2 v[18:19], v[34:35], off offset:48
	v_mul_f32_e32 v21, v30, v36
	s_waitcnt vmcnt(0)
	v_lshlrev_b32_e32 v0, 16, v18
	v_and_b32_e32 v18, 0xffff0000, v18
	v_mul_f32_e32 v0, v21, v0
	v_mul_f32_e32 v21, v31, v36
	v_mul_f32_e32 v18, v21, v18
	v_lshlrev_b32_e32 v20, 16, v19
	v_cvt_pk_bf16_f32 v18, v0, v18
	v_mul_f32_e32 v0, v32, v36
	v_and_b32_e32 v19, 0xffff0000, v19
	v_mul_f32_e32 v0, v0, v20
	v_mul_f32_e32 v20, v33, v36
	v_mul_f32_e32 v19, v20, v19
	v_cvt_pk_bf16_f32 v19, v0, v19
	global_store_dwordx2 v[34:35], v[18:19], off offset:48
	global_load_dwordx2 v[18:19], v[34:35], off offset:64
	s_waitcnt vmcnt(0)
	v_lshlrev_b32_e32 v0, 16, v18
	v_and_b32_e32 v18, 0xffff0000, v18
	v_mul_f32_e32 v0, v2, v0
	v_mul_f32_e32 v2, v3, v36
	v_lshlrev_b32_e32 v20, 16, v19
	v_and_b32_e32 v19, 0xffff0000, v19
	v_mul_f32_e32 v2, v2, v18
	v_mul_f32_e32 v3, v5, v36
	v_cvt_pk_bf16_f32 v2, v0, v2
	v_mul_f32_e32 v0, v4, v36
	v_mul_f32_e32 v3, v3, v19
	v_mul_f32_e32 v0, v0, v20
	v_cvt_pk_bf16_f32 v3, v0, v3
	global_store_dwordx2 v[34:35], v[2:3], off offset:64
	global_load_dwordx2 v[2:3], v[34:35], off offset:80
	v_mul_f32_e32 v5, v6, v36
	s_waitcnt vmcnt(0)
	v_lshlrev_b32_e32 v0, 16, v2
	v_and_b32_e32 v2, 0xffff0000, v2
	v_mul_f32_e32 v0, v5, v0
	v_mul_f32_e32 v5, v7, v36
	v_mul_f32_e32 v2, v5, v2
	v_lshlrev_b32_e32 v4, 16, v3
	v_cvt_pk_bf16_f32 v2, v0, v2
	v_mul_f32_e32 v0, v8, v36
	v_and_b32_e32 v3, 0xffff0000, v3
	v_mul_f32_e32 v0, v0, v4
	v_mul_f32_e32 v4, v9, v36
	v_mul_f32_e32 v3, v4, v3
	v_cvt_pk_bf16_f32 v3, v0, v3
	global_store_dwordx2 v[34:35], v[2:3], off offset:80
	global_load_dwordx2 v[2:3], v[34:35], off offset:96
	v_mul_f32_e32 v5, v10, v36
	s_waitcnt vmcnt(0)
	v_lshlrev_b32_e32 v0, 16, v2
	v_and_b32_e32 v2, 0xffff0000, v2
	v_mul_f32_e32 v0, v5, v0
	v_mul_f32_e32 v5, v11, v36
	v_mul_f32_e32 v2, v5, v2
	v_lshlrev_b32_e32 v4, 16, v3
	v_cvt_pk_bf16_f32 v2, v0, v2
	v_mul_f32_e32 v0, v12, v36
	v_and_b32_e32 v3, 0xffff0000, v3
	v_mul_f32_e32 v0, v0, v4
	v_mul_f32_e32 v4, v13, v36
	v_mul_f32_e32 v3, v4, v3
	v_cvt_pk_bf16_f32 v3, v0, v3
	global_store_dwordx2 v[34:35], v[2:3], off offset:96
	global_load_dwordx2 v[2:3], v[34:35], off offset:112
	v_mul_f32_e32 v5, v14, v36
	s_waitcnt vmcnt(0)
	v_lshlrev_b32_e32 v0, 16, v2
	v_and_b32_e32 v2, 0xffff0000, v2
	v_mul_f32_e32 v0, v5, v0
	v_mul_f32_e32 v5, v15, v36
	v_mul_f32_e32 v2, v5, v2
	v_lshlrev_b32_e32 v4, 16, v3
	v_cvt_pk_bf16_f32 v2, v0, v2
	v_mul_f32_e32 v0, v16, v36
	v_and_b32_e32 v3, 0xffff0000, v3
	v_mul_f32_e32 v0, v0, v4
	v_mul_f32_e32 v4, v17, v36
	v_mul_f32_e32 v3, v4, v3
	v_cvt_pk_bf16_f32 v3, v0, v3
	global_store_dwordx2 v[34:35], v[2:3], off offset:112

; DI unsigned pk2(float lo, float hi) { unsigned r; asm("v_cvt_pk_bf16_f32 %0, %1, %2" : "=v"(r) : "v"(lo), "v"(hi)); return r; }
; DI void attn_item(const P& p, bool isS, int b, int h, int qblk, char* lds) {
;     ...
;   const float ltot = lsum + __shfl_xor(lsum, 32);
;   const float inv = 1.f / ltot;
;   if (wvalid) {
;     bf16_t* za = (bf16_t*)(p.ws + W_ZA) + (size_t)qrow * 512 + h * 64;
; #pragma unroll
;     for (int db = 0; db < 2; ++db)
; #pragma unroll
;       for (int g4 = 0; g4 < 4; ++g4) {
;         const int d = db * 32 + 8 * g4 + 4 * hl;
;         const u32x2 z = *(const u32x2*)(za + d);
;         const float z0 = __uint_as_float(z.x << 16), z1 = __uint_as_float(z.x & 0xffff0000u), z2 = __uint_as_float(z.y << 16), z3 = __uint_as_float(z.y & 0xffff0000u);
;         *(u32x2*)(za + d) = u32x2{pk2(ot[db][4 * g4] * inv * z0, ot[db][4 * g4 + 1] * inv * z1), pk2(ot[db][4 * g4 + 2] * inv * z2, ot[db][4 * g4 + 3] * inv * z3)};
;       }
;   }
.LBB0_333:
	v_and_b32_e32 v19, 64, v170
	v_xor_b32_e32 v18, 32, v170
	v_add_u32_e32 v19, 64, v19
	v_cmp_lt_i32_e32 vcc, v18, v19
	s_nop 1
	v_cndmask_b32_e32 v18, v170, v18, vcc
	v_lshlrev_b32_e32 v18, 2, v18
	ds_bpermute_b32 v18, v18, v0
	s_andn2_b64 vcc, exec, s[10:11]
	s_cbranch_vccnz .LBB0_285
	s_waitcnt lgkmcnt(0)
	v_add_f32_e32 v0, v0, v18
	s_nop 0
	v_rcp_f32_e32 v20, v0
	s_nop 0
	v_lshl_add_u64 v[18:19], v[118:119], 1, s[8:9]
	v_lshlrev_b32_e32 v0, 1, v179
	v_lshl_add_u64 v[18:19], v[18:19], 0, v[0:1]
	global_load_dwordx2 v[22:23], v[18:19], off
	v_mul_f32_e32 v2, v2, v20
	s_waitcnt vmcnt(0)
	v_lshlrev_b32_e32 v0, 16, v22
	v_and_b32_e32 v21, 0xffff0000, v22
	v_mul_f32_e32 v22, v34, v20
	v_mul_f32_e32 v0, v22, v0
	v_mul_f32_e32 v22, v35, v20
	v_mul_f32_e32 v21, v22, v21
	v_lshlrev_b32_e32 v24, 16, v23
	v_and_b32_e32 v23, 0xffff0000, v23
	v_cvt_pk_bf16_f32 v22, v0, v21
	v_mul_f32_e32 v0, v36, v20
	v_mul_f32_e32 v21, v37, v20
	v_mul_f32_e32 v0, v0, v24
	v_mul_f32_e32 v21, v21, v23
	v_cvt_pk_bf16_f32 v23, v0, v21
	global_store_dwordx2 v[18:19], v[22:23], off
	global_load_dwordx2 v[22:23], v[18:19], off offset:16
	s_waitcnt vmcnt(0)
	v_lshlrev_b32_e32 v0, 16, v22
	v_and_b32_e32 v21, 0xffff0000, v22
	v_mul_f32_e32 v22, v38, v20
	v_mul_f32_e32 v0, v22, v0
	v_mul_f32_e32 v22, v39, v20
	v_mul_f32_e32 v21, v22, v21
	v_lshlrev_b32_e32 v24, 16, v23
	v_and_b32_e32 v23, 0xffff0000, v23
	v_cvt_pk_bf16_f32 v22, v0, v21
	v_mul_f32_e32 v0, v40, v20
	v_mul_f32_e32 v21, v41, v20
	v_mul_f32_e32 v0, v0, v24
	v_mul_f32_e32 v21, v21, v23
	v_cvt_pk_bf16_f32 v23, v0, v21
	global_store_dwordx2 v[18:19], v[22:23], off offset:16
	global_load_dwordx2 v[22:23], v[18:19], off offset:32
	s_waitcnt vmcnt(0)
	v_lshlrev_b32_e32 v0, 16, v22
	v_and_b32_e32 v21, 0xffff0000, v22
	v_mul_f32_e32 v22, v42, v20
	v_mul_f32_e32 v0, v22, v0
	v_mul_f32_e32 v22, v43, v20
	v_mul_f32_e32 v21, v22, v21
	v_lshlrev_b32_e32 v24, 16, v23
	v_and_b32_e32 v23, 0xffff0000, v23
	v_cvt_pk_bf16_f32 v22, v0, v21
	v_mul_f32_e32 v0, v44, v20
	v_mul_f32_e32 v21, v45, v20
	v_mul_f32_e32 v0, v0, v24
	v_mul_f32_e32 v21, v21, v23
	v_cvt_pk_bf16_f32 v23, v0, v21
	global_store_dwordx2 v[18:19], v[22:23], off offset:32
	global_load_dwordx2 v[22:23], v[18:19], off offset:48
	s_waitcnt vmcnt(0)
	v_lshlrev_b32_e32 v0, 16, v22
	v_and_b32_e32 v21, 0xffff0000, v22
	v_mul_f32_e32 v22, v46, v20
	v_mul_f32_e32 v0, v22, v0
	v_mul_f32_e32 v22, v47, v20
	v_mul_f32_e32 v21, v22, v21
	v_lshlrev_b32_e32 v24, 16, v23
	v_and_b32_e32 v23, 0xffff0000, v23
	v_cvt_pk_bf16_f32 v22, v0, v21
	v_mul_f32_e32 v0, v48, v20
	v_mul_f32_e32 v21, v49, v20
	v_mul_f32_e32 v0, v0, v24
	v_mul_f32_e32 v21, v21, v23
	v_cvt_pk_bf16_f32 v23, v0, v21
	global_store_dwordx2 v[18:19], v[22:23], off offset:48
	global_load_dwordx2 v[22:23], v[18:19], off offset:64
	s_waitcnt vmcnt(0)
	v_lshlrev_b32_e32 v0, 16, v22
	v_and_b32_e32 v21, 0xffff0000, v22
	v_mul_f32_e32 v0, v2, v0
	v_mul_f32_e32 v2, v3, v20
	v_lshlrev_b32_e32 v22, 16, v23
	v_and_b32_e32 v23, 0xffff0000, v23
	v_mul_f32_e32 v2, v2, v21
	v_mul_f32_e32 v3, v5, v20
	v_cvt_pk_bf16_f32 v2, v0, v2
	v_mul_f32_e32 v0, v4, v20
	v_mul_f32_e32 v3, v3, v23
	v_mul_f32_e32 v0, v0, v22
	v_cvt_pk_bf16_f32 v3, v0, v3
	global_store_dwordx2 v[18:19], v[2:3], off offset:64
	global_load_dwordx2 v[2:3], v[18:19], off offset:80
	v_mul_f32_e32 v5, v6, v20
	s_waitcnt vmcnt(0)
	v_lshlrev_b32_e32 v0, 16, v2
	v_and_b32_e32 v2, 0xffff0000, v2
	v_mul_f32_e32 v0, v5, v0
	v_mul_f32_e32 v5, v7, v20
	v_mul_f32_e32 v2, v5, v2
	v_lshlrev_b32_e32 v4, 16, v3
	v_cvt_pk_bf16_f32 v2, v0, v2
	v_mul_f32_e32 v0, v8, v20
	v_and_b32_e32 v3, 0xffff0000, v3
	v_mul_f32_e32 v0, v0, v4
	v_mul_f32_e32 v4, v9, v20
	v_mul_f32_e32 v3, v4, v3
	v_cvt_pk_bf16_f32 v3, v0, v3
	global_store_dwordx2 v[18:19], v[2:3], off offset:80
	global_load_dwordx2 v[2:3], v[18:19], off offset:96
	v_mul_f32_e32 v5, v10, v20
	s_waitcnt vmcnt(0)
	v_lshlrev_b32_e32 v0, 16, v2
	v_and_b32_e32 v2, 0xffff0000, v2
	v_mul_f32_e32 v0, v5, v0
	v_mul_f32_e32 v5, v11, v20
	v_mul_f32_e32 v2, v5, v2
	v_lshlrev_b32_e32 v4, 16, v3
	v_cvt_pk_bf16_f32 v2, v0, v2
	v_mul_f32_e32 v0, v12, v20
	v_and_b32_e32 v3, 0xffff0000, v3
	v_mul_f32_e32 v0, v0, v4
	v_mul_f32_e32 v4, v13, v20
	v_mul_f32_e32 v3, v4, v3
	v_cvt_pk_bf16_f32 v3, v0, v3
	global_store_dwordx2 v[18:19], v[2:3], off offset:96
	global_load_dwordx2 v[2:3], v[18:19], off offset:112
	v_mul_f32_e32 v5, v14, v20
	s_waitcnt vmcnt(0)
	v_lshlrev_b32_e32 v0, 16, v2
	v_and_b32_e32 v2, 0xffff0000, v2
	v_mul_f32_e32 v0, v5, v0
	v_mul_f32_e32 v5, v15, v20
	v_mul_f32_e32 v2, v5, v2
	v_lshlrev_b32_e32 v4, 16, v3
	v_cvt_pk_bf16_f32 v2, v0, v2
	v_mul_f32_e32 v0, v16, v20
	v_and_b32_e32 v3, 0xffff0000, v3
	v_mul_f32_e32 v0, v0, v4
	v_mul_f32_e32 v4, v17, v20
	v_mul_f32_e32 v3, v4, v3
	v_cvt_pk_bf16_f32 v3, v0, v3
	global_store_dwordx2 v[18:19], v[2:3], off offset:112
	s_branch .LBB0_285

; DI unsigned pk2(float lo, float hi) { unsigned r; asm("v_cvt_pk_bf16_f32 %0, %1, %2" : "=v"(r) : "v"(lo), "v"(hi)); return r; }
; DI void pooled_item(const P& p, int layer, int it) {
;     ...
;   const float inv = 1.f / (float)(isS ? w : ((t + 1) < w ? (t + 1) : w));
;   unsigned o[4];
; #pragma unroll
;   for (int e = 0; e < 4; ++e) o[e] = pk2(s[2 * e] * inv - __uint_as_float(uv[0][e] << 16), s[2 * e + 1] * inv - __uint_as_float(uv[0][e] & 0xffff0000u));
;   *(u32x4*)((bf16_t*)(p.ws + W_POOLED) + (size_t)row * 512 + c0) = u32x4{o[0], o[1], o[2], o[3]};
.LBB0_402:
	s_or_b64 exec, exec, s[0:1]
	v_min_u32_e32 v16, s6, v69
	v_cndmask_b32_e64 v16, v16, v69, s[40:41]
	v_cvt_f32_u32_e32 v16, v16
	s_add_u32 s0, s74, s2
	v_rcp_f32_e32 v16, v16
	s_nop 0
	v_fma_f32 v8, v16, v8, -v66
	v_fma_f32 v9, v16, v9, -v67
	v_fma_f32 v2, v16, v10, -v2
	v_fma_f32 v3, v16, v11, -v3
	s_addc_u32 s1, s75, s3
	s_add_i32 s11, s11, 1
	v_cvt_pk_bf16_f32 v8, v8, v9
	v_cvt_pk_bf16_f32 v9, v2, v3
	v_fma_f32 v2, v16, v12, -v6
	v_fma_f32 v3, v16, v13, -v7
	s_cmp_eq_u32 s11, 8
	v_cvt_pk_bf16_f32 v10, v2, v3
	v_fma_f32 v2, v16, v14, -v4
	v_fma_f32 v3, v16, v15, -v5
	v_cvt_pk_bf16_f32 v11, v2, v3
	global_store_dwordx4 v0, v[8:11], s[0:1]
	s_cbranch_scc1 .LBB0_438

; DI unsigned pk2(float lo, float hi) { unsigned r; asm("v_cvt_pk_bf16_f32 %0, %1, %2" : "=v"(r) : "v"(lo), "v"(hi)); return r; }
; DI float siluf_(float v) { return v / (1.f + __expf(-v)); }
; DI void phaseA_tile(const P& p, int layer, int mt, int nt, char* lds) {
;     ...
;     if (seg < 8) {
;       const int col = seg * 64 + cc * 4;
;       *(u32x2*)((bf16_t*)(p.ws + W_U) + (size_t)row * 512 + col) = u32x2{pk2(v.x, v.y), pk2(v.z, v.w)};
;       if (!isS) { if (t >= TP - 15) *(f32x4*)(out + O_PP + ((size_t)(layer * 16 + bb) * 15 + (t - (TP - 15))) * 512 + col) = v; }
;       else { if (t >= TS - 15) *(f32x4*)(out + O_PS + ((size_t)(layer * 8 + bb) * 15 + (t - (TS - 15))) * 512 + col) = v; }
;     } else if (seg < 16 || (seg >= 45 && seg < 53)) {
;       bf16_t* Z = (bf16_t*)(p.ws + (seg < 16 ? W_ZP : W_ZA)) + (size_t)row * 512 + (seg < 16 ? seg - 8 : seg - 45) * 64 + cc * 4;
;       *(u32x2*)Z = u32x2{pk2(siluf_(v.x), siluf_(v.y)), pk2(siluf_(v.z), siluf_(v.w))};
.LBB0_1276:
	s_and_b64 vcc, exec, s[16:17]
	s_cbranch_vccz .LBB0_1278
	v_mul_f32_e32 v0, 0xbfb8aa3b, v66
	v_exp_f32_e32 v0, v0
	v_ashrrev_i32_e32 v85, 31, v84
	v_lshlrev_b64 v[86:87], 10, v[84:85]
	v_lshl_add_u64 v[86:87], v[80:81], 0, v[86:87]
	v_add_f32_e32 v0, 1.0, v0
	s_nop 0
	v_rcp_f32_e32 v85, v0
	s_nop 0
	v_mul_f32_e32 v0, v66, v85
	v_mul_f32_e32 v85, 0xbfb8aa3b, v67
	v_exp_f32_e32 v85, v85
	s_nop 0
	v_add_f32_e32 v85, 1.0, v85
	s_nop 0
	v_rcp_f32_e32 v98, v85
	s_nop 0
	v_mul_f32_e32 v85, v67, v98
	v_cvt_pk_bf16_f32 v98, v0, v85
	v_mul_f32_e32 v0, 0xbfb8aa3b, v68
	v_exp_f32_e32 v0, v0
	s_nop 0
	v_add_f32_e32 v0, 1.0, v0
	s_nop 0
	v_rcp_f32_e32 v85, v0
	s_nop 0
	v_mul_f32_e32 v0, v68, v85
	v_mul_f32_e32 v85, 0xbfb8aa3b, v69
	v_exp_f32_e32 v85, v85
	s_nop 0
	v_add_f32_e32 v85, 1.0, v85
	s_nop 0
	v_rcp_f32_e32 v99, v85
	s_nop 0
	v_mul_f32_e32 v85, v69, v99
	v_cvt_pk_bf16_f32 v99, v0, v85
	global_store_dwordx2 v[86:87], v[98:99], off

; DI unsigned pk2(float lo, float hi) { unsigned r; asm("v_cvt_pk_bf16_f32 %0, %1, %2" : "=v"(r) : "v"(lo), "v"(hi)); return r; }
; DI float siluf_(float v) { return v / (1.f + __expf(-v)); }
; DI void phaseA_tile(const P& p, int layer, int mt, int nt, char* lds) {
;     ...
;     if (seg < 8) {
;       const int col = seg * 64 + cc * 4;
;       *(u32x2*)((bf16_t*)(p.ws + W_U) + (size_t)row * 512 + col) = u32x2{pk2(v.x, v.y), pk2(v.z, v.w)};
;       if (!isS) { if (t >= TP - 15) *(f32x4*)(out + O_PP + ((size_t)(layer * 16 + bb) * 15 + (t - (TP - 15))) * 512 + col) = v; }
;       else { if (t >= TS - 15) *(f32x4*)(out + O_PS + ((size_t)(layer * 8 + bb) * 15 + (t - (TS - 15))) * 512 + col) = v; }
;     } else if (seg < 16 || (seg >= 45 && seg < 53)) {
;       bf16_t* Z = (bf16_t*)(p.ws + (seg < 16 ? W_ZP : W_ZA)) + (size_t)row * 512 + (seg < 16 ? seg - 8 : seg - 45) * 64 + cc * 4;
;       *(u32x2*)Z = u32x2{pk2(siluf_(v.x), siluf_(v.y)), pk2(siluf_(v.z), siluf_(v.w))};
.LBB0_1296:
	s_and_b64 vcc, exec, s[16:17]
	s_cbranch_vccz .LBB0_1298
	v_mul_f32_e32 v0, 0xbfb8aa3b, v66
	v_exp_f32_e32 v0, v0
	v_ashrrev_i32_e32 v87, 31, v86
	v_lshlrev_b64 v[84:85], 10, v[86:87]
	v_lshl_add_u64 v[84:85], v[80:81], 0, v[84:85]
	v_add_f32_e32 v0, 1.0, v0
	s_nop 0
	v_rcp_f32_e32 v87, v0
	s_nop 0
	v_mul_f32_e32 v0, v66, v87
	v_mul_f32_e32 v87, 0xbfb8aa3b, v67
	v_exp_f32_e32 v87, v87
	s_nop 0
	v_add_f32_e32 v87, 1.0, v87
	s_nop 0
	v_rcp_f32_e32 v97, v87
	s_nop 0
	v_mul_f32_e32 v87, v67, v97
	v_cvt_pk_bf16_f32 v98, v0, v87
	v_mul_f32_e32 v0, 0xbfb8aa3b, v68
	v_exp_f32_e32 v0, v0
	s_nop 0
	v_add_f32_e32 v0, 1.0, v0
	s_nop 0
	v_rcp_f32_e32 v87, v0
	s_nop 0
	v_mul_f32_e32 v0, v68, v87
	v_mul_f32_e32 v87, 0xbfb8aa3b, v69
	v_exp_f32_e32 v87, v87
	s_nop 0
	v_add_f32_e32 v87, 1.0, v87
	s_nop 0
	v_rcp_f32_e32 v97, v87
	s_nop 0
	v_mul_f32_e32 v87, v69, v97
	v_cvt_pk_bf16_f32 v99, v0, v87
	global_store_dwordx2 v[84:85], v[98:99], off

; DI float sigmoidf_(float v) { return 1.f / (1.f + __expf(-v)); }
; DI void phaseA_tile(const P& p, int layer, int mt, int nt, char* lds) {
;     ...
;   if (seg >= 53) {
;     const bool isP = seg < 69;
;     unsigned* G = (unsigned*)(p.ws + (isP ? W_GP : W_GA)) + ((size_t)(((row0 >> 6) + wm) * 16 + (isP ? seg - 53 : seg - 69)) * 64 + lane) * 16;
; #pragma unroll
;     for (int mi = 0; mi < 4; ++mi) {
;       unsigned wv[4];
; #pragma unroll
;       for (int ni = 0; ni < 4; ++ni) {
;         unsigned w_ = 0u;
; #pragma unroll
;         for (int j = 0; j < 4; ++j) {
;           const float r = rr[wm * 64 + mi * 16 + fq * 4 + j];
;           w_ |= ((unsigned)(int)(sigmoidf_(acc[mi][ni][j] * r) * 255.f + 0.5f)) << (8 * j);
;         }
;         wv[ni] = w_;
;       }
;       *(u32x4*)(G + mi * 4) = u32x4{wv[0], wv[1], wv[2], wv[3]};
;     }
;     return;
.LBB0_1584:
	s_and_b64 vcc, exec, s[0:1]
	s_cbranch_vccz .LBB0_1183
	v_lshlrev_b32_e32 v66, 2, v127
	v_lshl_add_u32 v66, s11, 2, v66
	v_add_u32_e32 v66, 0x10800, v66
	ds_read_b128 v[68:71], v66
	s_cmpk_lt_u32 s55, 0x45
	s_cselect_b64 s[0:1], -1, 0
	s_and_b64 s[4:5], s[0:1], exec
	s_mov_b32 s4, 0x17ca2000
	s_waitcnt lgkmcnt(0)
	v_mul_f32_e32 v63, v63, v69
	v_mul_f32_e32 v63, 0xbfb8aa3b, v63
	s_cselect_b32 s4, s4, 0x19d22000
	v_exp_f32_e32 v72, v63
	v_mul_f32_e32 v63, v64, v70
	s_add_u32 s4, s90, s4
	v_mul_f32_e32 v63, 0xbfb8aa3b, v63
	s_addc_u32 s5, s91, 0
	s_lshl_b32 s10, s36, 5
	s_lshl_b32 s12, s56, 4
	v_exp_f32_e32 v64, v63
	v_mul_f32_e32 v63, v65, v71
	v_mul_f32_e32 v58, v58, v68
	s_and_b64 s[0:1], s[0:1], exec
	v_mul_f32_e32 v63, 0xbfb8aa3b, v63
	v_mul_f32_e32 v58, 0xbfb8aa3b, v58
	s_movk_i32 s0, 0xffcb
	v_mul_f32_e32 v62, v62, v68
	v_exp_f32_e32 v74, v63
	v_exp_f32_e32 v63, v58
	v_mul_f32_e32 v58, v59, v69
	s_cselect_b32 s0, s0, 0xffffffbb
	s_add_i32 s1, s12, s10
	v_mul_f32_e32 v62, 0xbfb8aa3b, v62
	v_mul_f32_e32 v58, 0xbfb8aa3b, v58
	s_add_i32 s1, s1, s55
	v_exp_f32_e32 v62, v62
	v_exp_f32_e32 v73, v58
	v_mul_f32_e32 v58, v60, v70
	s_add_i32 s0, s1, s0
	v_mul_f32_e32 v58, 0xbfb8aa3b, v58
	s_ashr_i32 s1, s0, 31
	v_exp_f32_e32 v65, v58
	v_mul_f32_e32 v58, v61, v71
	s_lshl_b64 s[0:1], s[0:1], 12
	v_mul_f32_e32 v58, 0xbfb8aa3b, v58
	s_add_u32 s0, s4, s0
	v_exp_f32_e32 v75, v58
	v_pk_add_f32 v[58:59], v[62:63], 1.0 op_sel_hi:[1,0]
	s_addc_u32 s1, s5, s1
	s_mov_b32 s10, 0x437f0000
	v_mul_f32_e32 v55, v55, v69
	v_mul_f32_e32 v55, 0xbfb8aa3b, v55
	v_rcp_f32_e32 v59, v59
	s_nop 0
	v_mul_f32_e32 v50, v50, v68
	v_mul_f32_e32 v50, 0xbfb8aa3b, v50
	v_mul_f32_e32 v54, v54, v68
	v_rcp_f32_e32 v58, v58
	s_nop 0
	v_pk_fma_f32 v[58:59], v[58:59], s[10:11], 0.5 op_sel_hi:[1,0,0]
	v_mul_f32_e32 v54, 0xbfb8aa3b, v54
	v_cvt_i32_f32_e32 v60, v59
	v_cvt_i32_f32_e32 v61, v58
	v_pk_add_f32 v[58:59], v[72:73], 1.0 op_sel_hi:[1,0]
	v_exp_f32_e32 v54, v54
	v_lshlrev_b32_e32 v0, 6, v152
	v_rcp_f32_e32 v59, v59
	s_nop 0
	s_nop 0
	v_rcp_f32_e32 v58, v58
	s_nop 0
	v_pk_fma_f32 v[58:59], v[58:59], s[10:11], 0.5 op_sel_hi:[1,0,0]
	s_nop 0
	v_cvt_i32_f32_e32 v58, v58
	v_cvt_i32_f32_e32 v59, v59
	v_lshlrev_b32_e32 v58, 8, v58
	v_lshlrev_b32_e32 v59, 8, v59
	v_or_b32_e32 v60, v59, v60
	v_or_b32_e32 v61, v58, v61
	v_pk_add_f32 v[58:59], v[64:65], 1.0 op_sel_hi:[1,0]
	s_nop 0
	s_nop 0
	v_rcp_f32_e32 v59, v59
	s_nop 0
	s_nop 0
	v_rcp_f32_e32 v58, v58
	s_nop 0
	v_pk_fma_f32 v[58:59], v[58:59], s[10:11], 0.5 op_sel_hi:[1,0,0]
	s_nop 0
	v_cvt_i32_f32_sdwa v58, v58 dst_sel:WORD_1 dst_unused:UNUSED_PAD src0_sel:DWORD
	v_cvt_i32_f32_sdwa v59, v59 dst_sel:WORD_1 dst_unused:UNUSED_PAD src0_sel:DWORD
	v_or_b32_e32 v61, v61, v58
	v_or_b32_e32 v60, v60, v59
	v_pk_add_f32 v[58:59], v[74:75], 1.0 op_sel_hi:[1,0]
	s_nop 0
	s_nop 0
	v_rcp_f32_e32 v59, v59
	s_nop 0
	s_nop 0
	v_rcp_f32_e32 v58, v58
	s_nop 0
	v_pk_fma_f32 v[58:59], v[58:59], s[10:11], 0.5 op_sel_hi:[1,0,0]
	s_nop 0
	v_cvt_i32_f32_sdwa v59, v59 dst_sel:BYTE_3 dst_unused:UNUSED_PAD src0_sel:DWORD
	v_cvt_i32_f32_sdwa v58, v58 dst_sel:BYTE_3 dst_unused:UNUSED_PAD src0_sel:DWORD
	v_or_b32_e32 v59, v60, v59
	v_exp_f32_e32 v60, v55
	v_mul_f32_e32 v55, v56, v70
	v_mul_f32_e32 v55, 0xbfb8aa3b, v55
	v_exp_f32_e32 v56, v55
	v_mul_f32_e32 v55, v57, v71
	v_mul_f32_e32 v55, 0xbfb8aa3b, v55
	v_exp_f32_e32 v62, v55
	v_exp_f32_e32 v55, v50
	v_mul_f32_e32 v50, v51, v69
	v_mul_f32_e32 v50, 0xbfb8aa3b, v50
	v_or_b32_e32 v58, v61, v58
	v_exp_f32_e32 v61, v50
	v_mul_f32_e32 v50, v52, v70
	v_mul_f32_e32 v50, 0xbfb8aa3b, v50
	v_exp_f32_e32 v57, v50
	v_mul_f32_e32 v50, v53, v71
	v_mul_f32_e32 v50, 0xbfb8aa3b, v50
	v_exp_f32_e32 v63, v50
	v_pk_add_f32 v[50:51], v[54:55], 1.0 op_sel_hi:[1,0]
	s_nop 0
	s_nop 0
	v_rcp_f32_e32 v51, v51
	s_nop 0
	s_nop 0
	v_rcp_f32_e32 v50, v50
	s_nop 0
	v_pk_fma_f32 v[50:51], v[50:51], s[10:11], 0.5 op_sel_hi:[1,0,0]
	s_nop 0
	v_cvt_i32_f32_e32 v52, v51
	v_cvt_i32_f32_e32 v53, v50
	v_pk_add_f32 v[50:51], v[60:61], 1.0 op_sel_hi:[1,0]
	s_nop 0
	s_nop 0
	v_rcp_f32_e32 v51, v51
	s_nop 0
	s_nop 0
	v_rcp_f32_e32 v50, v50
	s_nop 0
	v_pk_fma_f32 v[50:51], v[50:51], s[10:11], 0.5 op_sel_hi:[1,0,0]
	s_nop 0
	v_cvt_i32_f32_e32 v50, v50
	v_cvt_i32_f32_e32 v51, v51
	v_lshlrev_b32_e32 v50, 8, v50
	v_lshlrev_b32_e32 v51, 8, v51
	v_or_b32_e32 v52, v51, v52
	v_or_b32_e32 v53, v50, v53
	v_pk_add_f32 v[50:51], v[56:57], 1.0 op_sel_hi:[1,0]
	s_nop 0
	s_nop 0
	v_rcp_f32_e32 v51, v51
	s_nop 0
	s_nop 0
	v_rcp_f32_e32 v50, v50
	s_nop 0
	v_pk_fma_f32 v[50:51], v[50:51], s[10:11], 0.5 op_sel_hi:[1,0,0]
	s_nop 0
	v_cvt_i32_f32_sdwa v50, v50 dst_sel:WORD_1 dst_unused:UNUSED_PAD src0_sel:DWORD
	v_cvt_i32_f32_sdwa v51, v51 dst_sel:WORD_1 dst_unused:UNUSED_PAD src0_sel:DWORD
	v_or_b32_e32 v53, v53, v50
	v_or_b32_e32 v52, v52, v51
	v_pk_add_f32 v[50:51], v[62:63], 1.0 op_sel_hi:[1,0]
	s_nop 0
	s_nop 0
	v_rcp_f32_e32 v51, v51
	s_nop 0
	s_nop 0
	v_rcp_f32_e32 v50, v50
	s_nop 0
	v_pk_fma_f32 v[50:51], v[50:51], s[10:11], 0.5 op_sel_hi:[1,0,0]
	s_nop 0
	v_cvt_i32_f32_sdwa v50, v50 dst_sel:BYTE_3 dst_unused:UNUSED_PAD src0_sel:DWORD
	v_cvt_i32_f32_sdwa v51, v51 dst_sel:BYTE_3 dst_unused:UNUSED_PAD src0_sel:DWORD
	v_or_b32_e32 v60, v53, v50
	v_or_b32_e32 v61, v52, v51
	ds_read_b128 v[50:53], v66 offset:64
	global_store_dwordx4 v0, v[58:61], s[0:1]
	s_waitcnt lgkmcnt(0)
; DI float sigmoidf_(float v) { return 1.f / (1.f + __expf(-v)); }
; DI void phaseA_tile(const P& p, int layer, int mt, int nt, char* lds) {
;     ...
;   if (seg >= 53) {
;     const bool isP = seg < 69;
;     unsigned* G = (unsigned*)(p.ws + (isP ? W_GP : W_GA)) + ((size_t)(((row0 >> 6) + wm) * 16 + (isP ? seg - 53 : seg - 69)) * 64 + lane) * 16;
; #pragma unroll
;     for (int mi = 0; mi < 4; ++mi) {
;       unsigned wv[4];
; #pragma unroll
;       for (int ni = 0; ni < 4; ++ni) {
;         unsigned w_ = 0u;
; #pragma unroll
;         for (int j = 0; j < 4; ++j) {
;           const float r = rr[wm * 64 + mi * 16 + fq * 4 + j];
;           w_ |= ((unsigned)(int)(sigmoidf_(acc[mi][ni][j] * r) * 255.f + 0.5f)) << (8 * j);
;         }
;         wv[ni] = w_;
;       }
;       *(u32x4*)(G + mi * 4) = u32x4{wv[0], wv[1], wv[2], wv[3]};
;     }
;     return;
	v_mul_f32_e32 v46, v46, v50
	v_mul_f32_e32 v42, v42, v50
	v_mul_f32_e32 v46, 0xbfb8aa3b, v46
	v_mul_f32_e32 v42, 0xbfb8aa3b, v42
	v_exp_f32_e32 v54, v46
	v_mul_f32_e32 v46, v47, v51
	v_exp_f32_e32 v55, v42
	v_mul_f32_e32 v42, v43, v51
	v_mul_f32_e32 v46, 0xbfb8aa3b, v46
	v_mul_f32_e32 v42, 0xbfb8aa3b, v42
	v_exp_f32_e32 v56, v46
	v_mul_f32_e32 v46, v48, v52
	v_exp_f32_e32 v57, v42
	v_mul_f32_e32 v42, v44, v52
	v_mul_f32_e32 v46, 0xbfb8aa3b, v46
	v_mul_f32_e32 v42, 0xbfb8aa3b, v42
	v_exp_f32_e32 v48, v46
	v_mul_f32_e32 v46, v49, v53
	v_exp_f32_e32 v49, v42
	v_mul_f32_e32 v42, v45, v53
	v_mul_f32_e32 v42, 0xbfb8aa3b, v42
	v_exp_f32_e32 v47, v42
	v_pk_add_f32 v[42:43], v[54:55], 1.0 op_sel_hi:[1,0]
	v_mul_f32_e32 v46, 0xbfb8aa3b, v46
	v_exp_f32_e32 v46, v46
	v_mul_f32_e32 v39, v39, v51
	v_mul_f32_e32 v39, 0xbfb8aa3b, v39
	v_rcp_f32_e32 v43, v43
	s_nop 0
	v_mul_f32_e32 v34, v34, v50
	v_mul_f32_e32 v34, 0xbfb8aa3b, v34
	v_mul_f32_e32 v38, v38, v50
	v_rcp_f32_e32 v42, v42
	s_nop 0
	v_pk_fma_f32 v[42:43], v[42:43], s[10:11], 0.5 op_sel_hi:[1,0,0]
	v_mul_f32_e32 v38, 0xbfb8aa3b, v38
	v_cvt_i32_f32_e32 v44, v43
	v_cvt_i32_f32_e32 v45, v42
	v_pk_add_f32 v[42:43], v[56:57], 1.0 op_sel_hi:[1,0]
	v_exp_f32_e32 v38, v38
	s_nop 0
	v_rcp_f32_e32 v43, v43
	s_nop 0
	s_nop 0
	v_rcp_f32_e32 v42, v42
	s_nop 0
	v_pk_fma_f32 v[42:43], v[42:43], s[10:11], 0.5 op_sel_hi:[1,0,0]
	s_nop 0
	v_cvt_i32_f32_e32 v42, v42
	v_cvt_i32_f32_e32 v43, v43
	v_lshlrev_b32_e32 v42, 8, v42
	v_lshlrev_b32_e32 v43, 8, v43
	v_or_b32_e32 v44, v43, v44
	v_or_b32_e32 v45, v42, v45
	v_pk_add_f32 v[42:43], v[48:49], 1.0 op_sel_hi:[1,0]
	s_nop 0
	s_nop 0
	v_rcp_f32_e32 v43, v43
	s_nop 0
	s_nop 0
	v_rcp_f32_e32 v42, v42
	s_nop 0
	v_pk_fma_f32 v[42:43], v[42:43], s[10:11], 0.5 op_sel_hi:[1,0,0]
	s_nop 0
	v_cvt_i32_f32_sdwa v42, v42 dst_sel:WORD_1 dst_unused:UNUSED_PAD src0_sel:DWORD
	v_cvt_i32_f32_sdwa v43, v43 dst_sel:WORD_1 dst_unused:UNUSED_PAD src0_sel:DWORD
	v_or_b32_e32 v45, v45, v42
	v_or_b32_e32 v44, v44, v43
	v_pk_add_f32 v[42:43], v[46:47], 1.0 op_sel_hi:[1,0]
	s_nop 0
	s_nop 0
	v_rcp_f32_e32 v43, v43
	s_nop 0
	s_nop 0
	v_rcp_f32_e32 v42, v42
	s_nop 0
	v_pk_fma_f32 v[42:43], v[42:43], s[10:11], 0.5 op_sel_hi:[1,0,0]
	s_nop 0
	v_cvt_i32_f32_sdwa v43, v43 dst_sel:BYTE_3 dst_unused:UNUSED_PAD src0_sel:DWORD
	v_cvt_i32_f32_sdwa v42, v42 dst_sel:BYTE_3 dst_unused:UNUSED_PAD src0_sel:DWORD
	v_or_b32_e32 v43, v44, v43
	v_exp_f32_e32 v44, v39
	v_mul_f32_e32 v39, v40, v52
	v_mul_f32_e32 v39, 0xbfb8aa3b, v39
	v_exp_f32_e32 v40, v39
	v_mul_f32_e32 v39, v41, v53
	v_mul_f32_e32 v39, 0xbfb8aa3b, v39
	v_exp_f32_e32 v46, v39
	v_exp_f32_e32 v39, v34
	v_mul_f32_e32 v34, v35, v51
	v_mul_f32_e32 v34, 0xbfb8aa3b, v34
	v_or_b32_e32 v42, v45, v42
	v_exp_f32_e32 v45, v34
	v_mul_f32_e32 v34, v36, v52
	v_mul_f32_e32 v34, 0xbfb8aa3b, v34
	v_exp_f32_e32 v41, v34
	v_mul_f32_e32 v34, v37, v53
	v_mul_f32_e32 v34, 0xbfb8aa3b, v34
	v_exp_f32_e32 v47, v34
	v_pk_add_f32 v[34:35], v[38:39], 1.0 op_sel_hi:[1,0]
	s_nop 0
	s_nop 0
	v_rcp_f32_e32 v35, v35
	s_nop 0
	s_nop 0
	v_rcp_f32_e32 v34, v34
	s_nop 0
	v_pk_fma_f32 v[34:35], v[34:35], s[10:11], 0.5 op_sel_hi:[1,0,0]
	s_nop 0
	v_cvt_i32_f32_e32 v36, v35
	v_cvt_i32_f32_e32 v37, v34
	v_pk_add_f32 v[34:35], v[44:45], 1.0 op_sel_hi:[1,0]
	s_nop 0
	s_nop 0
	v_rcp_f32_e32 v35, v35
	s_nop 0
	s_nop 0
	v_rcp_f32_e32 v34, v34
	s_nop 0
	v_pk_fma_f32 v[34:35], v[34:35], s[10:11], 0.5 op_sel_hi:[1,0,0]
	s_nop 0
	v_cvt_i32_f32_e32 v34, v34
	v_cvt_i32_f32_e32 v35, v35
	v_lshlrev_b32_e32 v34, 8, v34
	v_lshlrev_b32_e32 v35, 8, v35
	v_or_b32_e32 v36, v35, v36
	v_or_b32_e32 v37, v34, v37
	v_pk_add_f32 v[34:35], v[40:41], 1.0 op_sel_hi:[1,0]
	s_nop 0
	s_nop 0
	v_rcp_f32_e32 v35, v35
	s_nop 0
	s_nop 0
	v_rcp_f32_e32 v34, v34
	s_nop 0
	v_pk_fma_f32 v[34:35], v[34:35], s[10:11], 0.5 op_sel_hi:[1,0,0]
	s_nop 0
	v_cvt_i32_f32_sdwa v34, v34 dst_sel:WORD_1 dst_unused:UNUSED_PAD src0_sel:DWORD
	v_cvt_i32_f32_sdwa v35, v35 dst_sel:WORD_1 dst_unused:UNUSED_PAD src0_sel:DWORD
	v_or_b32_e32 v37, v37, v34
	v_or_b32_e32 v36, v36, v35
	v_pk_add_f32 v[34:35], v[46:47], 1.0 op_sel_hi:[1,0]
	s_nop 0
	s_nop 0
	v_rcp_f32_e32 v35, v35
	s_nop 0
	s_nop 0
	v_rcp_f32_e32 v34, v34
	s_nop 0
	v_pk_fma_f32 v[34:35], v[34:35], s[10:11], 0.5 op_sel_hi:[1,0,0]
	s_nop 0
	v_cvt_i32_f32_sdwa v34, v34 dst_sel:BYTE_3 dst_unused:UNUSED_PAD src0_sel:DWORD
	v_cvt_i32_f32_sdwa v35, v35 dst_sel:BYTE_3 dst_unused:UNUSED_PAD src0_sel:DWORD
	v_or_b32_e32 v44, v37, v34
	v_or_b32_e32 v45, v36, v35
	ds_read_b128 v[34:37], v66 offset:128
	global_store_dwordx4 v0, v[42:45], s[0:1] offset:16
	s_waitcnt lgkmcnt(0)
; DI float sigmoidf_(float v) { return 1.f / (1.f + __expf(-v)); }
; DI void phaseA_tile(const P& p, int layer, int mt, int nt, char* lds) {
;     ...
;   if (seg >= 53) {
;     const bool isP = seg < 69;
;     unsigned* G = (unsigned*)(p.ws + (isP ? W_GP : W_GA)) + ((size_t)(((row0 >> 6) + wm) * 16 + (isP ? seg - 53 : seg - 69)) * 64 + lane) * 16;
; #pragma unroll
;     for (int mi = 0; mi < 4; ++mi) {
;       unsigned wv[4];
; #pragma unroll
;       for (int ni = 0; ni < 4; ++ni) {
;         unsigned w_ = 0u;
; #pragma unroll
;         for (int j = 0; j < 4; ++j) {
;           const float r = rr[wm * 64 + mi * 16 + fq * 4 + j];
;           w_ |= ((unsigned)(int)(sigmoidf_(acc[mi][ni][j] * r) * 255.f + 0.5f)) << (8 * j);
;         }
;         wv[ni] = w_;
;       }
;       *(u32x4*)(G + mi * 4) = u32x4{wv[0], wv[1], wv[2], wv[3]};
;     }
;     return;
	v_mul_f32_e32 v31, v31, v35
	v_mul_f32_e32 v31, 0xbfb8aa3b, v31
	v_exp_f32_e32 v38, v31
	v_mul_f32_e32 v31, v32, v36
	v_mul_f32_e32 v31, 0xbfb8aa3b, v31
	v_exp_f32_e32 v32, v31
	v_mul_f32_e32 v31, v33, v37
	v_mul_f32_e32 v26, v26, v34
	v_mul_f32_e32 v31, 0xbfb8aa3b, v31
	v_mul_f32_e32 v26, 0xbfb8aa3b, v26
	v_mul_f32_e32 v30, v30, v34
	v_exp_f32_e32 v40, v31
	v_exp_f32_e32 v31, v26
	v_mul_f32_e32 v26, v27, v35
	v_mul_f32_e32 v30, 0xbfb8aa3b, v30
	v_mul_f32_e32 v26, 0xbfb8aa3b, v26
	v_exp_f32_e32 v30, v30
	v_exp_f32_e32 v39, v26
	v_mul_f32_e32 v26, v28, v36
	v_mul_f32_e32 v26, 0xbfb8aa3b, v26
	v_exp_f32_e32 v33, v26
	v_mul_f32_e32 v26, v29, v37
	v_mul_f32_e32 v26, 0xbfb8aa3b, v26
	v_exp_f32_e32 v41, v26
	v_pk_add_f32 v[26:27], v[30:31], 1.0 op_sel_hi:[1,0]
	v_mul_f32_e32 v23, v23, v35
	v_mul_f32_e32 v23, 0xbfb8aa3b, v23
	v_mul_f32_e32 v18, v18, v34
	v_mul_f32_e32 v18, 0xbfb8aa3b, v18
	v_rcp_f32_e32 v27, v27
	s_nop 0
	v_mul_f32_e32 v22, v22, v34
	v_mul_f32_e32 v22, 0xbfb8aa3b, v22
	v_exp_f32_e32 v22, v22
	v_rcp_f32_e32 v26, v26
	s_nop 0
	v_pk_fma_f32 v[26:27], v[26:27], s[10:11], 0.5 op_sel_hi:[1,0,0]
	s_nop 0
	v_cvt_i32_f32_e32 v28, v27
	v_cvt_i32_f32_e32 v29, v26
	v_pk_add_f32 v[26:27], v[38:39], 1.0 op_sel_hi:[1,0]
	s_nop 0
	s_nop 0
	v_rcp_f32_e32 v27, v27
	s_nop 0
	s_nop 0
	v_rcp_f32_e32 v26, v26
	s_nop 0
	v_pk_fma_f32 v[26:27], v[26:27], s[10:11], 0.5 op_sel_hi:[1,0,0]
	s_nop 0
	v_cvt_i32_f32_e32 v26, v26
	v_cvt_i32_f32_e32 v27, v27
	v_lshlrev_b32_e32 v26, 8, v26
	v_lshlrev_b32_e32 v27, 8, v27
	v_or_b32_e32 v28, v27, v28
	v_or_b32_e32 v29, v26, v29
	v_pk_add_f32 v[26:27], v[32:33], 1.0 op_sel_hi:[1,0]
	s_nop 0
	s_nop 0
	v_rcp_f32_e32 v27, v27
	s_nop 0
	s_nop 0
	v_rcp_f32_e32 v26, v26
	s_nop 0
	v_pk_fma_f32 v[26:27], v[26:27], s[10:11], 0.5 op_sel_hi:[1,0,0]
	s_nop 0
	v_cvt_i32_f32_sdwa v26, v26 dst_sel:WORD_1 dst_unused:UNUSED_PAD src0_sel:DWORD
	v_cvt_i32_f32_sdwa v27, v27 dst_sel:WORD_1 dst_unused:UNUSED_PAD src0_sel:DWORD
	v_or_b32_e32 v29, v29, v26
	v_or_b32_e32 v28, v28, v27
	v_pk_add_f32 v[26:27], v[40:41], 1.0 op_sel_hi:[1,0]
	s_nop 0
	s_nop 0
	v_rcp_f32_e32 v27, v27
	s_nop 0
	s_nop 0
	v_rcp_f32_e32 v26, v26
	s_nop 0
	v_pk_fma_f32 v[26:27], v[26:27], s[10:11], 0.5 op_sel_hi:[1,0,0]
	s_nop 0
	v_cvt_i32_f32_sdwa v27, v27 dst_sel:BYTE_3 dst_unused:UNUSED_PAD src0_sel:DWORD
	v_cvt_i32_f32_sdwa v26, v26 dst_sel:BYTE_3 dst_unused:UNUSED_PAD src0_sel:DWORD
	v_or_b32_e32 v27, v28, v27
	v_exp_f32_e32 v28, v23
	v_mul_f32_e32 v23, v24, v36
	v_mul_f32_e32 v23, 0xbfb8aa3b, v23
	v_exp_f32_e32 v24, v23
	v_mul_f32_e32 v23, v25, v37
	v_mul_f32_e32 v23, 0xbfb8aa3b, v23
	v_exp_f32_e32 v30, v23
	v_exp_f32_e32 v23, v18
	v_mul_f32_e32 v18, v19, v35
	v_mul_f32_e32 v18, 0xbfb8aa3b, v18
	v_or_b32_e32 v26, v29, v26
	v_exp_f32_e32 v29, v18
	v_mul_f32_e32 v18, v20, v36
	v_mul_f32_e32 v18, 0xbfb8aa3b, v18
	v_exp_f32_e32 v25, v18
	v_mul_f32_e32 v18, v21, v37
	v_mul_f32_e32 v18, 0xbfb8aa3b, v18
	v_exp_f32_e32 v31, v18
	v_pk_add_f32 v[18:19], v[22:23], 1.0 op_sel_hi:[1,0]
	s_nop 0
	s_nop 0
	v_rcp_f32_e32 v19, v19
	s_nop 0
	s_nop 0
	v_rcp_f32_e32 v18, v18
	s_nop 0
	v_pk_fma_f32 v[18:19], v[18:19], s[10:11], 0.5 op_sel_hi:[1,0,0]
	s_nop 0
	v_cvt_i32_f32_e32 v20, v19
	v_cvt_i32_f32_e32 v21, v18
	v_pk_add_f32 v[18:19], v[28:29], 1.0 op_sel_hi:[1,0]
	s_nop 0
	s_nop 0
	v_rcp_f32_e32 v19, v19
	s_nop 0
	s_nop 0
	v_rcp_f32_e32 v18, v18
	s_nop 0
	v_pk_fma_f32 v[18:19], v[18:19], s[10:11], 0.5 op_sel_hi:[1,0,0]
	s_nop 0
	v_cvt_i32_f32_e32 v18, v18
	v_cvt_i32_f32_e32 v19, v19
	v_lshlrev_b32_e32 v18, 8, v18
	v_lshlrev_b32_e32 v19, 8, v19
	v_or_b32_e32 v20, v19, v20
	v_or_b32_e32 v21, v18, v21
	v_pk_add_f32 v[18:19], v[24:25], 1.0 op_sel_hi:[1,0]
	s_nop 0
	s_nop 0
	v_rcp_f32_e32 v19, v19
	s_nop 0
	s_nop 0
	v_rcp_f32_e32 v18, v18
	s_nop 0
	v_pk_fma_f32 v[18:19], v[18:19], s[10:11], 0.5 op_sel_hi:[1,0,0]
	s_nop 0
	v_cvt_i32_f32_sdwa v18, v18 dst_sel:WORD_1 dst_unused:UNUSED_PAD src0_sel:DWORD
	v_cvt_i32_f32_sdwa v19, v19 dst_sel:WORD_1 dst_unused:UNUSED_PAD src0_sel:DWORD
	v_or_b32_e32 v21, v21, v18
	v_or_b32_e32 v20, v20, v19
	v_pk_add_f32 v[18:19], v[30:31], 1.0 op_sel_hi:[1,0]
	s_nop 0
	s_nop 0
	v_rcp_f32_e32 v19, v19
	s_nop 0
	s_nop 0
	v_rcp_f32_e32 v18, v18
	s_nop 0
	v_pk_fma_f32 v[18:19], v[18:19], s[10:11], 0.5 op_sel_hi:[1,0,0]
	s_nop 0
	v_cvt_i32_f32_sdwa v18, v18 dst_sel:BYTE_3 dst_unused:UNUSED_PAD src0_sel:DWORD
	v_cvt_i32_f32_sdwa v19, v19 dst_sel:BYTE_3 dst_unused:UNUSED_PAD src0_sel:DWORD
	v_or_b32_e32 v28, v21, v18
	v_or_b32_e32 v29, v20, v19
	ds_read_b128 v[18:21], v66 offset:192
	global_store_dwordx4 v0, v[26:29], s[0:1] offset:32
	s_waitcnt lgkmcnt(0)
; DI float sigmoidf_(float v) { return 1.f / (1.f + __expf(-v)); }
; DI void phaseA_tile(const P& p, int layer, int mt, int nt, char* lds) {
;     ...
;   if (seg >= 53) {
;     const bool isP = seg < 69;
;     unsigned* G = (unsigned*)(p.ws + (isP ? W_GP : W_GA)) + ((size_t)(((row0 >> 6) + wm) * 16 + (isP ? seg - 53 : seg - 69)) * 64 + lane) * 16;
; #pragma unroll
;     for (int mi = 0; mi < 4; ++mi) {
;       unsigned wv[4];
; #pragma unroll
;       for (int ni = 0; ni < 4; ++ni) {
;         unsigned w_ = 0u;
; #pragma unroll
;         for (int j = 0; j < 4; ++j) {
;           const float r = rr[wm * 64 + mi * 16 + fq * 4 + j];
;           w_ |= ((unsigned)(int)(sigmoidf_(acc[mi][ni][j] * r) * 255.f + 0.5f)) << (8 * j);
;         }
;         wv[ni] = w_;
;       }
;       *(u32x4*)(G + mi * 4) = u32x4{wv[0], wv[1], wv[2], wv[3]};
;     }
;     return;
	v_mul_f32_e32 v14, v14, v18
	v_mul_f32_e32 v10, v10, v18
	v_mul_f32_e32 v14, 0xbfb8aa3b, v14
	v_mul_f32_e32 v10, 0xbfb8aa3b, v10
	v_exp_f32_e32 v22, v14
	v_mul_f32_e32 v14, v15, v19
	v_exp_f32_e32 v23, v10
	v_mul_f32_e32 v10, v11, v19
	v_mul_f32_e32 v14, 0xbfb8aa3b, v14
	v_mul_f32_e32 v10, 0xbfb8aa3b, v10
	v_exp_f32_e32 v24, v14
	v_mul_f32_e32 v14, v16, v20
	v_exp_f32_e32 v25, v10
	v_mul_f32_e32 v10, v12, v20
	v_mul_f32_e32 v14, 0xbfb8aa3b, v14
	v_mul_f32_e32 v10, 0xbfb8aa3b, v10
	v_exp_f32_e32 v16, v14
	v_mul_f32_e32 v14, v17, v21
	v_exp_f32_e32 v17, v10
	v_mul_f32_e32 v10, v13, v21
	v_mul_f32_e32 v10, 0xbfb8aa3b, v10
	v_exp_f32_e32 v15, v10
	v_pk_add_f32 v[10:11], v[22:23], 1.0 op_sel_hi:[1,0]
	v_mul_f32_e32 v14, 0xbfb8aa3b, v14
	v_exp_f32_e32 v14, v14
	v_mul_f32_e32 v6, v6, v18
	v_mul_f32_e32 v2, v2, v18
	v_rcp_f32_e32 v11, v11
	s_nop 0
	v_mul_f32_e32 v6, 0xbfb8aa3b, v6
	v_mul_f32_e32 v2, 0xbfb8aa3b, v2
	v_rcp_f32_e32 v10, v10
	s_nop 0
	v_pk_fma_f32 v[10:11], v[10:11], s[10:11], 0.5 op_sel_hi:[1,0,0]
	s_nop 0
	v_cvt_i32_f32_e32 v12, v11
	v_cvt_i32_f32_e32 v13, v10
	v_pk_add_f32 v[10:11], v[24:25], 1.0 op_sel_hi:[1,0]
	s_nop 0
	s_nop 0
	v_rcp_f32_e32 v11, v11
	s_nop 0
	s_nop 0
	v_rcp_f32_e32 v10, v10
	s_nop 0
	v_pk_fma_f32 v[10:11], v[10:11], s[10:11], 0.5 op_sel_hi:[1,0,0]
	s_nop 0
	v_cvt_i32_f32_e32 v10, v10
	v_cvt_i32_f32_e32 v11, v11
	v_lshlrev_b32_e32 v10, 8, v10
	v_lshlrev_b32_e32 v11, 8, v11
	v_or_b32_e32 v12, v11, v12
	v_or_b32_e32 v13, v10, v13
	v_pk_add_f32 v[10:11], v[16:17], 1.0 op_sel_hi:[1,0]
	s_nop 0
	s_nop 0
	v_rcp_f32_e32 v11, v11
	s_nop 0
	s_nop 0
	v_rcp_f32_e32 v10, v10
	s_nop 0
	v_pk_fma_f32 v[10:11], v[10:11], s[10:11], 0.5 op_sel_hi:[1,0,0]
	s_nop 0
	v_cvt_i32_f32_sdwa v10, v10 dst_sel:WORD_1 dst_unused:UNUSED_PAD src0_sel:DWORD
	v_cvt_i32_f32_sdwa v11, v11 dst_sel:WORD_1 dst_unused:UNUSED_PAD src0_sel:DWORD
	v_or_b32_e32 v13, v13, v10
	v_or_b32_e32 v12, v12, v11
	v_pk_add_f32 v[10:11], v[14:15], 1.0 op_sel_hi:[1,0]
	s_nop 0
	s_nop 0
	v_rcp_f32_e32 v11, v11
	s_nop 0
	s_nop 0
	v_rcp_f32_e32 v10, v10
	s_nop 0
	v_pk_fma_f32 v[10:11], v[10:11], s[10:11], 0.5 op_sel_hi:[1,0,0]
	s_nop 0
	v_cvt_i32_f32_sdwa v10, v10 dst_sel:BYTE_3 dst_unused:UNUSED_PAD src0_sel:DWORD
	v_cvt_i32_f32_sdwa v11, v11 dst_sel:BYTE_3 dst_unused:UNUSED_PAD src0_sel:DWORD
	v_or_b32_e32 v10, v13, v10
	v_or_b32_e32 v11, v12, v11
	v_exp_f32_e32 v12, v6
	v_mul_f32_e32 v6, v7, v19
	v_exp_f32_e32 v13, v2
	v_mul_f32_e32 v2, v3, v19
	v_mul_f32_e32 v6, 0xbfb8aa3b, v6
	v_mul_f32_e32 v2, 0xbfb8aa3b, v2
	v_exp_f32_e32 v14, v6
	v_mul_f32_e32 v6, v8, v20
	v_exp_f32_e32 v15, v2
	v_mul_f32_e32 v2, v4, v20
	v_mul_f32_e32 v6, 0xbfb8aa3b, v6
	v_mul_f32_e32 v2, 0xbfb8aa3b, v2
	v_exp_f32_e32 v8, v6
	v_mul_f32_e32 v6, v9, v21
	v_exp_f32_e32 v9, v2
	v_mul_f32_e32 v2, v5, v21
	v_mul_f32_e32 v2, 0xbfb8aa3b, v2
	v_exp_f32_e32 v7, v2
	v_pk_add_f32 v[2:3], v[12:13], 1.0 op_sel_hi:[1,0]
	v_mul_f32_e32 v6, 0xbfb8aa3b, v6
	v_exp_f32_e32 v6, v6
	v_rcp_f32_e32 v3, v3
	s_nop 0
	s_nop 0
	v_rcp_f32_e32 v2, v2
	s_nop 0
	v_pk_fma_f32 v[2:3], v[2:3], s[10:11], 0.5 op_sel_hi:[1,0,0]
	s_nop 0
	v_cvt_i32_f32_e32 v4, v3
	v_cvt_i32_f32_e32 v5, v2
	v_pk_add_f32 v[2:3], v[14:15], 1.0 op_sel_hi:[1,0]
	s_nop 0
	s_nop 0
	v_rcp_f32_e32 v3, v3
	s_nop 0
	s_nop 0
	v_rcp_f32_e32 v2, v2
	s_nop 0
	v_pk_fma_f32 v[2:3], v[2:3], s[10:11], 0.5 op_sel_hi:[1,0,0]
	s_nop 0
	v_cvt_i32_f32_e32 v2, v2
	v_cvt_i32_f32_e32 v3, v3
	v_lshlrev_b32_e32 v2, 8, v2
	v_lshlrev_b32_e32 v3, 8, v3
	v_or_b32_e32 v4, v3, v4
	v_or_b32_e32 v5, v2, v5
	v_pk_add_f32 v[2:3], v[8:9], 1.0 op_sel_hi:[1,0]
	s_nop 0
	s_nop 0
	v_rcp_f32_e32 v3, v3
	s_nop 0
	s_nop 0
	v_rcp_f32_e32 v2, v2
	s_nop 0
	v_pk_fma_f32 v[2:3], v[2:3], s[10:11], 0.5 op_sel_hi:[1,0,0]
	s_nop 0
	v_cvt_i32_f32_sdwa v2, v2 dst_sel:WORD_1 dst_unused:UNUSED_PAD src0_sel:DWORD
	v_cvt_i32_f32_sdwa v3, v3 dst_sel:WORD_1 dst_unused:UNUSED_PAD src0_sel:DWORD
	v_or_b32_e32 v5, v5, v2
	v_or_b32_e32 v4, v4, v3
	v_pk_add_f32 v[2:3], v[6:7], 1.0 op_sel_hi:[1,0]
	s_nop 0
	s_nop 0
	v_rcp_f32_e32 v3, v3
	s_nop 0
	s_movk_i32 s5, 0x2000
	v_rcp_f32_e32 v2, v2
	s_nop 0
	v_pk_fma_f32 v[2:3], v[2:3], s[10:11], 0.5 op_sel_hi:[1,0,0]
	s_nop 0
	v_cvt_i32_f32_sdwa v2, v2 dst_sel:BYTE_3 dst_unused:UNUSED_PAD src0_sel:DWORD
	v_cvt_i32_f32_sdwa v3, v3 dst_sel:BYTE_3 dst_unused:UNUSED_PAD src0_sel:DWORD
	v_or_b32_e32 v12, v5, v2
	v_or_b32_e32 v13, v4, v3
	global_store_dwordx4 v0, v[10:13], s[0:1] offset:48
	s_branch .LBB0_1183

; DI unsigned pk2(float lo, float hi) { unsigned r; asm("v_cvt_pk_bf16_f32 %0, %1, %2" : "=v"(r) : "v"(lo), "v"(hi)); return r; }
; DI float siluf_(float v) { return v / (1.f + __expf(-v)); }
; DI void phaseA_tile(const P& p, int layer, int mt, int nt, char* lds) {
;     ...
;     if (seg < 8) {
;       const int col = seg * 64 + cc * 4;
;       *(u32x2*)((bf16_t*)(p.ws + W_U) + (size_t)row * 512 + col) = u32x2{pk2(v.x, v.y), pk2(v.z, v.w)};
;       if (!isS) { if (t >= TP - 15) *(f32x4*)(out + O_PP + ((size_t)(layer * 16 + bb) * 15 + (t - (TP - 15))) * 512 + col) = v; }
;       else { if (t >= TS - 15) *(f32x4*)(out + O_PS + ((size_t)(layer * 8 + bb) * 15 + (t - (TS - 15))) * 512 + col) = v; }
;     } else if (seg < 16 || (seg >= 45 && seg < 53)) {
;       bf16_t* Z = (bf16_t*)(p.ws + (seg < 16 ? W_ZP : W_ZA)) + (size_t)row * 512 + (seg < 16 ? seg - 8 : seg - 45) * 64 + cc * 4;
;       *(u32x2*)Z = u32x2{pk2(siluf_(v.x), siluf_(v.y)), pk2(siluf_(v.z), siluf_(v.w))};
.LBB0_1677:
	s_and_b64 vcc, exec, s[12:13]
	s_cbranch_vccz .LBB0_1679
	v_mul_f32_e32 v0, 0xbfb8aa3b, v66
	v_exp_f32_e32 v0, v0
	v_ashrrev_i32_e32 v85, 31, v84
	v_lshlrev_b64 v[86:87], 10, v[84:85]
	v_lshl_add_u64 v[86:87], v[80:81], 0, v[86:87]
	v_add_f32_e32 v0, 1.0, v0
	s_nop 0
	v_rcp_f32_e32 v85, v0
	s_nop 0
	v_mul_f32_e32 v0, v66, v85
	v_mul_f32_e32 v85, 0xbfb8aa3b, v67
	v_exp_f32_e32 v85, v85
	s_nop 0
	v_add_f32_e32 v85, 1.0, v85
	s_nop 0
	v_rcp_f32_e32 v98, v85
	s_nop 0
	v_mul_f32_e32 v85, v67, v98
	v_cvt_pk_bf16_f32 v98, v0, v85
	v_mul_f32_e32 v0, 0xbfb8aa3b, v68
	v_exp_f32_e32 v0, v0
	s_nop 0
	v_add_f32_e32 v0, 1.0, v0
	s_nop 0
	v_rcp_f32_e32 v85, v0
	s_nop 0
	v_mul_f32_e32 v0, v68, v85
	v_mul_f32_e32 v85, 0xbfb8aa3b, v69
	v_exp_f32_e32 v85, v85
	s_nop 0
	v_add_f32_e32 v85, 1.0, v85
	s_nop 0
	v_rcp_f32_e32 v99, v85
	s_nop 0
	v_mul_f32_e32 v85, v69, v99
	v_cvt_pk_bf16_f32 v99, v0, v85
	global_store_dwordx2 v[86:87], v[98:99], off

; DI unsigned pk2(float lo, float hi) { unsigned r; asm("v_cvt_pk_bf16_f32 %0, %1, %2" : "=v"(r) : "v"(lo), "v"(hi)); return r; }
; DI float siluf_(float v) { return v / (1.f + __expf(-v)); }
; DI void phaseA_tile(const P& p, int layer, int mt, int nt, char* lds) {
;     ...
;     if (seg < 8) {
;       const int col = seg * 64 + cc * 4;
;       *(u32x2*)((bf16_t*)(p.ws + W_U) + (size_t)row * 512 + col) = u32x2{pk2(v.x, v.y), pk2(v.z, v.w)};
;       if (!isS) { if (t >= TP - 15) *(f32x4*)(out + O_PP + ((size_t)(layer * 16 + bb) * 15 + (t - (TP - 15))) * 512 + col) = v; }
;       else { if (t >= TS - 15) *(f32x4*)(out + O_PS + ((size_t)(layer * 8 + bb) * 15 + (t - (TS - 15))) * 512 + col) = v; }
;     } else if (seg < 16 || (seg >= 45 && seg < 53)) {
;       bf16_t* Z = (bf16_t*)(p.ws + (seg < 16 ? W_ZP : W_ZA)) + (size_t)row * 512 + (seg < 16 ? seg - 8 : seg - 45) * 64 + cc * 4;
;       *(u32x2*)Z = u32x2{pk2(siluf_(v.x), siluf_(v.y)), pk2(siluf_(v.z), siluf_(v.w))};
.LBB0_1697:
	s_and_b64 vcc, exec, s[12:13]
	s_cbranch_vccz .LBB0_1699
	v_mul_f32_e32 v0, 0xbfb8aa3b, v66
	v_exp_f32_e32 v0, v0
	v_ashrrev_i32_e32 v87, 31, v86
	v_lshlrev_b64 v[84:85], 10, v[86:87]
	v_lshl_add_u64 v[84:85], v[80:81], 0, v[84:85]
	v_add_f32_e32 v0, 1.0, v0
	s_nop 0
	v_rcp_f32_e32 v87, v0
	s_nop 0
	v_mul_f32_e32 v0, v66, v87
	v_mul_f32_e32 v87, 0xbfb8aa3b, v67
	v_exp_f32_e32 v87, v87
	s_nop 0
	v_add_f32_e32 v87, 1.0, v87
	s_nop 0
	v_rcp_f32_e32 v97, v87
	s_nop 0
	v_mul_f32_e32 v87, v67, v97
	v_cvt_pk_bf16_f32 v98, v0, v87
	v_mul_f32_e32 v0, 0xbfb8aa3b, v68
	v_exp_f32_e32 v0, v0
	s_nop 0
	v_add_f32_e32 v0, 1.0, v0
	s_nop 0
	v_rcp_f32_e32 v87, v0
	s_nop 0
	v_mul_f32_e32 v0, v68, v87
	v_mul_f32_e32 v87, 0xbfb8aa3b, v69
	v_exp_f32_e32 v87, v87
	s_nop 0
	v_add_f32_e32 v87, 1.0, v87
	s_nop 0
	v_rcp_f32_e32 v97, v87
	s_nop 0
	v_mul_f32_e32 v87, v69, v97
	v_cvt_pk_bf16_f32 v99, v0, v87
	global_store_dwordx2 v[84:85], v[98:99], off

; DI float sigmoidf_(float v) { return 1.f / (1.f + __expf(-v)); }
; DI void phaseA_tile(const P& p, int layer, int mt, int nt, char* lds) {
;     ...
;   if (seg >= 53) {
;     const bool isP = seg < 69;
;     unsigned* G = (unsigned*)(p.ws + (isP ? W_GP : W_GA)) + ((size_t)(((row0 >> 6) + wm) * 16 + (isP ? seg - 53 : seg - 69)) * 64 + lane) * 16;
; #pragma unroll
;     for (int mi = 0; mi < 4; ++mi) {
;       unsigned wv[4];
; #pragma unroll
;       for (int ni = 0; ni < 4; ++ni) {
;         unsigned w_ = 0u;
; #pragma unroll
;         for (int j = 0; j < 4; ++j) {
;           const float r = rr[wm * 64 + mi * 16 + fq * 4 + j];
;           w_ |= ((unsigned)(int)(sigmoidf_(acc[mi][ni][j] * r) * 255.f + 0.5f)) << (8 * j);
;         }
;         wv[ni] = w_;
;       }
;       *(u32x4*)(G + mi * 4) = u32x4{wv[0], wv[1], wv[2], wv[3]};
;     }
;     return;
.LBB0_1985:
	s_and_b64 vcc, exec, s[0:1]
	s_cbranch_vccz .LBB0_1588
	v_lshlrev_b32_e32 v66, 2, v127
	v_lshl_add_u32 v66, s7, 2, v66
	v_add_u32_e32 v66, 0x10800, v66
	ds_read_b128 v[68:71], v66
	s_cmpk_lt_u32 s29, 0x45
	s_cselect_b64 s[0:1], -1, 0
	s_and_b64 s[4:5], s[0:1], exec
	s_mov_b32 s4, 0x17ca2000
	s_waitcnt lgkmcnt(0)
	v_mul_f32_e32 v63, v63, v69
	v_mul_f32_e32 v63, 0xbfb8aa3b, v63
	s_cselect_b32 s4, s4, 0x19d22000
	v_exp_f32_e32 v72, v63
	v_mul_f32_e32 v63, v64, v70
	s_add_u32 s4, s90, s4
	v_mul_f32_e32 v63, 0xbfb8aa3b, v63
	s_addc_u32 s5, s91, 0
	s_lshl_b32 s6, s36, 5
	s_lshl_b32 s8, s48, 4
	v_exp_f32_e32 v64, v63
	v_mul_f32_e32 v63, v65, v71
	v_mul_f32_e32 v58, v58, v68
	s_and_b64 s[0:1], s[0:1], exec
	v_mul_f32_e32 v63, 0xbfb8aa3b, v63
	v_mul_f32_e32 v58, 0xbfb8aa3b, v58
	s_movk_i32 s0, 0xffcb
	v_mul_f32_e32 v62, v62, v68
	v_exp_f32_e32 v74, v63
	v_exp_f32_e32 v63, v58
	v_mul_f32_e32 v58, v59, v69
	s_cselect_b32 s0, s0, 0xffffffbb
	s_add_i32 s1, s8, s6
	v_mul_f32_e32 v62, 0xbfb8aa3b, v62
	v_mul_f32_e32 v58, 0xbfb8aa3b, v58
	s_add_i32 s1, s1, s29
	v_exp_f32_e32 v62, v62
	v_exp_f32_e32 v73, v58
	v_mul_f32_e32 v58, v60, v70
	s_add_i32 s0, s1, s0
	v_mul_f32_e32 v58, 0xbfb8aa3b, v58
	s_ashr_i32 s1, s0, 31
	v_exp_f32_e32 v65, v58
	v_mul_f32_e32 v58, v61, v71
	s_lshl_b64 s[0:1], s[0:1], 12
	v_mul_f32_e32 v58, 0xbfb8aa3b, v58
	s_add_u32 s0, s4, s0
	v_exp_f32_e32 v75, v58
	v_pk_add_f32 v[58:59], v[62:63], 1.0 op_sel_hi:[1,0]
	s_addc_u32 s1, s5, s1
	s_mov_b32 s6, 0x437f0000
	v_mul_f32_e32 v55, v55, v69
	v_mul_f32_e32 v55, 0xbfb8aa3b, v55
	v_rcp_f32_e32 v59, v59
	s_nop 0
	v_mul_f32_e32 v50, v50, v68
	v_mul_f32_e32 v50, 0xbfb8aa3b, v50
	v_mul_f32_e32 v54, v54, v68
	v_rcp_f32_e32 v58, v58
	s_nop 0
	v_pk_fma_f32 v[58:59], v[58:59], s[6:7], 0.5 op_sel_hi:[1,0,0]
	v_mul_f32_e32 v54, 0xbfb8aa3b, v54
	v_cvt_i32_f32_e32 v60, v59
	v_cvt_i32_f32_e32 v61, v58
	v_pk_add_f32 v[58:59], v[72:73], 1.0 op_sel_hi:[1,0]
	v_exp_f32_e32 v54, v54
	v_lshlrev_b32_e32 v0, 6, v152
	v_rcp_f32_e32 v59, v59
	s_nop 0
	s_nop 0
	v_rcp_f32_e32 v58, v58
	s_nop 0
	v_pk_fma_f32 v[58:59], v[58:59], s[6:7], 0.5 op_sel_hi:[1,0,0]
	s_nop 0
	v_cvt_i32_f32_e32 v58, v58
	v_cvt_i32_f32_e32 v59, v59
	v_lshlrev_b32_e32 v58, 8, v58
	v_lshlrev_b32_e32 v59, 8, v59
	v_or_b32_e32 v60, v59, v60
	v_or_b32_e32 v61, v58, v61
	v_pk_add_f32 v[58:59], v[64:65], 1.0 op_sel_hi:[1,0]
	s_nop 0
	s_nop 0
	v_rcp_f32_e32 v59, v59
	s_nop 0
	s_nop 0
	v_rcp_f32_e32 v58, v58
	s_nop 0
	v_pk_fma_f32 v[58:59], v[58:59], s[6:7], 0.5 op_sel_hi:[1,0,0]
	s_nop 0
	v_cvt_i32_f32_sdwa v58, v58 dst_sel:WORD_1 dst_unused:UNUSED_PAD src0_sel:DWORD
	v_cvt_i32_f32_sdwa v59, v59 dst_sel:WORD_1 dst_unused:UNUSED_PAD src0_sel:DWORD
	v_or_b32_e32 v61, v61, v58
	v_or_b32_e32 v60, v60, v59
	v_pk_add_f32 v[58:59], v[74:75], 1.0 op_sel_hi:[1,0]
	s_nop 0
	s_nop 0
	v_rcp_f32_e32 v59, v59
	s_nop 0
	s_nop 0
	v_rcp_f32_e32 v58, v58
	s_nop 0
	v_pk_fma_f32 v[58:59], v[58:59], s[6:7], 0.5 op_sel_hi:[1,0,0]
	s_nop 0
	v_cvt_i32_f32_sdwa v59, v59 dst_sel:BYTE_3 dst_unused:UNUSED_PAD src0_sel:DWORD
	v_cvt_i32_f32_sdwa v58, v58 dst_sel:BYTE_3 dst_unused:UNUSED_PAD src0_sel:DWORD
	v_or_b32_e32 v59, v60, v59
	v_exp_f32_e32 v60, v55
	v_mul_f32_e32 v55, v56, v70
	v_mul_f32_e32 v55, 0xbfb8aa3b, v55
	v_exp_f32_e32 v56, v55
	v_mul_f32_e32 v55, v57, v71
	v_mul_f32_e32 v55, 0xbfb8aa3b, v55
	v_exp_f32_e32 v62, v55
	v_exp_f32_e32 v55, v50
	v_mul_f32_e32 v50, v51, v69
	v_mul_f32_e32 v50, 0xbfb8aa3b, v50
	v_or_b32_e32 v58, v61, v58
	v_exp_f32_e32 v61, v50
	v_mul_f32_e32 v50, v52, v70
	v_mul_f32_e32 v50, 0xbfb8aa3b, v50
	v_exp_f32_e32 v57, v50
	v_mul_f32_e32 v50, v53, v71
	v_mul_f32_e32 v50, 0xbfb8aa3b, v50
	v_exp_f32_e32 v63, v50
	v_pk_add_f32 v[50:51], v[54:55], 1.0 op_sel_hi:[1,0]
	s_nop 0
	s_nop 0
	v_rcp_f32_e32 v51, v51
	s_nop 0
	s_nop 0
	v_rcp_f32_e32 v50, v50
	s_nop 0
	v_pk_fma_f32 v[50:51], v[50:51], s[6:7], 0.5 op_sel_hi:[1,0,0]
	s_nop 0
	v_cvt_i32_f32_e32 v52, v51
	v_cvt_i32_f32_e32 v53, v50
	v_pk_add_f32 v[50:51], v[60:61], 1.0 op_sel_hi:[1,0]
	s_nop 0
	s_nop 0
	v_rcp_f32_e32 v51, v51
	s_nop 0
	s_nop 0
	v_rcp_f32_e32 v50, v50
	s_nop 0
	v_pk_fma_f32 v[50:51], v[50:51], s[6:7], 0.5 op_sel_hi:[1,0,0]
	s_nop 0
	v_cvt_i32_f32_e32 v50, v50
	v_cvt_i32_f32_e32 v51, v51
	v_lshlrev_b32_e32 v50, 8, v50
	v_lshlrev_b32_e32 v51, 8, v51
	v_or_b32_e32 v52, v51, v52
	v_or_b32_e32 v53, v50, v53
	v_pk_add_f32 v[50:51], v[56:57], 1.0 op_sel_hi:[1,0]
	s_nop 0
	s_nop 0
	v_rcp_f32_e32 v51, v51
	s_nop 0
	s_nop 0
	v_rcp_f32_e32 v50, v50
	s_nop 0
	v_pk_fma_f32 v[50:51], v[50:51], s[6:7], 0.5 op_sel_hi:[1,0,0]
	s_nop 0
	v_cvt_i32_f32_sdwa v50, v50 dst_sel:WORD_1 dst_unused:UNUSED_PAD src0_sel:DWORD
	v_cvt_i32_f32_sdwa v51, v51 dst_sel:WORD_1 dst_unused:UNUSED_PAD src0_sel:DWORD
	v_or_b32_e32 v53, v53, v50
	v_or_b32_e32 v52, v52, v51
	v_pk_add_f32 v[50:51], v[62:63], 1.0 op_sel_hi:[1,0]
	s_nop 0
	s_nop 0
	v_rcp_f32_e32 v51, v51
	s_nop 0
	s_nop 0
	v_rcp_f32_e32 v50, v50
	s_nop 0
	v_pk_fma_f32 v[50:51], v[50:51], s[6:7], 0.5 op_sel_hi:[1,0,0]
	s_nop 0
	v_cvt_i32_f32_sdwa v50, v50 dst_sel:BYTE_3 dst_unused:UNUSED_PAD src0_sel:DWORD
	v_cvt_i32_f32_sdwa v51, v51 dst_sel:BYTE_3 dst_unused:UNUSED_PAD src0_sel:DWORD
	v_or_b32_e32 v60, v53, v50
	v_or_b32_e32 v61, v52, v51
	ds_read_b128 v[50:53], v66 offset:64
	global_store_dwordx4 v0, v[58:61], s[0:1]
	s_waitcnt lgkmcnt(0)
; DI float sigmoidf_(float v) { return 1.f / (1.f + __expf(-v)); }
; DI void phaseA_tile(const P& p, int layer, int mt, int nt, char* lds) {
;     ...
;   if (seg >= 53) {
;     const bool isP = seg < 69;
;     unsigned* G = (unsigned*)(p.ws + (isP ? W_GP : W_GA)) + ((size_t)(((row0 >> 6) + wm) * 16 + (isP ? seg - 53 : seg - 69)) * 64 + lane) * 16;
; #pragma unroll
;     for (int mi = 0; mi < 4; ++mi) {
;       unsigned wv[4];
; #pragma unroll
;       for (int ni = 0; ni < 4; ++ni) {
;         unsigned w_ = 0u;
; #pragma unroll
;         for (int j = 0; j < 4; ++j) {
;           const float r = rr[wm * 64 + mi * 16 + fq * 4 + j];
;           w_ |= ((unsigned)(int)(sigmoidf_(acc[mi][ni][j] * r) * 255.f + 0.5f)) << (8 * j);
;         }
;         wv[ni] = w_;
;       }
;       *(u32x4*)(G + mi * 4) = u32x4{wv[0], wv[1], wv[2], wv[3]};
;     }
;     return;
	v_mul_f32_e32 v46, v46, v50
	v_mul_f32_e32 v42, v42, v50
	v_mul_f32_e32 v46, 0xbfb8aa3b, v46
	v_mul_f32_e32 v42, 0xbfb8aa3b, v42
	v_exp_f32_e32 v54, v46
	v_mul_f32_e32 v46, v47, v51
	v_exp_f32_e32 v55, v42
	v_mul_f32_e32 v42, v43, v51
	v_mul_f32_e32 v46, 0xbfb8aa3b, v46
	v_mul_f32_e32 v42, 0xbfb8aa3b, v42
	v_exp_f32_e32 v56, v46
	v_mul_f32_e32 v46, v48, v52
	v_exp_f32_e32 v57, v42
	v_mul_f32_e32 v42, v44, v52
	v_mul_f32_e32 v46, 0xbfb8aa3b, v46
	v_mul_f32_e32 v42, 0xbfb8aa3b, v42
	v_exp_f32_e32 v48, v46
	v_mul_f32_e32 v46, v49, v53
	v_exp_f32_e32 v49, v42
	v_mul_f32_e32 v42, v45, v53
	v_mul_f32_e32 v42, 0xbfb8aa3b, v42
	v_exp_f32_e32 v47, v42
	v_pk_add_f32 v[42:43], v[54:55], 1.0 op_sel_hi:[1,0]
	v_mul_f32_e32 v46, 0xbfb8aa3b, v46
	v_exp_f32_e32 v46, v46
	v_mul_f32_e32 v39, v39, v51
	v_mul_f32_e32 v39, 0xbfb8aa3b, v39
	v_rcp_f32_e32 v43, v43
	s_nop 0
	v_mul_f32_e32 v34, v34, v50
	v_mul_f32_e32 v34, 0xbfb8aa3b, v34
	v_mul_f32_e32 v38, v38, v50
	v_rcp_f32_e32 v42, v42
	s_nop 0
	v_pk_fma_f32 v[42:43], v[42:43], s[6:7], 0.5 op_sel_hi:[1,0,0]
	v_mul_f32_e32 v38, 0xbfb8aa3b, v38
	v_cvt_i32_f32_e32 v44, v43
	v_cvt_i32_f32_e32 v45, v42
	v_pk_add_f32 v[42:43], v[56:57], 1.0 op_sel_hi:[1,0]
	v_exp_f32_e32 v38, v38
	s_nop 0
	v_rcp_f32_e32 v43, v43
	s_nop 0
	s_nop 0
	v_rcp_f32_e32 v42, v42
	s_nop 0
	v_pk_fma_f32 v[42:43], v[42:43], s[6:7], 0.5 op_sel_hi:[1,0,0]
	s_nop 0
	v_cvt_i32_f32_e32 v42, v42
	v_cvt_i32_f32_e32 v43, v43
	v_lshlrev_b32_e32 v42, 8, v42
	v_lshlrev_b32_e32 v43, 8, v43
	v_or_b32_e32 v44, v43, v44
	v_or_b32_e32 v45, v42, v45
	v_pk_add_f32 v[42:43], v[48:49], 1.0 op_sel_hi:[1,0]
	s_nop 0
	s_nop 0
	v_rcp_f32_e32 v43, v43
	s_nop 0
	s_nop 0
	v_rcp_f32_e32 v42, v42
	s_nop 0
	v_pk_fma_f32 v[42:43], v[42:43], s[6:7], 0.5 op_sel_hi:[1,0,0]
	s_nop 0
	v_cvt_i32_f32_sdwa v42, v42 dst_sel:WORD_1 dst_unused:UNUSED_PAD src0_sel:DWORD
	v_cvt_i32_f32_sdwa v43, v43 dst_sel:WORD_1 dst_unused:UNUSED_PAD src0_sel:DWORD
	v_or_b32_e32 v45, v45, v42
	v_or_b32_e32 v44, v44, v43
	v_pk_add_f32 v[42:43], v[46:47], 1.0 op_sel_hi:[1,0]
	s_nop 0
	s_nop 0
	v_rcp_f32_e32 v43, v43
	s_nop 0
	s_nop 0
	v_rcp_f32_e32 v42, v42
	s_nop 0
	v_pk_fma_f32 v[42:43], v[42:43], s[6:7], 0.5 op_sel_hi:[1,0,0]
	s_nop 0
	v_cvt_i32_f32_sdwa v43, v43 dst_sel:BYTE_3 dst_unused:UNUSED_PAD src0_sel:DWORD
	v_cvt_i32_f32_sdwa v42, v42 dst_sel:BYTE_3 dst_unused:UNUSED_PAD src0_sel:DWORD
	v_or_b32_e32 v43, v44, v43
	v_exp_f32_e32 v44, v39
	v_mul_f32_e32 v39, v40, v52
	v_mul_f32_e32 v39, 0xbfb8aa3b, v39
	v_exp_f32_e32 v40, v39
	v_mul_f32_e32 v39, v41, v53
	v_mul_f32_e32 v39, 0xbfb8aa3b, v39
	v_exp_f32_e32 v46, v39
	v_exp_f32_e32 v39, v34
	v_mul_f32_e32 v34, v35, v51
	v_mul_f32_e32 v34, 0xbfb8aa3b, v34
	v_or_b32_e32 v42, v45, v42
	v_exp_f32_e32 v45, v34
	v_mul_f32_e32 v34, v36, v52
	v_mul_f32_e32 v34, 0xbfb8aa3b, v34
	v_exp_f32_e32 v41, v34
	v_mul_f32_e32 v34, v37, v53
	v_mul_f32_e32 v34, 0xbfb8aa3b, v34
	v_exp_f32_e32 v47, v34
	v_pk_add_f32 v[34:35], v[38:39], 1.0 op_sel_hi:[1,0]
	s_nop 0
	s_nop 0
	v_rcp_f32_e32 v35, v35
	s_nop 0
	s_nop 0
	v_rcp_f32_e32 v34, v34
	s_nop 0
	v_pk_fma_f32 v[34:35], v[34:35], s[6:7], 0.5 op_sel_hi:[1,0,0]
	s_nop 0
	v_cvt_i32_f32_e32 v36, v35
	v_cvt_i32_f32_e32 v37, v34
	v_pk_add_f32 v[34:35], v[44:45], 1.0 op_sel_hi:[1,0]
	s_nop 0
	s_nop 0
	v_rcp_f32_e32 v35, v35
	s_nop 0
	s_nop 0
	v_rcp_f32_e32 v34, v34
	s_nop 0
	v_pk_fma_f32 v[34:35], v[34:35], s[6:7], 0.5 op_sel_hi:[1,0,0]
	s_nop 0
	v_cvt_i32_f32_e32 v34, v34
	v_cvt_i32_f32_e32 v35, v35
	v_lshlrev_b32_e32 v34, 8, v34
	v_lshlrev_b32_e32 v35, 8, v35
	v_or_b32_e32 v36, v35, v36
	v_or_b32_e32 v37, v34, v37
	v_pk_add_f32 v[34:35], v[40:41], 1.0 op_sel_hi:[1,0]
	s_nop 0
	s_nop 0
	v_rcp_f32_e32 v35, v35
	s_nop 0
	s_nop 0
	v_rcp_f32_e32 v34, v34
	s_nop 0
	v_pk_fma_f32 v[34:35], v[34:35], s[6:7], 0.5 op_sel_hi:[1,0,0]
	s_nop 0
	v_cvt_i32_f32_sdwa v34, v34 dst_sel:WORD_1 dst_unused:UNUSED_PAD src0_sel:DWORD
	v_cvt_i32_f32_sdwa v35, v35 dst_sel:WORD_1 dst_unused:UNUSED_PAD src0_sel:DWORD
	v_or_b32_e32 v37, v37, v34
	v_or_b32_e32 v36, v36, v35
	v_pk_add_f32 v[34:35], v[46:47], 1.0 op_sel_hi:[1,0]
	s_nop 0
	s_nop 0
	v_rcp_f32_e32 v35, v35
	s_nop 0
	s_nop 0
	v_rcp_f32_e32 v34, v34
	s_nop 0
	v_pk_fma_f32 v[34:35], v[34:35], s[6:7], 0.5 op_sel_hi:[1,0,0]
	s_nop 0
	v_cvt_i32_f32_sdwa v34, v34 dst_sel:BYTE_3 dst_unused:UNUSED_PAD src0_sel:DWORD
	v_cvt_i32_f32_sdwa v35, v35 dst_sel:BYTE_3 dst_unused:UNUSED_PAD src0_sel:DWORD
	v_or_b32_e32 v44, v37, v34
	v_or_b32_e32 v45, v36, v35
	ds_read_b128 v[34:37], v66 offset:128
	global_store_dwordx4 v0, v[42:45], s[0:1] offset:16
	s_waitcnt lgkmcnt(0)
; DI float sigmoidf_(float v) { return 1.f / (1.f + __expf(-v)); }
; DI void phaseA_tile(const P& p, int layer, int mt, int nt, char* lds) {
;     ...
;   if (seg >= 53) {
;     const bool isP = seg < 69;
;     unsigned* G = (unsigned*)(p.ws + (isP ? W_GP : W_GA)) + ((size_t)(((row0 >> 6) + wm) * 16 + (isP ? seg - 53 : seg - 69)) * 64 + lane) * 16;
; #pragma unroll
;     for (int mi = 0; mi < 4; ++mi) {
;       unsigned wv[4];
; #pragma unroll
;       for (int ni = 0; ni < 4; ++ni) {
;         unsigned w_ = 0u;
; #pragma unroll
;         for (int j = 0; j < 4; ++j) {
;           const float r = rr[wm * 64 + mi * 16 + fq * 4 + j];
;           w_ |= ((unsigned)(int)(sigmoidf_(acc[mi][ni][j] * r) * 255.f + 0.5f)) << (8 * j);
;         }
;         wv[ni] = w_;
;       }
;       *(u32x4*)(G + mi * 4) = u32x4{wv[0], wv[1], wv[2], wv[3]};
;     }
;     return;
	v_mul_f32_e32 v31, v31, v35
	v_mul_f32_e32 v31, 0xbfb8aa3b, v31
	v_exp_f32_e32 v38, v31
	v_mul_f32_e32 v31, v32, v36
	v_mul_f32_e32 v31, 0xbfb8aa3b, v31
	v_exp_f32_e32 v32, v31
	v_mul_f32_e32 v31, v33, v37
	v_mul_f32_e32 v26, v26, v34
	v_mul_f32_e32 v31, 0xbfb8aa3b, v31
	v_mul_f32_e32 v26, 0xbfb8aa3b, v26
	v_mul_f32_e32 v30, v30, v34
	v_exp_f32_e32 v40, v31
	v_exp_f32_e32 v31, v26
	v_mul_f32_e32 v26, v27, v35
	v_mul_f32_e32 v30, 0xbfb8aa3b, v30
	v_mul_f32_e32 v26, 0xbfb8aa3b, v26
	v_exp_f32_e32 v30, v30
	v_exp_f32_e32 v39, v26
	v_mul_f32_e32 v26, v28, v36
	v_mul_f32_e32 v26, 0xbfb8aa3b, v26
	v_exp_f32_e32 v33, v26
	v_mul_f32_e32 v26, v29, v37
	v_mul_f32_e32 v26, 0xbfb8aa3b, v26
	v_exp_f32_e32 v41, v26
	v_pk_add_f32 v[26:27], v[30:31], 1.0 op_sel_hi:[1,0]
	v_mul_f32_e32 v23, v23, v35
	v_mul_f32_e32 v23, 0xbfb8aa3b, v23
	v_mul_f32_e32 v18, v18, v34
	v_mul_f32_e32 v18, 0xbfb8aa3b, v18
	v_rcp_f32_e32 v27, v27
	s_nop 0
	v_mul_f32_e32 v22, v22, v34
	v_mul_f32_e32 v22, 0xbfb8aa3b, v22
	v_exp_f32_e32 v22, v22
	v_rcp_f32_e32 v26, v26
	s_nop 0
	v_pk_fma_f32 v[26:27], v[26:27], s[6:7], 0.5 op_sel_hi:[1,0,0]
	s_nop 0
	v_cvt_i32_f32_e32 v28, v27
	v_cvt_i32_f32_e32 v29, v26
	v_pk_add_f32 v[26:27], v[38:39], 1.0 op_sel_hi:[1,0]
	s_nop 0
	s_nop 0
	v_rcp_f32_e32 v27, v27
	s_nop 0
	s_nop 0
	v_rcp_f32_e32 v26, v26
	s_nop 0
	v_pk_fma_f32 v[26:27], v[26:27], s[6:7], 0.5 op_sel_hi:[1,0,0]
	s_nop 0
	v_cvt_i32_f32_e32 v26, v26
	v_cvt_i32_f32_e32 v27, v27
	v_lshlrev_b32_e32 v26, 8, v26
	v_lshlrev_b32_e32 v27, 8, v27
	v_or_b32_e32 v28, v27, v28
	v_or_b32_e32 v29, v26, v29
	v_pk_add_f32 v[26:27], v[32:33], 1.0 op_sel_hi:[1,0]
	s_nop 0
	s_nop 0
	v_rcp_f32_e32 v27, v27
	s_nop 0
	s_nop 0
	v_rcp_f32_e32 v26, v26
	s_nop 0
	v_pk_fma_f32 v[26:27], v[26:27], s[6:7], 0.5 op_sel_hi:[1,0,0]
	s_nop 0
	v_cvt_i32_f32_sdwa v26, v26 dst_sel:WORD_1 dst_unused:UNUSED_PAD src0_sel:DWORD
	v_cvt_i32_f32_sdwa v27, v27 dst_sel:WORD_1 dst_unused:UNUSED_PAD src0_sel:DWORD
	v_or_b32_e32 v29, v29, v26
	v_or_b32_e32 v28, v28, v27
	v_pk_add_f32 v[26:27], v[40:41], 1.0 op_sel_hi:[1,0]
	s_nop 0
	s_nop 0
	v_rcp_f32_e32 v27, v27
	s_nop 0
	s_nop 0
	v_rcp_f32_e32 v26, v26
	s_nop 0
	v_pk_fma_f32 v[26:27], v[26:27], s[6:7], 0.5 op_sel_hi:[1,0,0]
	s_nop 0
	v_cvt_i32_f32_sdwa v27, v27 dst_sel:BYTE_3 dst_unused:UNUSED_PAD src0_sel:DWORD
	v_cvt_i32_f32_sdwa v26, v26 dst_sel:BYTE_3 dst_unused:UNUSED_PAD src0_sel:DWORD
	v_or_b32_e32 v27, v28, v27
	v_exp_f32_e32 v28, v23
	v_mul_f32_e32 v23, v24, v36
	v_mul_f32_e32 v23, 0xbfb8aa3b, v23
	v_exp_f32_e32 v24, v23
	v_mul_f32_e32 v23, v25, v37
	v_mul_f32_e32 v23, 0xbfb8aa3b, v23
	v_exp_f32_e32 v30, v23
	v_exp_f32_e32 v23, v18
	v_mul_f32_e32 v18, v19, v35
	v_mul_f32_e32 v18, 0xbfb8aa3b, v18
	v_or_b32_e32 v26, v29, v26
	v_exp_f32_e32 v29, v18
	v_mul_f32_e32 v18, v20, v36
	v_mul_f32_e32 v18, 0xbfb8aa3b, v18
	v_exp_f32_e32 v25, v18
	v_mul_f32_e32 v18, v21, v37
	v_mul_f32_e32 v18, 0xbfb8aa3b, v18
	v_exp_f32_e32 v31, v18
	v_pk_add_f32 v[18:19], v[22:23], 1.0 op_sel_hi:[1,0]
	s_nop 0
	s_nop 0
	v_rcp_f32_e32 v19, v19
	s_nop 0
	s_nop 0
	v_rcp_f32_e32 v18, v18
	s_nop 0
	v_pk_fma_f32 v[18:19], v[18:19], s[6:7], 0.5 op_sel_hi:[1,0,0]
	s_nop 0
	v_cvt_i32_f32_e32 v20, v19
	v_cvt_i32_f32_e32 v21, v18
	v_pk_add_f32 v[18:19], v[28:29], 1.0 op_sel_hi:[1,0]
	s_nop 0
	s_nop 0
	v_rcp_f32_e32 v19, v19
	s_nop 0
	s_nop 0
	v_rcp_f32_e32 v18, v18
	s_nop 0
	v_pk_fma_f32 v[18:19], v[18:19], s[6:7], 0.5 op_sel_hi:[1,0,0]
	s_nop 0
	v_cvt_i32_f32_e32 v18, v18
	v_cvt_i32_f32_e32 v19, v19
	v_lshlrev_b32_e32 v18, 8, v18
	v_lshlrev_b32_e32 v19, 8, v19
	v_or_b32_e32 v20, v19, v20
	v_or_b32_e32 v21, v18, v21
	v_pk_add_f32 v[18:19], v[24:25], 1.0 op_sel_hi:[1,0]
	s_nop 0
	s_nop 0
	v_rcp_f32_e32 v19, v19
	s_nop 0
	s_nop 0
	v_rcp_f32_e32 v18, v18
	s_nop 0
	v_pk_fma_f32 v[18:19], v[18:19], s[6:7], 0.5 op_sel_hi:[1,0,0]
	s_nop 0
	v_cvt_i32_f32_sdwa v18, v18 dst_sel:WORD_1 dst_unused:UNUSED_PAD src0_sel:DWORD
	v_cvt_i32_f32_sdwa v19, v19 dst_sel:WORD_1 dst_unused:UNUSED_PAD src0_sel:DWORD
	v_or_b32_e32 v21, v21, v18
	v_or_b32_e32 v20, v20, v19
	v_pk_add_f32 v[18:19], v[30:31], 1.0 op_sel_hi:[1,0]
	s_nop 0
	s_nop 0
	v_rcp_f32_e32 v19, v19
	s_nop 0
	s_nop 0
	v_rcp_f32_e32 v18, v18
	s_nop 0
	v_pk_fma_f32 v[18:19], v[18:19], s[6:7], 0.5 op_sel_hi:[1,0,0]
	s_nop 0
	v_cvt_i32_f32_sdwa v18, v18 dst_sel:BYTE_3 dst_unused:UNUSED_PAD src0_sel:DWORD
	v_cvt_i32_f32_sdwa v19, v19 dst_sel:BYTE_3 dst_unused:UNUSED_PAD src0_sel:DWORD
	v_or_b32_e32 v28, v21, v18
	v_or_b32_e32 v29, v20, v19
	ds_read_b128 v[18:21], v66 offset:192
	global_store_dwordx4 v0, v[26:29], s[0:1] offset:32
	s_waitcnt lgkmcnt(0)
; DI float sigmoidf_(float v) { return 1.f / (1.f + __expf(-v)); }
; DI void phaseA_tile(const P& p, int layer, int mt, int nt, char* lds) {
;     ...
;   if (seg >= 53) {
;     const bool isP = seg < 69;
;     unsigned* G = (unsigned*)(p.ws + (isP ? W_GP : W_GA)) + ((size_t)(((row0 >> 6) + wm) * 16 + (isP ? seg - 53 : seg - 69)) * 64 + lane) * 16;
; #pragma unroll
;     for (int mi = 0; mi < 4; ++mi) {
;       unsigned wv[4];
; #pragma unroll
;       for (int ni = 0; ni < 4; ++ni) {
;         unsigned w_ = 0u;
; #pragma unroll
;         for (int j = 0; j < 4; ++j) {
;           const float r = rr[wm * 64 + mi * 16 + fq * 4 + j];
;           w_ |= ((unsigned)(int)(sigmoidf_(acc[mi][ni][j] * r) * 255.f + 0.5f)) << (8 * j);
;         }
;         wv[ni] = w_;
;       }
;       *(u32x4*)(G + mi * 4) = u32x4{wv[0], wv[1], wv[2], wv[3]};
;     }
;     return;
	v_mul_f32_e32 v14, v14, v18
	v_mul_f32_e32 v10, v10, v18
	v_mul_f32_e32 v14, 0xbfb8aa3b, v14
	v_mul_f32_e32 v10, 0xbfb8aa3b, v10
	v_exp_f32_e32 v22, v14
	v_mul_f32_e32 v14, v15, v19
	v_exp_f32_e32 v23, v10
	v_mul_f32_e32 v10, v11, v19
	v_mul_f32_e32 v14, 0xbfb8aa3b, v14
	v_mul_f32_e32 v10, 0xbfb8aa3b, v10
	v_exp_f32_e32 v24, v14
	v_mul_f32_e32 v14, v16, v20
	v_exp_f32_e32 v25, v10
	v_mul_f32_e32 v10, v12, v20
	v_mul_f32_e32 v14, 0xbfb8aa3b, v14
	v_mul_f32_e32 v10, 0xbfb8aa3b, v10
	v_exp_f32_e32 v16, v14
	v_mul_f32_e32 v14, v17, v21
	v_exp_f32_e32 v17, v10
	v_mul_f32_e32 v10, v13, v21
	v_mul_f32_e32 v10, 0xbfb8aa3b, v10
	v_exp_f32_e32 v15, v10
	v_pk_add_f32 v[10:11], v[22:23], 1.0 op_sel_hi:[1,0]
	v_mul_f32_e32 v14, 0xbfb8aa3b, v14
	v_exp_f32_e32 v14, v14
	v_mul_f32_e32 v6, v6, v18
	v_mul_f32_e32 v2, v2, v18
	v_rcp_f32_e32 v11, v11
	s_nop 0
	v_mul_f32_e32 v6, 0xbfb8aa3b, v6
	v_mul_f32_e32 v2, 0xbfb8aa3b, v2
	v_rcp_f32_e32 v10, v10
	s_nop 0
	v_pk_fma_f32 v[10:11], v[10:11], s[6:7], 0.5 op_sel_hi:[1,0,0]
	s_nop 0
	v_cvt_i32_f32_e32 v12, v11
	v_cvt_i32_f32_e32 v13, v10
	v_pk_add_f32 v[10:11], v[24:25], 1.0 op_sel_hi:[1,0]
	s_nop 0
	s_nop 0
	v_rcp_f32_e32 v11, v11
	s_nop 0
	s_nop 0
	v_rcp_f32_e32 v10, v10
	s_nop 0
	v_pk_fma_f32 v[10:11], v[10:11], s[6:7], 0.5 op_sel_hi:[1,0,0]
	s_nop 0
	v_cvt_i32_f32_e32 v10, v10
	v_cvt_i32_f32_e32 v11, v11
	v_lshlrev_b32_e32 v10, 8, v10
	v_lshlrev_b32_e32 v11, 8, v11
	v_or_b32_e32 v12, v11, v12
	v_or_b32_e32 v13, v10, v13
	v_pk_add_f32 v[10:11], v[16:17], 1.0 op_sel_hi:[1,0]
	s_nop 0
	s_nop 0
	v_rcp_f32_e32 v11, v11
	s_nop 0
	s_nop 0
	v_rcp_f32_e32 v10, v10
	s_nop 0
	v_pk_fma_f32 v[10:11], v[10:11], s[6:7], 0.5 op_sel_hi:[1,0,0]
	s_nop 0
	v_cvt_i32_f32_sdwa v10, v10 dst_sel:WORD_1 dst_unused:UNUSED_PAD src0_sel:DWORD
	v_cvt_i32_f32_sdwa v11, v11 dst_sel:WORD_1 dst_unused:UNUSED_PAD src0_sel:DWORD
	v_or_b32_e32 v13, v13, v10
	v_or_b32_e32 v12, v12, v11
	v_pk_add_f32 v[10:11], v[14:15], 1.0 op_sel_hi:[1,0]
	s_nop 0
	s_nop 0
	v_rcp_f32_e32 v11, v11
	s_nop 0
	s_nop 0
	v_rcp_f32_e32 v10, v10
	s_nop 0
	v_pk_fma_f32 v[10:11], v[10:11], s[6:7], 0.5 op_sel_hi:[1,0,0]
	s_nop 0
	v_cvt_i32_f32_sdwa v10, v10 dst_sel:BYTE_3 dst_unused:UNUSED_PAD src0_sel:DWORD
	v_cvt_i32_f32_sdwa v11, v11 dst_sel:BYTE_3 dst_unused:UNUSED_PAD src0_sel:DWORD
	v_or_b32_e32 v10, v13, v10
	v_or_b32_e32 v11, v12, v11
	v_exp_f32_e32 v12, v6
	v_mul_f32_e32 v6, v7, v19
	v_exp_f32_e32 v13, v2
	v_mul_f32_e32 v2, v3, v19
	v_mul_f32_e32 v6, 0xbfb8aa3b, v6
	v_mul_f32_e32 v2, 0xbfb8aa3b, v2
	v_exp_f32_e32 v14, v6
	v_mul_f32_e32 v6, v8, v20
	v_exp_f32_e32 v15, v2
	v_mul_f32_e32 v2, v4, v20
	v_mul_f32_e32 v6, 0xbfb8aa3b, v6
	v_mul_f32_e32 v2, 0xbfb8aa3b, v2
	v_exp_f32_e32 v8, v6
	v_mul_f32_e32 v6, v9, v21
	v_exp_f32_e32 v9, v2
	v_mul_f32_e32 v2, v5, v21
	v_mul_f32_e32 v2, 0xbfb8aa3b, v2
	v_exp_f32_e32 v7, v2
	v_pk_add_f32 v[2:3], v[12:13], 1.0 op_sel_hi:[1,0]
	v_mul_f32_e32 v6, 0xbfb8aa3b, v6
	v_exp_f32_e32 v6, v6
	v_rcp_f32_e32 v3, v3
	s_nop 0
	s_nop 0
	v_rcp_f32_e32 v2, v2
	s_nop 0
	v_pk_fma_f32 v[2:3], v[2:3], s[6:7], 0.5 op_sel_hi:[1,0,0]
	s_nop 0
	v_cvt_i32_f32_e32 v4, v3
	v_cvt_i32_f32_e32 v5, v2
	v_pk_add_f32 v[2:3], v[14:15], 1.0 op_sel_hi:[1,0]
	s_nop 0
	s_nop 0
	v_rcp_f32_e32 v3, v3
	s_nop 0
	s_nop 0
	v_rcp_f32_e32 v2, v2
	s_nop 0
	v_pk_fma_f32 v[2:3], v[2:3], s[6:7], 0.5 op_sel_hi:[1,0,0]
	s_nop 0
	v_cvt_i32_f32_e32 v2, v2
	v_cvt_i32_f32_e32 v3, v3
	v_lshlrev_b32_e32 v2, 8, v2
	v_lshlrev_b32_e32 v3, 8, v3
	v_or_b32_e32 v4, v3, v4
	v_or_b32_e32 v5, v2, v5
	v_pk_add_f32 v[2:3], v[8:9], 1.0 op_sel_hi:[1,0]
	s_nop 0
	s_nop 0
	v_rcp_f32_e32 v3, v3
	s_nop 0
	s_nop 0
	v_rcp_f32_e32 v2, v2
	s_nop 0
	v_pk_fma_f32 v[2:3], v[2:3], s[6:7], 0.5 op_sel_hi:[1,0,0]
	s_nop 0
	v_cvt_i32_f32_sdwa v2, v2 dst_sel:WORD_1 dst_unused:UNUSED_PAD src0_sel:DWORD
	v_cvt_i32_f32_sdwa v3, v3 dst_sel:WORD_1 dst_unused:UNUSED_PAD src0_sel:DWORD
	v_or_b32_e32 v5, v5, v2
	v_or_b32_e32 v4, v4, v3
	v_pk_add_f32 v[2:3], v[6:7], 1.0 op_sel_hi:[1,0]
	s_nop 0
	s_nop 0
	v_rcp_f32_e32 v3, v3
	s_nop 0
	s_movk_i32 s5, 0x2000
	v_rcp_f32_e32 v2, v2
	s_nop 0
	v_pk_fma_f32 v[2:3], v[2:3], s[6:7], 0.5 op_sel_hi:[1,0,0]
	s_nop 0
	v_cvt_i32_f32_sdwa v2, v2 dst_sel:BYTE_3 dst_unused:UNUSED_PAD src0_sel:DWORD
	v_cvt_i32_f32_sdwa v3, v3 dst_sel:BYTE_3 dst_unused:UNUSED_PAD src0_sel:DWORD
	v_or_b32_e32 v12, v5, v2
	v_or_b32_e32 v13, v4, v3
	global_store_dwordx4 v0, v[10:13], s[0:1] offset:48
	s_branch .LBB0_1588
